# A/B: all s_setprio around the GEMM MFMA blocks deleted
# speedup vs baseline: 1.0019x; 1.0019x over previous
.LBB0_329:
	s_waitcnt lgkmcnt(0)
	s_barrier
	s_waitcnt lgkmcnt(0)
	v_mfma_f32_16x16x32_bf16 v[66:69], v[150:153], v[190:193], v[66:69]
	v_mfma_f32_16x16x32_bf16 v[58:61], v[158:161], v[190:193], v[58:61]
	v_mfma_f32_16x16x32_bf16 v[50:53], v[150:153], v[182:185], v[50:53]
	v_mfma_f32_16x16x32_bf16 v[42:45], v[158:161], v[182:185], v[42:45]
	v_mfma_f32_16x16x32_bf16 v[34:37], v[150:153], v[174:177], v[34:37]
	v_mfma_f32_16x16x32_bf16 v[26:29], v[158:161], v[174:177], v[26:29]
	v_mfma_f32_16x16x32_bf16 v[18:21], v[150:153], v[166:169], v[18:21]
	v_mfma_f32_16x16x32_bf16 v[10:13], v[158:161], v[166:169], v[10:13]
	v_mfma_f32_16x16x32_bf16 v[66:69], v[154:157], v[194:197], v[66:69]
	v_mfma_f32_16x16x32_bf16 v[58:61], v[162:165], v[194:197], v[58:61]
	v_mfma_f32_16x16x32_bf16 v[50:53], v[154:157], v[186:189], v[50:53]
	v_mfma_f32_16x16x32_bf16 v[42:45], v[162:165], v[186:189], v[42:45]
	v_mfma_f32_16x16x32_bf16 v[34:37], v[154:157], v[178:181], v[34:37]
	v_mfma_f32_16x16x32_bf16 v[26:29], v[162:165], v[178:181], v[26:29]
	v_mfma_f32_16x16x32_bf16 v[18:21], v[154:157], v[170:173], v[18:21]
	v_mfma_f32_16x16x32_bf16 v[10:13], v[162:165], v[170:173], v[10:13]
	v_mfma_f32_16x16x32_bf16 v[62:65], v[134:137], v[190:193], v[62:65]
	v_mfma_f32_16x16x32_bf16 v[54:57], v[142:145], v[190:193], v[54:57]
	v_mfma_f32_16x16x32_bf16 v[46:49], v[134:137], v[182:185], v[46:49]
	v_mfma_f32_16x16x32_bf16 v[38:41], v[142:145], v[182:185], v[38:41]
	v_mfma_f32_16x16x32_bf16 v[30:33], v[134:137], v[174:177], v[30:33]
	v_mfma_f32_16x16x32_bf16 v[22:25], v[142:145], v[174:177], v[22:25]
	v_mfma_f32_16x16x32_bf16 v[14:17], v[134:137], v[166:169], v[14:17]
	v_mfma_f32_16x16x32_bf16 v[6:9], v[142:145], v[166:169], v[6:9]
	v_mfma_f32_16x16x32_bf16 v[62:65], v[138:141], v[194:197], v[62:65]
	v_mfma_f32_16x16x32_bf16 v[54:57], v[146:149], v[194:197], v[54:57]
	v_mfma_f32_16x16x32_bf16 v[46:49], v[138:141], v[186:189], v[46:49]
	v_mfma_f32_16x16x32_bf16 v[38:41], v[146:149], v[186:189], v[38:41]
	v_mfma_f32_16x16x32_bf16 v[30:33], v[138:141], v[178:181], v[30:33]
	v_mfma_f32_16x16x32_bf16 v[22:25], v[146:149], v[178:181], v[22:25]
	v_mfma_f32_16x16x32_bf16 v[14:17], v[138:141], v[170:173], v[14:17]
	v_mfma_f32_16x16x32_bf16 v[6:9], v[146:149], v[170:173], v[6:9]
	s_barrier
	s_add_i32 s61, s61, 2
	s_cmp_gt_u32 s61, 13
	s_cbranch_scc1 .Lkr1_exit

.LBB0_332:
	s_add_u32 s48, s28, 0xfffc0080
	s_addc_u32 s49, s29, -1
	s_and_b64 s[46:47], s[30:31], exec
	s_cselect_b32 s49, s23, s49
	s_cselect_b32 s48, s56, s48
	s_cselect_b32 s47, s57, s60
	s_cselect_b32 s46, s58, s59
	s_add_i32 m0, s40, 0xc000
	s_nop 0
	global_load_lds_dwordx4 v206, s[28:29]
	s_add_i32 m0, s40, 0xe000
	s_nop 0
	global_load_lds_dwordx4 v208, s[28:29]
	s_waitcnt vmcnt(8)
	s_waitcnt lgkmcnt(0)
	s_barrier
	s_waitcnt lgkmcnt(0)
	v_mfma_f32_16x16x32_bf16 v[130:133], v[134:137], v[166:169], v[130:133]
	v_mfma_f32_16x16x32_bf16 v[122:125], v[142:145], v[166:169], v[122:125]
	v_mfma_f32_16x16x32_bf16 v[114:117], v[134:137], v[174:177], v[114:117]
	v_mfma_f32_16x16x32_bf16 v[106:109], v[142:145], v[174:177], v[106:109]
	v_mfma_f32_16x16x32_bf16 v[98:101], v[134:137], v[182:185], v[98:101]
	v_mfma_f32_16x16x32_bf16 v[90:93], v[142:145], v[182:185], v[90:93]
	v_mfma_f32_16x16x32_bf16 v[82:85], v[134:137], v[190:193], v[82:85]
	v_mfma_f32_16x16x32_bf16 v[74:77], v[142:145], v[190:193], v[74:77]
	v_mfma_f32_16x16x32_bf16 v[130:133], v[138:141], v[170:173], v[130:133]
	v_mfma_f32_16x16x32_bf16 v[122:125], v[146:149], v[170:173], v[122:125]
	v_mfma_f32_16x16x32_bf16 v[114:117], v[138:141], v[178:181], v[114:117]
	v_mfma_f32_16x16x32_bf16 v[106:109], v[146:149], v[178:181], v[106:109]
	v_mfma_f32_16x16x32_bf16 v[98:101], v[138:141], v[186:189], v[98:101]
	v_mfma_f32_16x16x32_bf16 v[90:93], v[146:149], v[186:189], v[90:93]
	v_mfma_f32_16x16x32_bf16 v[82:85], v[138:141], v[194:197], v[82:85]
	v_mfma_f32_16x16x32_bf16 v[74:77], v[146:149], v[194:197], v[74:77]
	v_mfma_f32_16x16x32_bf16 v[126:129], v[150:153], v[166:169], v[126:129]
	v_mfma_f32_16x16x32_bf16 v[118:121], v[158:161], v[166:169], v[118:121]
	v_mfma_f32_16x16x32_bf16 v[110:113], v[150:153], v[174:177], v[110:113]
	v_mfma_f32_16x16x32_bf16 v[102:105], v[158:161], v[174:177], v[102:105]
	v_mfma_f32_16x16x32_bf16 v[94:97], v[150:153], v[182:185], v[94:97]
	v_mfma_f32_16x16x32_bf16 v[86:89], v[158:161], v[182:185], v[86:89]
	v_mfma_f32_16x16x32_bf16 v[78:81], v[150:153], v[190:193], v[78:81]
	v_mfma_f32_16x16x32_bf16 v[70:73], v[158:161], v[190:193], v[70:73]
	v_mfma_f32_16x16x32_bf16 v[126:129], v[154:157], v[170:173], v[126:129]
	v_mfma_f32_16x16x32_bf16 v[118:121], v[162:165], v[170:173], v[118:121]
	v_mfma_f32_16x16x32_bf16 v[110:113], v[154:157], v[178:181], v[110:113]
	v_mfma_f32_16x16x32_bf16 v[102:105], v[162:165], v[178:181], v[102:105]
	v_mfma_f32_16x16x32_bf16 v[94:97], v[154:157], v[186:189], v[94:97]
	v_mfma_f32_16x16x32_bf16 v[86:89], v[162:165], v[186:189], v[86:89]
	v_mfma_f32_16x16x32_bf16 v[78:81], v[154:157], v[194:197], v[78:81]
	v_mfma_f32_16x16x32_bf16 v[70:73], v[162:165], v[194:197], v[70:73]
	s_barrier
	ds_read_b128 v[166:169], v229 offset:16384
	ds_read_b128 v[170:173], v229 offset:17408
	ds_read_b128 v[174:177], v229 offset:18432
	ds_read_b128 v[178:181], v229 offset:19456
	ds_read_b128 v[182:185], v229 offset:20480
	ds_read_b128 v[186:189], v229 offset:21504
	ds_read_b128 v[190:193], v229 offset:22528
	ds_read_b128 v[194:197], v229 offset:23552
	s_add_i32 s62, s53, s12
	s_add_u32 s98, s46, s10
	s_addc_u32 s99, s47, s11
	s_mov_b32 m0, s62
	s_nop 0
	global_load_lds_dwordx4 v202, s[46:47]
	s_add_i32 m0, s62, 0x2000
	s_add_u32 s62, s46, 0x40000
	s_addc_u32 s63, s47, 0
	s_add_i32 s64, s54, s12
	global_load_lds_dwordx4 v198, s[46:47]
	s_mov_b32 m0, s64
	s_add_u32 s100, s48, s10
	s_addc_u32 s101, s49, s11
	global_load_lds_dwordx4 v202, s[62:63]
	s_add_i32 m0, s64, 0x2000
	s_nop 0
	global_load_lds_dwordx4 v198, s[62:63]
	s_mov_b32 m0, s40
	s_nop 0
	global_load_lds_dwordx4 v204, s[48:49]
	s_mov_b32 m0, s41
	s_nop 0
	global_load_lds_dwordx4 v200, s[48:49]
	s_waitcnt vmcnt(8)
	s_waitcnt lgkmcnt(0)
	s_barrier
	s_waitcnt lgkmcnt(0)
	v_mfma_f32_16x16x32_bf16 v[66:69], v[134:137], v[166:169], v[66:69]
	v_mfma_f32_16x16x32_bf16 v[58:61], v[142:145], v[166:169], v[58:61]
	v_mfma_f32_16x16x32_bf16 v[50:53], v[134:137], v[174:177], v[50:53]
	v_mfma_f32_16x16x32_bf16 v[42:45], v[142:145], v[174:177], v[42:45]
	v_mfma_f32_16x16x32_bf16 v[34:37], v[134:137], v[182:185], v[34:37]
	v_mfma_f32_16x16x32_bf16 v[26:29], v[142:145], v[182:185], v[26:29]
	v_mfma_f32_16x16x32_bf16 v[18:21], v[134:137], v[190:193], v[18:21]
	v_mfma_f32_16x16x32_bf16 v[10:13], v[142:145], v[190:193], v[10:13]
	v_mfma_f32_16x16x32_bf16 v[66:69], v[138:141], v[170:173], v[66:69]
	v_mfma_f32_16x16x32_bf16 v[58:61], v[146:149], v[170:173], v[58:61]
	v_mfma_f32_16x16x32_bf16 v[50:53], v[138:141], v[178:181], v[50:53]
	v_mfma_f32_16x16x32_bf16 v[42:45], v[146:149], v[178:181], v[42:45]
	v_mfma_f32_16x16x32_bf16 v[34:37], v[138:141], v[186:189], v[34:37]
	v_mfma_f32_16x16x32_bf16 v[26:29], v[146:149], v[186:189], v[26:29]
	v_mfma_f32_16x16x32_bf16 v[18:21], v[138:141], v[194:197], v[18:21]
	v_mfma_f32_16x16x32_bf16 v[10:13], v[146:149], v[194:197], v[10:13]
	v_mfma_f32_16x16x32_bf16 v[62:65], v[150:153], v[166:169], v[62:65]
	v_mfma_f32_16x16x32_bf16 v[54:57], v[158:161], v[166:169], v[54:57]
	v_mfma_f32_16x16x32_bf16 v[46:49], v[150:153], v[174:177], v[46:49]
	v_mfma_f32_16x16x32_bf16 v[38:41], v[158:161], v[174:177], v[38:41]
	v_mfma_f32_16x16x32_bf16 v[30:33], v[150:153], v[182:185], v[30:33]
	v_mfma_f32_16x16x32_bf16 v[22:25], v[158:161], v[182:185], v[22:25]
	v_mfma_f32_16x16x32_bf16 v[14:17], v[150:153], v[190:193], v[14:17]
	v_mfma_f32_16x16x32_bf16 v[6:9], v[158:161], v[190:193], v[6:9]
	v_mfma_f32_16x16x32_bf16 v[62:65], v[154:157], v[170:173], v[62:65]
	v_mfma_f32_16x16x32_bf16 v[54:57], v[162:165], v[170:173], v[54:57]
	v_mfma_f32_16x16x32_bf16 v[46:49], v[154:157], v[178:181], v[46:49]
	v_mfma_f32_16x16x32_bf16 v[38:41], v[162:165], v[178:181], v[38:41]
	v_mfma_f32_16x16x32_bf16 v[30:33], v[154:157], v[186:189], v[30:33]
	v_mfma_f32_16x16x32_bf16 v[22:25], v[162:165], v[186:189], v[22:25]
	v_mfma_f32_16x16x32_bf16 v[14:17], v[154:157], v[194:197], v[14:17]
	v_mfma_f32_16x16x32_bf16 v[6:9], v[162:165], v[194:197], v[6:9]
	s_barrier
	ds_read_b128 v[166:169], v229 offset:32768
	ds_read_b128 v[170:173], v229 offset:33792
	ds_read_b128 v[174:177], v229 offset:34816
	ds_read_b128 v[178:181], v229 offset:35840
	ds_read_b128 v[182:185], v229 offset:36864
	ds_read_b128 v[186:189], v229 offset:37888
	ds_read_b128 v[190:193], v229 offset:38912
	ds_read_b128 v[194:197], v229 offset:39936
	v_add_u32_e32 v134, 0x18000, v225
	v_add_u32_e32 v146, 0x1c000, v225
	ds_read_b128 v[150:153], v134
	ds_read_b128 v[154:157], v134 offset:1024
	ds_read_b128 v[158:161], v134 offset:2048
	ds_read_b128 v[162:165], v134 offset:3072
	ds_read_b128 v[134:137], v146
	ds_read_b128 v[138:141], v146 offset:1024
	ds_read_b128 v[142:145], v146 offset:2048
	ds_read_b128 v[146:149], v146 offset:3072
	s_add_i32 s62, 0, 0x18000
	s_add_i32 s63, 0, 0x1c000
	s_add_u32 s48, s48, 0x40000
	s_addc_u32 s49, s49, 0
	s_mov_b32 m0, s42
	s_nop 0
	global_load_lds_dwordx4 v204, s[48:49]
	s_mov_b32 m0, s43
	s_nop 0
	global_load_lds_dwordx4 v200, s[48:49]
	s_waitcnt vmcnt(8)
	s_waitcnt lgkmcnt(0)
	s_barrier
	s_waitcnt lgkmcnt(0)
	v_mfma_f32_16x16x32_bf16 v[130:133], v[150:153], v[166:169], v[130:133]
	v_mfma_f32_16x16x32_bf16 v[122:125], v[158:161], v[166:169], v[122:125]
	v_mfma_f32_16x16x32_bf16 v[114:117], v[150:153], v[174:177], v[114:117]
	v_mfma_f32_16x16x32_bf16 v[106:109], v[158:161], v[174:177], v[106:109]
	v_mfma_f32_16x16x32_bf16 v[98:101], v[150:153], v[182:185], v[98:101]
	v_mfma_f32_16x16x32_bf16 v[90:93], v[158:161], v[182:185], v[90:93]
	v_mfma_f32_16x16x32_bf16 v[82:85], v[150:153], v[190:193], v[82:85]
	v_mfma_f32_16x16x32_bf16 v[74:77], v[158:161], v[190:193], v[74:77]
	v_mfma_f32_16x16x32_bf16 v[130:133], v[154:157], v[170:173], v[130:133]
	v_mfma_f32_16x16x32_bf16 v[122:125], v[162:165], v[170:173], v[122:125]
	v_mfma_f32_16x16x32_bf16 v[114:117], v[154:157], v[178:181], v[114:117]
	v_mfma_f32_16x16x32_bf16 v[106:109], v[162:165], v[178:181], v[106:109]
	v_mfma_f32_16x16x32_bf16 v[98:101], v[154:157], v[186:189], v[98:101]
	v_mfma_f32_16x16x32_bf16 v[90:93], v[162:165], v[186:189], v[90:93]
	v_mfma_f32_16x16x32_bf16 v[82:85], v[154:157], v[194:197], v[82:85]
	v_mfma_f32_16x16x32_bf16 v[74:77], v[162:165], v[194:197], v[74:77]
	v_mfma_f32_16x16x32_bf16 v[126:129], v[134:137], v[166:169], v[126:129]
	v_mfma_f32_16x16x32_bf16 v[118:121], v[142:145], v[166:169], v[118:121]
	v_mfma_f32_16x16x32_bf16 v[110:113], v[134:137], v[174:177], v[110:113]
	v_mfma_f32_16x16x32_bf16 v[102:105], v[142:145], v[174:177], v[102:105]
	v_mfma_f32_16x16x32_bf16 v[94:97], v[134:137], v[182:185], v[94:97]
	v_mfma_f32_16x16x32_bf16 v[86:89], v[142:145], v[182:185], v[86:89]
	v_mfma_f32_16x16x32_bf16 v[78:81], v[134:137], v[190:193], v[78:81]
	v_mfma_f32_16x16x32_bf16 v[70:73], v[142:145], v[190:193], v[70:73]
	v_mfma_f32_16x16x32_bf16 v[126:129], v[138:141], v[170:173], v[126:129]
	v_mfma_f32_16x16x32_bf16 v[118:121], v[146:149], v[170:173], v[118:121]
	v_mfma_f32_16x16x32_bf16 v[110:113], v[138:141], v[178:181], v[110:113]
	v_mfma_f32_16x16x32_bf16 v[102:105], v[146:149], v[178:181], v[102:105]
	v_mfma_f32_16x16x32_bf16 v[94:97], v[138:141], v[186:189], v[94:97]
	v_mfma_f32_16x16x32_bf16 v[86:89], v[146:149], v[186:189], v[86:89]
	v_mfma_f32_16x16x32_bf16 v[78:81], v[138:141], v[194:197], v[78:81]
	v_mfma_f32_16x16x32_bf16 v[70:73], v[146:149], v[194:197], v[70:73]
	s_barrier
	ds_read_b128 v[190:193], v229 offset:49152
	ds_read_b128 v[194:197], v229 offset:50176
	ds_read_b128 v[182:185], v229 offset:51200
	ds_read_b128 v[186:189], v229 offset:52224
	ds_read_b128 v[174:177], v229 offset:53248
	ds_read_b128 v[178:181], v229 offset:54272
	ds_read_b128 v[166:169], v229 offset:55296
	ds_read_b128 v[170:173], v229 offset:56320
	s_add_i32 s48, s62, s12
	s_mov_b32 m0, s48
	s_nop 0
	global_load_lds_dwordx4 v202, s[98:99]
	s_add_i32 m0, s48, 0x2000
	s_add_u32 s46, s46, 0x40080
	s_addc_u32 s47, s47, 0
	s_add_i32 s48, s63, s12
	global_load_lds_dwordx4 v198, s[98:99]
	s_mov_b32 m0, s48
	s_andn2_b64 vcc, exec, s[30:31]
	global_load_lds_dwordx4 v202, s[46:47]
	s_add_i32 m0, s48, 0x2000
	s_nop 0
	global_load_lds_dwordx4 v198, s[46:47]
	s_mov_b32 m0, s51
	s_nop 0
	global_load_lds_dwordx4 v204, s[100:101]
	s_mov_b32 m0, s52
	s_nop 0
	global_load_lds_dwordx4 v200, s[100:101]
	s_waitcnt vmcnt(8)
	s_cbranch_vccnz .LBB0_329
	s_and_saveexec_b64 s[30:31], s[4:5]
	s_cbranch_execz .LBB0_328
	v_mov_b32_e32 v232, v3
	v_mov_b32_e32 v233, v4
	v_mov_b32_e32 v234, v2
	v_mov_b32_e32 v235, v5
	v_pk_add_f32 v[232:233], v[232:233], v[234:235]
	s_nop 0
	v_add_f32_e32 v226, v232, v233
	v_fmamk_f32 v226, v226, 0x3a800000, v230
	ds_write_b32 v228, v226
	s_branch .LBB0_328

.LBB0_370:
	ds_read_b128 v[2:5], v148
	ds_read_b128 v[6:9], v148 offset:1024
	ds_read_b128 v[10:13], v148 offset:2048
	ds_read_b128 v[14:17], v148 offset:3072
	ds_read_b128 v[18:21], v149
	ds_read_b128 v[22:25], v149 offset:1024
	ds_read_b128 v[26:29], v149 offset:2048
	ds_read_b128 v[30:33], v149 offset:3072
	s_ashr_i32 s47, s46, 31
	s_lshl_b64 s[52:53], s[46:47], 17
	s_add_u32 s52, s0, s52
	s_addc_u32 s53, s1, s53
	s_and_b64 s[6:7], s[6:7], exec
	s_cselect_b32 s7, s53, s61
	s_cselect_b32 s6, s52, s60
	s_add_u32 s66, s58, 0x10080
	s_addc_u32 s67, s59, 0
	s_add_i32 s65, s13, 0xc000
	v_lshl_add_u64 v[66:67], s[66:67], 0, v[130:131]
	s_mov_b32 m0, s65
	s_add_i32 s2, s13, 0xe000
	ds_read_b128 v[34:37], v150
	ds_read_b128 v[38:41], v150 offset:1024
	ds_read_b128 v[42:45], v150 offset:2048
	ds_read_b128 v[46:49], v150 offset:3072
	ds_read_b128 v[50:53], v150 offset:4096
	ds_read_b128 v[54:57], v150 offset:5120
	ds_read_b128 v[58:61], v150 offset:6144
	ds_read_b128 v[62:65], v150 offset:7168
	global_load_lds_dwordx4 v[66:67], off
	v_lshl_add_u64 v[66:67], s[66:67], 0, v[134:135]
	s_mov_b32 m0, s2
	s_nop 0
	global_load_lds_dwordx4 v[66:67], off
	s_waitcnt vmcnt(8)
	s_waitcnt lgkmcnt(0)
	s_barrier
	s_waitcnt lgkmcnt(0)
	v_mfma_f32_16x16x32_bf16 v[66:69], v[2:5], v[34:37], 0
	v_mfma_f32_16x16x32_bf16 v[70:73], v[10:13], v[34:37], 0
	v_mfma_f32_16x16x32_bf16 v[74:77], v[2:5], v[42:45], 0
	v_mfma_f32_16x16x32_bf16 v[78:81], v[10:13], v[42:45], 0
	v_mfma_f32_16x16x32_bf16 v[82:85], v[2:5], v[50:53], 0
	v_mfma_f32_16x16x32_bf16 v[86:89], v[10:13], v[50:53], 0
	v_mfma_f32_16x16x32_bf16 v[90:93], v[2:5], v[58:61], 0
	v_mfma_f32_16x16x32_bf16 v[94:97], v[10:13], v[58:61], 0
	v_mfma_f32_16x16x32_bf16 v[66:69], v[6:9], v[38:41], v[66:69]
	v_mfma_f32_16x16x32_bf16 v[70:73], v[14:17], v[38:41], v[70:73]
	v_mfma_f32_16x16x32_bf16 v[74:77], v[6:9], v[46:49], v[74:77]
	v_mfma_f32_16x16x32_bf16 v[78:81], v[14:17], v[46:49], v[78:81]
	v_mfma_f32_16x16x32_bf16 v[82:85], v[6:9], v[54:57], v[82:85]
	v_mfma_f32_16x16x32_bf16 v[86:89], v[14:17], v[54:57], v[86:89]
	v_mfma_f32_16x16x32_bf16 v[90:93], v[6:9], v[62:65], v[90:93]
	v_mfma_f32_16x16x32_bf16 v[94:97], v[14:17], v[62:65], v[94:97]
	v_mfma_f32_16x16x32_bf16 v[98:101], v[18:21], v[34:37], 0
	v_mfma_f32_16x16x32_bf16 v[34:37], v[26:29], v[34:37], 0
	v_mfma_f32_16x16x32_bf16 v[98:101], v[22:25], v[38:41], v[98:101]
	v_mfma_f32_16x16x32_bf16 v[34:37], v[30:33], v[38:41], v[34:37]
	v_mfma_f32_16x16x32_bf16 v[38:41], v[18:21], v[42:45], 0
	v_mfma_f32_16x16x32_bf16 v[42:45], v[26:29], v[42:45], 0
	v_mfma_f32_16x16x32_bf16 v[38:41], v[22:25], v[46:49], v[38:41]
	v_mfma_f32_16x16x32_bf16 v[42:45], v[30:33], v[46:49], v[42:45]
	v_mfma_f32_16x16x32_bf16 v[46:49], v[18:21], v[50:53], 0
	v_mfma_f32_16x16x32_bf16 v[50:53], v[26:29], v[50:53], 0
	v_mfma_f32_16x16x32_bf16 v[46:49], v[22:25], v[54:57], v[46:49]
	v_mfma_f32_16x16x32_bf16 v[50:53], v[30:33], v[54:57], v[50:53]
	v_mfma_f32_16x16x32_bf16 v[54:57], v[18:21], v[58:61], 0
	v_mfma_f32_16x16x32_bf16 v[58:61], v[26:29], v[58:61], 0
	v_mfma_f32_16x16x32_bf16 v[54:57], v[22:25], v[62:65], v[54:57]
	v_mfma_f32_16x16x32_bf16 v[58:61], v[30:33], v[62:65], v[58:61]
	s_barrier
	s_add_i32 s57, s62, s12
	v_lshl_add_u64 v[212:213], s[60:61], 0, v[132:133]
	s_add_i32 s47, s57, 0x2000
	v_lshl_add_u64 v[142:143], v[212:213], 0, s[28:29]
	s_mov_b32 m0, s57
	v_lshl_add_u64 v[214:215], s[60:61], 0, v[136:137]
	s_add_u32 s66, s60, 0x10100
	ds_read_b128 v[62:65], v150 offset:16384
	ds_read_b128 v[102:105], v150 offset:17408
	ds_read_b128 v[106:109], v150 offset:18432
	ds_read_b128 v[110:113], v150 offset:19456
	ds_read_b128 v[114:117], v150 offset:20480
	ds_read_b128 v[118:121], v150 offset:21504
	ds_read_b128 v[122:125], v150 offset:22528
	ds_read_b128 v[126:129], v150 offset:23552
	global_load_lds_dwordx4 v[142:143], off
	v_lshl_add_u64 v[142:143], v[214:215], 0, s[28:29]
	s_mov_b32 m0, s47
	s_addc_u32 s67, s61, 0
	s_add_i32 s49, s63, s12
	global_load_lds_dwordx4 v[142:143], off
	v_lshl_add_u64 v[142:143], s[66:67], 0, v[132:133]
	s_mov_b32 m0, s49
	s_add_i32 s55, s49, 0x2000
	global_load_lds_dwordx4 v[142:143], off
	v_lshl_add_u64 v[142:143], s[66:67], 0, v[136:137]
	s_mov_b32 m0, s55
	v_lshl_add_u64 v[218:219], s[58:59], 0, v[130:131]
	global_load_lds_dwordx4 v[142:143], off
	v_lshl_add_u64 v[142:143], v[218:219], 0, s[28:29]
	s_mov_b32 m0, s13
	v_lshl_add_u64 v[220:221], s[58:59], 0, v[134:135]
	global_load_lds_dwordx4 v[142:143], off
	v_lshl_add_u64 v[142:143], v[220:221], 0, s[28:29]
	s_mov_b32 m0, s14
	s_nop 0
	global_load_lds_dwordx4 v[142:143], off
	s_waitcnt vmcnt(8)
	s_waitcnt lgkmcnt(0)
	s_barrier
	s_waitcnt lgkmcnt(0)
	v_mfma_f32_16x16x32_bf16 v[142:145], v[2:5], v[62:65], 0
	v_mfma_f32_16x16x32_bf16 v[156:159], v[2:5], v[106:109], 0
	v_mfma_f32_16x16x32_bf16 v[164:167], v[2:5], v[114:117], 0
	v_mfma_f32_16x16x32_bf16 v[2:5], v[2:5], v[122:125], 0
	v_mfma_f32_16x16x32_bf16 v[142:145], v[6:9], v[102:105], v[142:145]
	v_mfma_f32_16x16x32_bf16 v[156:159], v[6:9], v[110:113], v[156:159]
	v_mfma_f32_16x16x32_bf16 v[164:167], v[6:9], v[118:121], v[164:167]
	v_mfma_f32_16x16x32_bf16 v[2:5], v[6:9], v[126:129], v[2:5]
	v_mfma_f32_16x16x32_bf16 v[6:9], v[10:13], v[122:125], 0
	v_mfma_f32_16x16x32_bf16 v[152:155], v[10:13], v[62:65], 0
	v_mfma_f32_16x16x32_bf16 v[160:163], v[10:13], v[106:109], 0
	v_mfma_f32_16x16x32_bf16 v[168:171], v[10:13], v[114:117], 0
	v_mfma_f32_16x16x32_bf16 v[6:9], v[14:17], v[126:129], v[6:9]
	v_mfma_f32_16x16x32_bf16 v[152:155], v[14:17], v[102:105], v[152:155]
	v_mfma_f32_16x16x32_bf16 v[160:163], v[14:17], v[110:113], v[160:163]
	v_mfma_f32_16x16x32_bf16 v[168:171], v[14:17], v[118:121], v[168:171]
	v_mfma_f32_16x16x32_bf16 v[10:13], v[18:21], v[62:65], 0
	v_mfma_f32_16x16x32_bf16 v[14:17], v[26:29], v[62:65], 0
	v_mfma_f32_16x16x32_bf16 v[10:13], v[22:25], v[102:105], v[10:13]
	v_mfma_f32_16x16x32_bf16 v[14:17], v[30:33], v[102:105], v[14:17]
	v_mfma_f32_16x16x32_bf16 v[62:65], v[18:21], v[106:109], 0
	v_mfma_f32_16x16x32_bf16 v[102:105], v[26:29], v[106:109], 0
	v_mfma_f32_16x16x32_bf16 v[106:109], v[18:21], v[114:117], 0
	v_mfma_f32_16x16x32_bf16 v[18:21], v[18:21], v[122:125], 0
	v_mfma_f32_16x16x32_bf16 v[62:65], v[22:25], v[110:113], v[62:65]
	v_mfma_f32_16x16x32_bf16 v[102:105], v[30:33], v[110:113], v[102:105]
	v_mfma_f32_16x16x32_bf16 v[106:109], v[22:25], v[118:121], v[106:109]
	v_mfma_f32_16x16x32_bf16 v[110:113], v[26:29], v[114:117], 0
	v_mfma_f32_16x16x32_bf16 v[18:21], v[22:25], v[126:129], v[18:21]
	v_mfma_f32_16x16x32_bf16 v[22:25], v[26:29], v[122:125], 0
	v_mfma_f32_16x16x32_bf16 v[110:113], v[30:33], v[118:121], v[110:113]
	v_mfma_f32_16x16x32_bf16 v[22:25], v[30:33], v[126:129], v[22:25]
	s_barrier
	s_add_i32 s64, 0, 0x18000
	s_add_i32 s70, 0, 0x1c000
	v_add_u32_e32 v151, s64, v147
	v_add_u32_e32 v217, s70, v147
	ds_read_b128 v[26:29], v151
	ds_read_b128 v[30:33], v151 offset:1024
	ds_read_b128 v[114:117], v151 offset:2048
	ds_read_b128 v[118:121], v151 offset:3072
	ds_read_b128 v[122:125], v217
	ds_read_b128 v[126:129], v217 offset:1024
	ds_read_b128 v[172:175], v217 offset:2048
	ds_read_b128 v[176:179], v217 offset:3072
	s_add_u32 s66, s58, 0x10100
	s_addc_u32 s67, s59, 0
	s_mov_b32 m0, s15
	v_lshl_add_u64 v[222:223], s[66:67], 0, v[130:131]
	ds_read_b128 v[180:183], v150 offset:32768
	ds_read_b128 v[184:187], v150 offset:33792
	ds_read_b128 v[188:191], v150 offset:34816
	ds_read_b128 v[192:195], v150 offset:35840
	ds_read_b128 v[196:199], v150 offset:36864
	ds_read_b128 v[200:203], v150 offset:37888
	ds_read_b128 v[204:207], v150 offset:38912
	ds_read_b128 v[208:211], v150 offset:39936
	global_load_lds_dwordx4 v[222:223], off
	v_lshl_add_u64 v[222:223], s[66:67], 0, v[134:135]
	s_mov_b32 m0, s33
	s_nop 0
	global_load_lds_dwordx4 v[222:223], off
	s_waitcnt vmcnt(8)
	s_waitcnt lgkmcnt(0)
	s_barrier
	s_waitcnt lgkmcnt(0)
	v_mfma_f32_16x16x32_bf16 v[66:69], v[26:29], v[180:183], v[66:69]
	v_mfma_f32_16x16x32_bf16 v[70:73], v[114:117], v[180:183], v[70:73]
	v_mfma_f32_16x16x32_bf16 v[74:77], v[26:29], v[188:191], v[74:77]
	v_mfma_f32_16x16x32_bf16 v[78:81], v[114:117], v[188:191], v[78:81]
	v_mfma_f32_16x16x32_bf16 v[82:85], v[26:29], v[196:199], v[82:85]
	v_mfma_f32_16x16x32_bf16 v[86:89], v[114:117], v[196:199], v[86:89]
	v_mfma_f32_16x16x32_bf16 v[90:93], v[26:29], v[204:207], v[90:93]
	v_mfma_f32_16x16x32_bf16 v[94:97], v[114:117], v[204:207], v[94:97]
	v_mfma_f32_16x16x32_bf16 v[66:69], v[30:33], v[184:187], v[66:69]
	v_mfma_f32_16x16x32_bf16 v[70:73], v[118:121], v[184:187], v[70:73]
	v_mfma_f32_16x16x32_bf16 v[74:77], v[30:33], v[192:195], v[74:77]
	v_mfma_f32_16x16x32_bf16 v[78:81], v[118:121], v[192:195], v[78:81]
	v_mfma_f32_16x16x32_bf16 v[82:85], v[30:33], v[200:203], v[82:85]
	v_mfma_f32_16x16x32_bf16 v[86:89], v[118:121], v[200:203], v[86:89]
	v_mfma_f32_16x16x32_bf16 v[90:93], v[30:33], v[208:211], v[90:93]
	v_mfma_f32_16x16x32_bf16 v[94:97], v[118:121], v[208:211], v[94:97]
	v_mfma_f32_16x16x32_bf16 v[98:101], v[122:125], v[180:183], v[98:101]
	v_mfma_f32_16x16x32_bf16 v[34:37], v[172:175], v[180:183], v[34:37]
	v_mfma_f32_16x16x32_bf16 v[38:41], v[122:125], v[188:191], v[38:41]
	v_mfma_f32_16x16x32_bf16 v[42:45], v[172:175], v[188:191], v[42:45]
	v_mfma_f32_16x16x32_bf16 v[46:49], v[122:125], v[196:199], v[46:49]
	v_mfma_f32_16x16x32_bf16 v[50:53], v[172:175], v[196:199], v[50:53]
	v_mfma_f32_16x16x32_bf16 v[54:57], v[122:125], v[204:207], v[54:57]
	v_mfma_f32_16x16x32_bf16 v[58:61], v[172:175], v[204:207], v[58:61]
	v_mfma_f32_16x16x32_bf16 v[98:101], v[126:129], v[184:187], v[98:101]
	v_mfma_f32_16x16x32_bf16 v[34:37], v[176:179], v[184:187], v[34:37]
	v_mfma_f32_16x16x32_bf16 v[38:41], v[126:129], v[192:195], v[38:41]
	v_mfma_f32_16x16x32_bf16 v[42:45], v[176:179], v[192:195], v[42:45]
	v_mfma_f32_16x16x32_bf16 v[46:49], v[126:129], v[200:203], v[46:49]
	v_mfma_f32_16x16x32_bf16 v[50:53], v[176:179], v[200:203], v[50:53]
	v_mfma_f32_16x16x32_bf16 v[54:57], v[126:129], v[208:211], v[54:57]
	v_mfma_f32_16x16x32_bf16 v[58:61], v[176:179], v[208:211], v[58:61]
	s_barrier
	s_add_i32 s66, s64, s12
	s_add_i32 s64, s66, 0x2000
	v_lshl_add_u64 v[212:213], v[212:213], 0, s[30:31]
	s_mov_b32 m0, s66
	s_add_u32 s68, s60, 0x10180
	ds_read_b128 v[180:183], v150 offset:49152
	ds_read_b128 v[184:187], v150 offset:50176
	ds_read_b128 v[188:191], v150 offset:51200
	ds_read_b128 v[192:195], v150 offset:52224
	ds_read_b128 v[196:199], v150 offset:53248
	ds_read_b128 v[200:203], v150 offset:54272
	ds_read_b128 v[204:207], v150 offset:55296
	ds_read_b128 v[208:211], v150 offset:56320
	global_load_lds_dwordx4 v[212:213], off
	v_lshl_add_u64 v[212:213], v[214:215], 0, s[30:31]
	s_mov_b32 m0, s64
	s_addc_u32 s69, s61, 0
	s_add_i32 s60, s70, s12
	global_load_lds_dwordx4 v[212:213], off
	v_lshl_add_u64 v[212:213], s[68:69], 0, v[132:133]
	s_mov_b32 m0, s60
	s_add_i32 s61, s60, 0x2000
	global_load_lds_dwordx4 v[212:213], off
	v_lshl_add_u64 v[212:213], s[68:69], 0, v[136:137]
	s_mov_b32 m0, s61
	s_nop 0
	global_load_lds_dwordx4 v[212:213], off
	v_lshl_add_u64 v[212:213], v[218:219], 0, s[30:31]
	s_mov_b32 m0, s42
	s_nop 0
	global_load_lds_dwordx4 v[212:213], off
	v_lshl_add_u64 v[212:213], v[220:221], 0, s[30:31]
	s_mov_b32 m0, s43
	s_nop 0
	global_load_lds_dwordx4 v[212:213], off
	s_waitcnt vmcnt(8)
	s_waitcnt lgkmcnt(0)
	s_barrier
	s_waitcnt lgkmcnt(0)
	v_mfma_f32_16x16x32_bf16 v[2:5], v[26:29], v[204:207], v[2:5]
	v_mfma_f32_16x16x32_bf16 v[6:9], v[114:117], v[204:207], v[6:9]
	v_mfma_f32_16x16x32_bf16 v[142:145], v[26:29], v[180:183], v[142:145]
	v_mfma_f32_16x16x32_bf16 v[152:155], v[114:117], v[180:183], v[152:155]
	v_mfma_f32_16x16x32_bf16 v[156:159], v[26:29], v[188:191], v[156:159]
	v_mfma_f32_16x16x32_bf16 v[160:163], v[114:117], v[188:191], v[160:163]
	v_mfma_f32_16x16x32_bf16 v[164:167], v[26:29], v[196:199], v[164:167]
	v_mfma_f32_16x16x32_bf16 v[168:171], v[114:117], v[196:199], v[168:171]
	v_mfma_f32_16x16x32_bf16 v[2:5], v[30:33], v[208:211], v[2:5]
	v_mfma_f32_16x16x32_bf16 v[6:9], v[118:121], v[208:211], v[6:9]
	v_mfma_f32_16x16x32_bf16 v[142:145], v[30:33], v[184:187], v[142:145]
	v_mfma_f32_16x16x32_bf16 v[152:155], v[118:121], v[184:187], v[152:155]
	v_mfma_f32_16x16x32_bf16 v[156:159], v[30:33], v[192:195], v[156:159]
	v_mfma_f32_16x16x32_bf16 v[160:163], v[118:121], v[192:195], v[160:163]
	v_mfma_f32_16x16x32_bf16 v[164:167], v[30:33], v[200:203], v[164:167]
	v_mfma_f32_16x16x32_bf16 v[168:171], v[118:121], v[200:203], v[168:171]
	v_mfma_f32_16x16x32_bf16 v[10:13], v[122:125], v[180:183], v[10:13]
	v_mfma_f32_16x16x32_bf16 v[14:17], v[172:175], v[180:183], v[14:17]
	v_mfma_f32_16x16x32_bf16 v[26:29], v[122:125], v[188:191], v[62:65]
	v_mfma_f32_16x16x32_bf16 v[30:33], v[172:175], v[188:191], v[102:105]
	v_mfma_f32_16x16x32_bf16 v[62:65], v[122:125], v[196:199], v[106:109]
	v_mfma_f32_16x16x32_bf16 v[102:105], v[172:175], v[196:199], v[110:113]
	v_mfma_f32_16x16x32_bf16 v[18:21], v[122:125], v[204:207], v[18:21]
	v_mfma_f32_16x16x32_bf16 v[22:25], v[172:175], v[204:207], v[22:25]
	v_mfma_f32_16x16x32_bf16 v[10:13], v[126:129], v[184:187], v[10:13]
	v_mfma_f32_16x16x32_bf16 v[14:17], v[176:179], v[184:187], v[14:17]
	v_mfma_f32_16x16x32_bf16 v[26:29], v[126:129], v[192:195], v[26:29]
	v_mfma_f32_16x16x32_bf16 v[30:33], v[176:179], v[192:195], v[30:33]
	v_mfma_f32_16x16x32_bf16 v[62:65], v[126:129], v[200:203], v[62:65]
	v_mfma_f32_16x16x32_bf16 v[102:105], v[176:179], v[200:203], v[102:105]
	v_mfma_f32_16x16x32_bf16 v[18:21], v[126:129], v[208:211], v[18:21]
	v_mfma_f32_16x16x32_bf16 v[22:25], v[176:179], v[208:211], v[22:25]
	s_barrier
	ds_read_b128 v[106:109], v148
	ds_read_b128 v[110:113], v148 offset:1024
	ds_read_b128 v[114:117], v148 offset:2048
	ds_read_b128 v[118:121], v148 offset:3072
	ds_read_b128 v[122:125], v149
	ds_read_b128 v[126:129], v149 offset:1024
	ds_read_b128 v[172:175], v149 offset:2048
	ds_read_b128 v[176:179], v149 offset:3072
	s_add_u32 s58, s58, 0x10180
	s_addc_u32 s59, s59, 0
	s_mov_b32 m0, s65
	v_lshl_add_u64 v[212:213], s[58:59], 0, v[130:131]
	ds_read_b128 v[180:183], v150
	ds_read_b128 v[184:187], v150 offset:1024
	ds_read_b128 v[188:191], v150 offset:2048
	ds_read_b128 v[192:195], v150 offset:3072
	ds_read_b128 v[196:199], v150 offset:4096
	ds_read_b128 v[200:203], v150 offset:5120
	ds_read_b128 v[204:207], v150 offset:6144
	ds_read_b128 v[208:211], v150 offset:7168
	global_load_lds_dwordx4 v[212:213], off
	v_lshl_add_u64 v[212:213], s[58:59], 0, v[134:135]
	s_mov_b32 m0, s2
	s_nop 0
	global_load_lds_dwordx4 v[212:213], off
	s_waitcnt vmcnt(8)
	s_waitcnt lgkmcnt(0)
	s_barrier
	s_waitcnt lgkmcnt(0)
	v_mfma_f32_16x16x32_bf16 v[90:93], v[106:109], v[204:207], v[90:93]
	v_mfma_f32_16x16x32_bf16 v[66:69], v[106:109], v[180:183], v[66:69]
	v_mfma_f32_16x16x32_bf16 v[70:73], v[114:117], v[180:183], v[70:73]
	v_mfma_f32_16x16x32_bf16 v[74:77], v[106:109], v[188:191], v[74:77]
	v_mfma_f32_16x16x32_bf16 v[78:81], v[114:117], v[188:191], v[78:81]
	v_mfma_f32_16x16x32_bf16 v[82:85], v[106:109], v[196:199], v[82:85]
	v_mfma_f32_16x16x32_bf16 v[86:89], v[114:117], v[196:199], v[86:89]
	v_mfma_f32_16x16x32_bf16 v[212:215], v[110:113], v[208:211], v[90:93]
	v_mfma_f32_16x16x32_bf16 v[90:93], v[114:117], v[204:207], v[94:97]
	v_mfma_f32_16x16x32_bf16 v[66:69], v[110:113], v[184:187], v[66:69]
	v_mfma_f32_16x16x32_bf16 v[70:73], v[118:121], v[184:187], v[70:73]
	v_mfma_f32_16x16x32_bf16 v[74:77], v[110:113], v[192:195], v[74:77]
	v_mfma_f32_16x16x32_bf16 v[78:81], v[118:121], v[192:195], v[78:81]
	v_mfma_f32_16x16x32_bf16 v[82:85], v[110:113], v[200:203], v[82:85]
	v_mfma_f32_16x16x32_bf16 v[86:89], v[118:121], v[200:203], v[86:89]
	v_mfma_f32_16x16x32_bf16 v[94:97], v[118:121], v[208:211], v[90:93]
	v_mfma_f32_16x16x32_bf16 v[34:37], v[172:175], v[180:183], v[34:37]
	v_mfma_f32_16x16x32_bf16 v[38:41], v[122:125], v[188:191], v[38:41]
	v_mfma_f32_16x16x32_bf16 v[42:45], v[172:175], v[188:191], v[42:45]
	v_mfma_f32_16x16x32_bf16 v[46:49], v[122:125], v[196:199], v[46:49]
	v_mfma_f32_16x16x32_bf16 v[50:53], v[172:175], v[196:199], v[50:53]
	v_mfma_f32_16x16x32_bf16 v[54:57], v[122:125], v[204:207], v[54:57]
	v_mfma_f32_16x16x32_bf16 v[58:61], v[172:175], v[204:207], v[58:61]
	v_mfma_f32_16x16x32_bf16 v[90:93], v[122:125], v[180:183], v[98:101]
	v_mfma_f32_16x16x32_bf16 v[34:37], v[176:179], v[184:187], v[34:37]
	v_mfma_f32_16x16x32_bf16 v[38:41], v[126:129], v[192:195], v[38:41]
	v_mfma_f32_16x16x32_bf16 v[42:45], v[176:179], v[192:195], v[42:45]
	v_mfma_f32_16x16x32_bf16 v[46:49], v[126:129], v[200:203], v[46:49]
	v_mfma_f32_16x16x32_bf16 v[50:53], v[176:179], v[200:203], v[50:53]
	v_mfma_f32_16x16x32_bf16 v[54:57], v[126:129], v[208:211], v[54:57]
	v_mfma_f32_16x16x32_bf16 v[58:61], v[176:179], v[208:211], v[58:61]
	v_mfma_f32_16x16x32_bf16 v[218:221], v[126:129], v[184:187], v[90:93]
	s_barrier
	s_mov_b32 m0, s57
	v_lshl_add_u64 v[248:249], s[6:7], 0, v[132:133]
	s_add_u32 s58, s6, 0x10000
	ds_read_b128 v[90:93], v150 offset:16384
	ds_read_b128 v[98:101], v150 offset:17408
	ds_read_b128 v[180:183], v150 offset:18432
	ds_read_b128 v[184:187], v150 offset:19456
	ds_read_b128 v[188:191], v150 offset:20480
	ds_read_b128 v[192:195], v150 offset:21504
	ds_read_b128 v[196:199], v150 offset:22528
	ds_read_b128 v[200:203], v150 offset:23552
	global_load_lds_dwordx4 v[248:249], off
	v_lshl_add_u64 v[250:251], s[6:7], 0, v[136:137]
	s_mov_b32 m0, s47
	s_addc_u32 s59, s7, 0
	global_load_lds_dwordx4 v[250:251], off
	v_lshl_add_u64 v[204:205], s[58:59], 0, v[132:133]
	s_mov_b32 m0, s49
	v_lshl_add_u64 v[252:253], s[50:51], 0, v[130:131]
	global_load_lds_dwordx4 v[204:205], off
	v_lshl_add_u64 v[204:205], s[58:59], 0, v[136:137]
	s_mov_b32 m0, s55
	v_lshl_add_u64 v[226:227], s[50:51], 0, v[134:135]
	global_load_lds_dwordx4 v[204:205], off
	s_mov_b32 m0, s13
	s_nop 0
	global_load_lds_dwordx4 v[252:253], off
	s_mov_b32 m0, s14
	s_nop 0
	global_load_lds_dwordx4 v[226:227], off
	s_waitcnt vmcnt(8)
	s_waitcnt lgkmcnt(0)
	s_barrier
	s_waitcnt lgkmcnt(0)
	v_mfma_f32_16x16x32_bf16 v[2:5], v[106:109], v[196:199], v[2:5]
	v_mfma_f32_16x16x32_bf16 v[6:9], v[114:117], v[196:199], v[6:9]
	v_mfma_f32_16x16x32_bf16 v[142:145], v[106:109], v[90:93], v[142:145]
	v_mfma_f32_16x16x32_bf16 v[152:155], v[114:117], v[90:93], v[152:155]
	v_mfma_f32_16x16x32_bf16 v[156:159], v[106:109], v[180:183], v[156:159]
	v_mfma_f32_16x16x32_bf16 v[160:163], v[114:117], v[180:183], v[160:163]
	v_mfma_f32_16x16x32_bf16 v[164:167], v[106:109], v[188:191], v[164:167]
	v_mfma_f32_16x16x32_bf16 v[168:171], v[114:117], v[188:191], v[168:171]
	v_mfma_f32_16x16x32_bf16 v[2:5], v[110:113], v[200:203], v[2:5]
	v_mfma_f32_16x16x32_bf16 v[6:9], v[118:121], v[200:203], v[6:9]
	v_mfma_f32_16x16x32_bf16 v[142:145], v[110:113], v[98:101], v[142:145]
	v_mfma_f32_16x16x32_bf16 v[152:155], v[118:121], v[98:101], v[152:155]
	v_mfma_f32_16x16x32_bf16 v[156:159], v[110:113], v[184:187], v[156:159]
	v_mfma_f32_16x16x32_bf16 v[160:163], v[118:121], v[184:187], v[160:163]
	v_mfma_f32_16x16x32_bf16 v[164:167], v[110:113], v[192:195], v[164:167]
	v_mfma_f32_16x16x32_bf16 v[168:171], v[118:121], v[192:195], v[168:171]
	v_mfma_f32_16x16x32_bf16 v[10:13], v[122:125], v[90:93], v[10:13]
	v_mfma_f32_16x16x32_bf16 v[204:207], v[126:129], v[98:101], v[10:13]
	v_mfma_f32_16x16x32_bf16 v[10:13], v[172:175], v[90:93], v[14:17]
	v_mfma_f32_16x16x32_bf16 v[14:17], v[176:179], v[98:101], v[10:13]
	v_mfma_f32_16x16x32_bf16 v[10:13], v[122:125], v[180:183], v[26:29]
	v_mfma_f32_16x16x32_bf16 v[208:211], v[126:129], v[184:187], v[10:13]
	v_mfma_f32_16x16x32_bf16 v[10:13], v[172:175], v[180:183], v[30:33]
	v_mfma_f32_16x16x32_bf16 v[30:33], v[176:179], v[184:187], v[10:13]
	v_mfma_f32_16x16x32_bf16 v[10:13], v[122:125], v[188:191], v[62:65]
	v_mfma_f32_16x16x32_bf16 v[180:183], v[126:129], v[192:195], v[10:13]
	v_mfma_f32_16x16x32_bf16 v[10:13], v[172:175], v[188:191], v[102:105]
	v_mfma_f32_16x16x32_bf16 v[184:187], v[176:179], v[192:195], v[10:13]
	v_mfma_f32_16x16x32_bf16 v[10:13], v[122:125], v[196:199], v[18:21]
	v_mfma_f32_16x16x32_bf16 v[188:191], v[126:129], v[200:203], v[10:13]
	v_mfma_f32_16x16x32_bf16 v[10:13], v[172:175], v[196:199], v[22:25]
	v_mfma_f32_16x16x32_bf16 v[172:175], v[176:179], v[200:203], v[10:13]
	s_barrier
	s_nop 4
	ds_read_b128 v[10:13], v151
	ds_read_b128 v[22:25], v151 offset:1024
	ds_read_b128 v[62:65], v151 offset:2048
	ds_read_b128 v[176:179], v151 offset:3072
	ds_read_b128 v[192:195], v217
	ds_read_b128 v[196:199], v217 offset:1024
	ds_read_b128 v[200:203], v217 offset:2048
	ds_read_b128 v[222:225], v217 offset:3072
	s_add_u32 s58, s50, 0x10000
	s_addc_u32 s59, s51, 0
	s_mov_b32 m0, s15
	v_lshl_add_u64 v[90:91], s[58:59], 0, v[130:131]
	ds_read_b128 v[18:21], v150 offset:32768
	ds_read_b128 v[26:29], v150 offset:33792
	ds_read_b128 v[102:105], v150 offset:34816
	ds_read_b128 v[228:231], v150 offset:35840
	ds_read_b128 v[232:235], v150 offset:36864
	ds_read_b128 v[236:239], v150 offset:37888
	ds_read_b128 v[240:243], v150 offset:38912
	ds_read_b128 v[244:247], v150 offset:39936
	global_load_lds_dwordx4 v[90:91], off
	v_lshl_add_u64 v[90:91], s[58:59], 0, v[134:135]
	s_mov_b32 m0, s33
	s_nop 0
	global_load_lds_dwordx4 v[90:91], off
	s_waitcnt vmcnt(8)
	s_waitcnt lgkmcnt(0)
	s_barrier
	s_waitcnt lgkmcnt(0)
	v_mfma_f32_16x16x32_bf16 v[66:69], v[10:13], v[18:21], v[66:69]
	v_mfma_f32_16x16x32_bf16 v[122:125], v[22:25], v[26:29], v[66:69]
	v_mfma_f32_16x16x32_bf16 v[66:69], v[62:65], v[18:21], v[70:73]
	v_mfma_f32_16x16x32_bf16 v[114:117], v[176:179], v[26:29], v[66:69]
	v_mfma_f32_16x16x32_bf16 v[66:69], v[10:13], v[102:105], v[74:77]
	v_mfma_f32_16x16x32_bf16 v[106:109], v[22:25], v[228:231], v[66:69]
	v_mfma_f32_16x16x32_bf16 v[66:69], v[62:65], v[102:105], v[78:81]
	v_mfma_f32_16x16x32_bf16 v[98:101], v[176:179], v[228:231], v[66:69]
	v_mfma_f32_16x16x32_bf16 v[66:69], v[10:13], v[232:235], v[82:85]
	v_mfma_f32_16x16x32_bf16 v[90:93], v[22:25], v[236:239], v[66:69]
	v_mfma_f32_16x16x32_bf16 v[66:69], v[62:65], v[232:235], v[86:89]
	v_mfma_f32_16x16x32_bf16 v[82:85], v[176:179], v[236:239], v[66:69]
	v_mfma_f32_16x16x32_bf16 v[66:69], v[10:13], v[240:243], v[212:215]
	v_mfma_f32_16x16x32_bf16 v[74:77], v[22:25], v[244:247], v[66:69]
	v_mfma_f32_16x16x32_bf16 v[66:69], v[62:65], v[240:243], v[94:97]
	v_mfma_f32_16x16x32_bf16 v[66:69], v[176:179], v[244:247], v[66:69]
	v_mfma_f32_16x16x32_bf16 v[70:73], v[192:195], v[18:21], v[218:221]
	v_mfma_f32_16x16x32_bf16 v[18:21], v[200:203], v[18:21], v[34:37]
	v_mfma_f32_16x16x32_bf16 v[118:121], v[222:225], v[26:29], v[18:21]
	v_mfma_f32_16x16x32_bf16 v[18:21], v[192:195], v[102:105], v[38:41]
	v_mfma_f32_16x16x32_bf16 v[110:113], v[196:199], v[228:231], v[18:21]
	v_mfma_f32_16x16x32_bf16 v[18:21], v[200:203], v[102:105], v[42:45]
	v_mfma_f32_16x16x32_bf16 v[102:105], v[222:225], v[228:231], v[18:21]
	v_mfma_f32_16x16x32_bf16 v[18:21], v[192:195], v[232:235], v[46:49]
	v_mfma_f32_16x16x32_bf16 v[94:97], v[196:199], v[236:239], v[18:21]
	v_mfma_f32_16x16x32_bf16 v[18:21], v[200:203], v[232:235], v[50:53]
	v_mfma_f32_16x16x32_bf16 v[86:89], v[222:225], v[236:239], v[18:21]
	v_mfma_f32_16x16x32_bf16 v[18:21], v[192:195], v[240:243], v[54:57]
	v_mfma_f32_16x16x32_bf16 v[78:81], v[196:199], v[244:247], v[18:21]
	v_mfma_f32_16x16x32_bf16 v[18:21], v[200:203], v[240:243], v[58:61]
	v_mfma_f32_16x16x32_bf16 v[126:129], v[196:199], v[26:29], v[70:73]
	v_mfma_f32_16x16x32_bf16 v[70:73], v[222:225], v[244:247], v[18:21]
	s_barrier
	s_mov_b32 m0, s66
	s_nop 2
	v_lshl_add_u64 v[18:19], v[248:249], 0, s[22:23]
	s_add_u32 s6, s6, 0x10080
	ds_read_b128 v[38:41], v150 offset:49152
	ds_read_b128 v[46:49], v150 offset:50176
	ds_read_b128 v[212:215], v150 offset:51200
	ds_read_b128 v[218:221], v150 offset:52224
	ds_read_b128 v[228:231], v150 offset:53248
	ds_read_b128 v[232:235], v150 offset:54272
	ds_read_b128 v[236:239], v150 offset:55296
	ds_read_b128 v[240:243], v150 offset:56320
	global_load_lds_dwordx4 v[18:19], off
	v_lshl_add_u64 v[18:19], v[250:251], 0, s[22:23]
	s_mov_b32 m0, s64
	s_addc_u32 s7, s7, 0
	global_load_lds_dwordx4 v[18:19], off
	v_lshl_add_u64 v[18:19], s[6:7], 0, v[132:133]
	s_mov_b32 m0, s60
	s_nop 0
	global_load_lds_dwordx4 v[18:19], off
	v_lshl_add_u64 v[18:19], s[6:7], 0, v[136:137]
	s_mov_b32 m0, s61
	s_nop 0
	global_load_lds_dwordx4 v[18:19], off
	v_lshl_add_u64 v[18:19], v[252:253], 0, s[22:23]
	s_mov_b32 m0, s42
	s_nop 0
	global_load_lds_dwordx4 v[18:19], off
	v_lshl_add_u64 v[18:19], v[226:227], 0, s[22:23]
	s_mov_b32 m0, s43
	s_nop 0
	global_load_lds_dwordx4 v[18:19], off
	s_waitcnt vmcnt(8)
	s_waitcnt lgkmcnt(0)
	s_barrier
	s_waitcnt lgkmcnt(0)
	v_mfma_f32_16x16x32_bf16 v[18:21], v[10:13], v[38:41], v[142:145]
	v_mfma_f32_16x16x32_bf16 v[58:61], v[22:25], v[46:49], v[18:21]
	v_mfma_f32_16x16x32_bf16 v[18:21], v[62:65], v[38:41], v[152:155]
	v_mfma_f32_16x16x32_bf16 v[50:53], v[176:179], v[46:49], v[18:21]
	v_mfma_f32_16x16x32_bf16 v[18:21], v[10:13], v[212:215], v[156:159]
	v_mfma_f32_16x16x32_bf16 v[42:45], v[22:25], v[218:221], v[18:21]
	v_mfma_f32_16x16x32_bf16 v[18:21], v[62:65], v[212:215], v[160:163]
	v_mfma_f32_16x16x32_bf16 v[34:37], v[176:179], v[218:221], v[18:21]
	v_mfma_f32_16x16x32_bf16 v[18:21], v[10:13], v[228:231], v[164:167]
	v_mfma_f32_16x16x32_bf16 v[2:5], v[10:13], v[236:239], v[2:5]
	v_mfma_f32_16x16x32_bf16 v[26:29], v[22:25], v[232:235], v[18:21]
	v_mfma_f32_16x16x32_bf16 v[18:21], v[62:65], v[228:231], v[168:171]
	v_mfma_f32_16x16x32_bf16 v[10:13], v[22:25], v[240:243], v[2:5]
	v_mfma_f32_16x16x32_bf16 v[2:5], v[62:65], v[236:239], v[6:9]
	v_mfma_f32_16x16x32_bf16 v[18:21], v[176:179], v[232:235], v[18:21]
	v_mfma_f32_16x16x32_bf16 v[2:5], v[176:179], v[240:243], v[2:5]
	v_mfma_f32_16x16x32_bf16 v[6:9], v[192:195], v[38:41], v[204:207]
	v_mfma_f32_16x16x32_bf16 v[62:65], v[196:199], v[46:49], v[6:9]
	v_mfma_f32_16x16x32_bf16 v[6:9], v[200:203], v[38:41], v[14:17]
	v_mfma_f32_16x16x32_bf16 v[54:57], v[222:225], v[46:49], v[6:9]
	v_mfma_f32_16x16x32_bf16 v[6:9], v[192:195], v[212:215], v[208:211]
	v_mfma_f32_16x16x32_bf16 v[46:49], v[196:199], v[218:221], v[6:9]
	v_mfma_f32_16x16x32_bf16 v[6:9], v[200:203], v[212:215], v[30:33]
	v_mfma_f32_16x16x32_bf16 v[38:41], v[222:225], v[218:221], v[6:9]
	v_mfma_f32_16x16x32_bf16 v[6:9], v[192:195], v[228:231], v[180:183]
	v_mfma_f32_16x16x32_bf16 v[30:33], v[196:199], v[232:235], v[6:9]
	v_mfma_f32_16x16x32_bf16 v[6:9], v[200:203], v[228:231], v[184:187]
	v_mfma_f32_16x16x32_bf16 v[22:25], v[222:225], v[232:235], v[6:9]
	v_mfma_f32_16x16x32_bf16 v[6:9], v[192:195], v[236:239], v[188:191]
	v_mfma_f32_16x16x32_bf16 v[14:17], v[196:199], v[240:243], v[6:9]
	v_mfma_f32_16x16x32_bf16 v[6:9], v[200:203], v[236:239], v[172:175]
	v_mfma_f32_16x16x32_bf16 v[6:9], v[222:225], v[240:243], v[6:9]
	s_barrier
	s_andn2_b64 vcc, exec, s[24:25]
	s_cbranch_vccnz .LBB0_372
	s_barrier

.LBB0_619:
	v_add_u32_e32 v153, s44, v151
	ds_read_b128 v[154:157], v153
	ds_read_b128 v[158:161], v153 offset:1024
	ds_read_b128 v[162:165], v153 offset:2048
	ds_read_b128 v[166:169], v153 offset:3072
	v_add_u32_e32 v153, s45, v151
	s_add_u32 s26, s18, s24
	ds_read_b128 v[170:173], v153
	ds_read_b128 v[174:177], v153 offset:1024
	ds_read_b128 v[178:181], v153 offset:2048
	ds_read_b128 v[182:185], v153 offset:3072
	s_addc_u32 s27, s19, s25
	s_add_u32 s26, s26, 0x100
	s_addc_u32 s27, s27, 0
	s_add_u32 s51, s48, s24
	s_addc_u32 s52, s49, s25
	s_cmpk_eq_i32 s24, 0x1500
	s_cselect_b32 s29, s23, s27
	s_cselect_b32 s28, s22, s26
	s_cselect_b32 s27, s9, s52
	s_cselect_b32 s26, s8, s51
	v_lshl_add_u64 v[218:219], v[146:147], 0, s[24:25]
	s_add_i32 m0, s33, 0xc000
	ds_read_b128 v[186:189], v152
	ds_read_b128 v[190:193], v152 offset:1024
	ds_read_b128 v[194:197], v152 offset:2048
	ds_read_b128 v[198:201], v152 offset:3072
	ds_read_b128 v[202:205], v152 offset:4096
	ds_read_b128 v[206:209], v152 offset:5120
	ds_read_b128 v[210:213], v152 offset:6144
	ds_read_b128 v[214:217], v152 offset:7168
	global_load_lds_dwordx4 v[218:219], off
	v_lshl_add_u64 v[218:219], v[148:149], 0, s[24:25]
	s_add_i32 m0, s33, 0xe000
	s_nop 0
	global_load_lds_dwordx4 v[218:219], off
	s_waitcnt vmcnt(8)
	s_waitcnt lgkmcnt(0)
	s_barrier
	s_waitcnt lgkmcnt(0)
	v_mfma_f32_16x16x32_bf16 v[126:129], v[154:157], v[186:189], v[126:129]
	v_mfma_f32_16x16x32_bf16 v[122:125], v[162:165], v[186:189], v[122:125]
	v_mfma_f32_16x16x32_bf16 v[110:113], v[154:157], v[194:197], v[110:113]
	v_mfma_f32_16x16x32_bf16 v[106:109], v[162:165], v[194:197], v[106:109]
	v_mfma_f32_16x16x32_bf16 v[94:97], v[154:157], v[202:205], v[94:97]
	v_mfma_f32_16x16x32_bf16 v[90:93], v[162:165], v[202:205], v[90:93]
	v_mfma_f32_16x16x32_bf16 v[78:81], v[154:157], v[210:213], v[78:81]
	v_mfma_f32_16x16x32_bf16 v[74:77], v[162:165], v[210:213], v[74:77]
	v_mfma_f32_16x16x32_bf16 v[126:129], v[158:161], v[190:193], v[126:129]
	v_mfma_f32_16x16x32_bf16 v[122:125], v[166:169], v[190:193], v[122:125]
	v_mfma_f32_16x16x32_bf16 v[110:113], v[158:161], v[198:201], v[110:113]
	v_mfma_f32_16x16x32_bf16 v[106:109], v[166:169], v[198:201], v[106:109]
	v_mfma_f32_16x16x32_bf16 v[94:97], v[158:161], v[206:209], v[94:97]
	v_mfma_f32_16x16x32_bf16 v[90:93], v[166:169], v[206:209], v[90:93]
	v_mfma_f32_16x16x32_bf16 v[78:81], v[158:161], v[214:217], v[78:81]
	v_mfma_f32_16x16x32_bf16 v[74:77], v[166:169], v[214:217], v[74:77]
	v_mfma_f32_16x16x32_bf16 v[118:121], v[170:173], v[186:189], v[118:121]
	v_mfma_f32_16x16x32_bf16 v[114:117], v[178:181], v[186:189], v[114:117]
	v_mfma_f32_16x16x32_bf16 v[102:105], v[170:173], v[194:197], v[102:105]
	v_mfma_f32_16x16x32_bf16 v[98:101], v[178:181], v[194:197], v[98:101]
	v_mfma_f32_16x16x32_bf16 v[86:89], v[170:173], v[202:205], v[86:89]
	v_mfma_f32_16x16x32_bf16 v[82:85], v[178:181], v[202:205], v[82:85]
	v_mfma_f32_16x16x32_bf16 v[70:73], v[170:173], v[210:213], v[70:73]
	v_mfma_f32_16x16x32_bf16 v[66:69], v[178:181], v[210:213], v[66:69]
	v_mfma_f32_16x16x32_bf16 v[118:121], v[174:177], v[190:193], v[118:121]
	v_mfma_f32_16x16x32_bf16 v[114:117], v[182:185], v[190:193], v[114:117]
	v_mfma_f32_16x16x32_bf16 v[102:105], v[174:177], v[198:201], v[102:105]
	v_mfma_f32_16x16x32_bf16 v[98:101], v[182:185], v[198:201], v[98:101]
	v_mfma_f32_16x16x32_bf16 v[86:89], v[174:177], v[206:209], v[86:89]
	v_mfma_f32_16x16x32_bf16 v[82:85], v[182:185], v[206:209], v[82:85]
	v_mfma_f32_16x16x32_bf16 v[70:73], v[174:177], v[214:217], v[70:73]
	v_mfma_f32_16x16x32_bf16 v[66:69], v[182:185], v[214:217], v[66:69]
	s_barrier
	s_add_i32 s51, s44, s13
	s_add_u32 s98, s26, s20
	s_addc_u32 s99, s27, s21
	s_mov_b32 m0, s51
	ds_read_b128 v[186:189], v152 offset:16384
	ds_read_b128 v[190:193], v152 offset:17408
	ds_read_b128 v[194:197], v152 offset:18432
	ds_read_b128 v[198:201], v152 offset:19456
	ds_read_b128 v[202:205], v152 offset:20480
	ds_read_b128 v[206:209], v152 offset:21504
	ds_read_b128 v[210:213], v152 offset:22528
	ds_read_b128 v[214:217], v152 offset:23552
	global_load_lds_dwordx4 v132, s[26:27]
	s_add_i32 m0, s51, 0x2000
	s_add_u32 s52, s26, 0xb0000
	s_addc_u32 s53, s27, 0
	s_add_i32 s51, s45, s13
	global_load_lds_dwordx4 v136, s[26:27]
	s_mov_b32 m0, s51
	s_nop 0
	global_load_lds_dwordx4 v132, s[52:53]
	s_add_i32 m0, s51, 0x2000
	s_nop 0
	global_load_lds_dwordx4 v136, s[52:53]
	s_add_u32 s100, s28, s20
	s_addc_u32 s101, s29, s21
	s_mov_b32 m0, s33
	s_nop 0
	global_load_lds_dwordx4 v130, s[28:29]
	s_mov_b32 m0, s14
	s_nop 0
	global_load_lds_dwordx4 v134, s[28:29]
	s_waitcnt vmcnt(8)
	s_waitcnt lgkmcnt(0)
	s_barrier
	s_waitcnt lgkmcnt(0)
	v_mfma_f32_16x16x32_bf16 v[62:65], v[154:157], v[186:189], v[62:65]
	v_mfma_f32_16x16x32_bf16 v[58:61], v[162:165], v[186:189], v[58:61]
	v_mfma_f32_16x16x32_bf16 v[46:49], v[154:157], v[194:197], v[46:49]
	v_mfma_f32_16x16x32_bf16 v[42:45], v[162:165], v[194:197], v[42:45]
	v_mfma_f32_16x16x32_bf16 v[30:33], v[154:157], v[202:205], v[30:33]
	v_mfma_f32_16x16x32_bf16 v[26:29], v[162:165], v[202:205], v[26:29]
	v_mfma_f32_16x16x32_bf16 v[14:17], v[154:157], v[210:213], v[14:17]
	v_mfma_f32_16x16x32_bf16 v[10:13], v[162:165], v[210:213], v[10:13]
	v_mfma_f32_16x16x32_bf16 v[62:65], v[158:161], v[190:193], v[62:65]
	v_mfma_f32_16x16x32_bf16 v[58:61], v[166:169], v[190:193], v[58:61]
	v_mfma_f32_16x16x32_bf16 v[46:49], v[158:161], v[198:201], v[46:49]
	v_mfma_f32_16x16x32_bf16 v[42:45], v[166:169], v[198:201], v[42:45]
	v_mfma_f32_16x16x32_bf16 v[30:33], v[158:161], v[206:209], v[30:33]
	v_mfma_f32_16x16x32_bf16 v[26:29], v[166:169], v[206:209], v[26:29]
	v_mfma_f32_16x16x32_bf16 v[14:17], v[158:161], v[214:217], v[14:17]
	v_mfma_f32_16x16x32_bf16 v[10:13], v[166:169], v[214:217], v[10:13]
	v_mfma_f32_16x16x32_bf16 v[54:57], v[170:173], v[186:189], v[54:57]
	v_mfma_f32_16x16x32_bf16 v[50:53], v[178:181], v[186:189], v[50:53]
	v_mfma_f32_16x16x32_bf16 v[38:41], v[170:173], v[194:197], v[38:41]
	v_mfma_f32_16x16x32_bf16 v[34:37], v[178:181], v[194:197], v[34:37]
	v_mfma_f32_16x16x32_bf16 v[22:25], v[170:173], v[202:205], v[22:25]
	v_mfma_f32_16x16x32_bf16 v[18:21], v[178:181], v[202:205], v[18:21]
	v_mfma_f32_16x16x32_bf16 v[6:9], v[170:173], v[210:213], v[6:9]
	v_mfma_f32_16x16x32_bf16 v[2:5], v[178:181], v[210:213], v[2:5]
	v_mfma_f32_16x16x32_bf16 v[54:57], v[174:177], v[190:193], v[54:57]
	v_mfma_f32_16x16x32_bf16 v[50:53], v[182:185], v[190:193], v[50:53]
	v_mfma_f32_16x16x32_bf16 v[38:41], v[174:177], v[198:201], v[38:41]
	v_mfma_f32_16x16x32_bf16 v[34:37], v[182:185], v[198:201], v[34:37]
	v_mfma_f32_16x16x32_bf16 v[22:25], v[174:177], v[206:209], v[22:25]
	v_mfma_f32_16x16x32_bf16 v[18:21], v[182:185], v[206:209], v[18:21]
	v_mfma_f32_16x16x32_bf16 v[6:9], v[174:177], v[214:217], v[6:9]
	v_mfma_f32_16x16x32_bf16 v[2:5], v[182:185], v[214:217], v[2:5]
	s_barrier
	s_add_i32 s51, 0, 0x18000
	v_add_u32_e32 v153, s51, v151
	s_add_i32 s52, 0, 0x1c000
	ds_read_b128 v[154:157], v153
	ds_read_b128 v[158:161], v153 offset:1024
	ds_read_b128 v[162:165], v153 offset:2048
	ds_read_b128 v[166:169], v153 offset:3072
	v_add_u32_e32 v153, s52, v151
	ds_read_b128 v[170:173], v153
	ds_read_b128 v[174:177], v153 offset:1024
	ds_read_b128 v[178:181], v153 offset:2048
	ds_read_b128 v[182:185], v153 offset:3072
	s_add_u32 s28, s28, 0xb0000
	s_addc_u32 s29, s29, 0
	s_mov_b32 m0, s15
	ds_read_b128 v[186:189], v152 offset:32768
	ds_read_b128 v[190:193], v152 offset:33792
	ds_read_b128 v[194:197], v152 offset:34816
	ds_read_b128 v[198:201], v152 offset:35840
	ds_read_b128 v[202:205], v152 offset:36864
	ds_read_b128 v[206:209], v152 offset:37888
	ds_read_b128 v[210:213], v152 offset:38912
	ds_read_b128 v[214:217], v152 offset:39936
	global_load_lds_dwordx4 v130, s[28:29]
	s_mov_b32 m0, s40
	s_nop 0
	global_load_lds_dwordx4 v134, s[28:29]
	s_waitcnt vmcnt(8)
	s_waitcnt lgkmcnt(0)
	s_barrier
	s_waitcnt lgkmcnt(0)
	v_mfma_f32_16x16x32_bf16 v[126:129], v[154:157], v[186:189], v[126:129]
	v_mfma_f32_16x16x32_bf16 v[122:125], v[162:165], v[186:189], v[122:125]
	v_mfma_f32_16x16x32_bf16 v[110:113], v[154:157], v[194:197], v[110:113]
	v_mfma_f32_16x16x32_bf16 v[106:109], v[162:165], v[194:197], v[106:109]
	v_mfma_f32_16x16x32_bf16 v[94:97], v[154:157], v[202:205], v[94:97]
	v_mfma_f32_16x16x32_bf16 v[90:93], v[162:165], v[202:205], v[90:93]
	v_mfma_f32_16x16x32_bf16 v[78:81], v[154:157], v[210:213], v[78:81]
	v_mfma_f32_16x16x32_bf16 v[74:77], v[162:165], v[210:213], v[74:77]
	v_mfma_f32_16x16x32_bf16 v[126:129], v[158:161], v[190:193], v[126:129]
	v_mfma_f32_16x16x32_bf16 v[122:125], v[166:169], v[190:193], v[122:125]
	v_mfma_f32_16x16x32_bf16 v[110:113], v[158:161], v[198:201], v[110:113]
	v_mfma_f32_16x16x32_bf16 v[106:109], v[166:169], v[198:201], v[106:109]
	v_mfma_f32_16x16x32_bf16 v[94:97], v[158:161], v[206:209], v[94:97]
	v_mfma_f32_16x16x32_bf16 v[90:93], v[166:169], v[206:209], v[90:93]
	v_mfma_f32_16x16x32_bf16 v[78:81], v[158:161], v[214:217], v[78:81]
	v_mfma_f32_16x16x32_bf16 v[74:77], v[166:169], v[214:217], v[74:77]
	v_mfma_f32_16x16x32_bf16 v[118:121], v[170:173], v[186:189], v[118:121]
	v_mfma_f32_16x16x32_bf16 v[114:117], v[178:181], v[186:189], v[114:117]
	v_mfma_f32_16x16x32_bf16 v[102:105], v[170:173], v[194:197], v[102:105]
	v_mfma_f32_16x16x32_bf16 v[98:101], v[178:181], v[194:197], v[98:101]
	v_mfma_f32_16x16x32_bf16 v[86:89], v[170:173], v[202:205], v[86:89]
	v_mfma_f32_16x16x32_bf16 v[82:85], v[178:181], v[202:205], v[82:85]
	v_mfma_f32_16x16x32_bf16 v[70:73], v[170:173], v[210:213], v[70:73]
	v_mfma_f32_16x16x32_bf16 v[66:69], v[178:181], v[210:213], v[66:69]
	v_mfma_f32_16x16x32_bf16 v[118:121], v[174:177], v[190:193], v[118:121]
	v_mfma_f32_16x16x32_bf16 v[114:117], v[182:185], v[190:193], v[114:117]
	v_mfma_f32_16x16x32_bf16 v[102:105], v[174:177], v[198:201], v[102:105]
	v_mfma_f32_16x16x32_bf16 v[98:101], v[182:185], v[198:201], v[98:101]
	v_mfma_f32_16x16x32_bf16 v[86:89], v[174:177], v[206:209], v[86:89]
	v_mfma_f32_16x16x32_bf16 v[82:85], v[182:185], v[206:209], v[82:85]
	v_mfma_f32_16x16x32_bf16 v[70:73], v[174:177], v[214:217], v[70:73]
	v_mfma_f32_16x16x32_bf16 v[66:69], v[182:185], v[214:217], v[66:69]
	s_barrier
	s_add_i32 s28, s51, s13
	s_mov_b32 m0, s28
	ds_read_b128 v[186:189], v152 offset:49152
	ds_read_b128 v[190:193], v152 offset:50176
	ds_read_b128 v[194:197], v152 offset:51200
	ds_read_b128 v[198:201], v152 offset:52224
	ds_read_b128 v[202:205], v152 offset:53248
	ds_read_b128 v[206:209], v152 offset:54272
	ds_read_b128 v[210:213], v152 offset:55296
	ds_read_b128 v[214:217], v152 offset:56320
	global_load_lds_dwordx4 v132, s[98:99]
	s_add_i32 m0, s28, 0x2000
	s_add_u32 s26, s26, 0xb0080
	s_addc_u32 s27, s27, 0
	s_add_i32 s28, s52, s13
	global_load_lds_dwordx4 v136, s[98:99]
	s_mov_b32 m0, s28
	s_nop 0
	global_load_lds_dwordx4 v132, s[26:27]
	s_add_i32 m0, s28, 0x2000
	s_nop 0
	global_load_lds_dwordx4 v136, s[26:27]
	s_mov_b32 m0, s42
	s_nop 0
	global_load_lds_dwordx4 v130, s[100:101]
	s_mov_b32 m0, s43
	s_nop 0
	global_load_lds_dwordx4 v134, s[100:101]
	s_waitcnt vmcnt(8)
	s_waitcnt lgkmcnt(0)
	s_barrier
	s_waitcnt lgkmcnt(0)
	v_mfma_f32_16x16x32_bf16 v[62:65], v[154:157], v[186:189], v[62:65]
	v_mfma_f32_16x16x32_bf16 v[58:61], v[162:165], v[186:189], v[58:61]
	v_mfma_f32_16x16x32_bf16 v[46:49], v[154:157], v[194:197], v[46:49]
	v_mfma_f32_16x16x32_bf16 v[42:45], v[162:165], v[194:197], v[42:45]
	v_mfma_f32_16x16x32_bf16 v[30:33], v[154:157], v[202:205], v[30:33]
	v_mfma_f32_16x16x32_bf16 v[26:29], v[162:165], v[202:205], v[26:29]
	v_mfma_f32_16x16x32_bf16 v[14:17], v[154:157], v[210:213], v[14:17]
	v_mfma_f32_16x16x32_bf16 v[10:13], v[162:165], v[210:213], v[10:13]
	v_mfma_f32_16x16x32_bf16 v[62:65], v[158:161], v[190:193], v[62:65]
	v_mfma_f32_16x16x32_bf16 v[58:61], v[166:169], v[190:193], v[58:61]
	v_mfma_f32_16x16x32_bf16 v[46:49], v[158:161], v[198:201], v[46:49]
	v_mfma_f32_16x16x32_bf16 v[42:45], v[166:169], v[198:201], v[42:45]
	v_mfma_f32_16x16x32_bf16 v[30:33], v[158:161], v[206:209], v[30:33]
	v_mfma_f32_16x16x32_bf16 v[26:29], v[166:169], v[206:209], v[26:29]
	v_mfma_f32_16x16x32_bf16 v[14:17], v[158:161], v[214:217], v[14:17]
	v_mfma_f32_16x16x32_bf16 v[10:13], v[166:169], v[214:217], v[10:13]
	v_mfma_f32_16x16x32_bf16 v[54:57], v[170:173], v[186:189], v[54:57]
	v_mfma_f32_16x16x32_bf16 v[50:53], v[178:181], v[186:189], v[50:53]
	v_mfma_f32_16x16x32_bf16 v[38:41], v[170:173], v[194:197], v[38:41]
	v_mfma_f32_16x16x32_bf16 v[34:37], v[178:181], v[194:197], v[34:37]
	v_mfma_f32_16x16x32_bf16 v[22:25], v[170:173], v[202:205], v[22:25]
	v_mfma_f32_16x16x32_bf16 v[18:21], v[178:181], v[202:205], v[18:21]
	v_mfma_f32_16x16x32_bf16 v[6:9], v[170:173], v[210:213], v[6:9]
	v_mfma_f32_16x16x32_bf16 v[2:5], v[178:181], v[210:213], v[2:5]
	v_mfma_f32_16x16x32_bf16 v[54:57], v[174:177], v[190:193], v[54:57]
	v_mfma_f32_16x16x32_bf16 v[50:53], v[182:185], v[190:193], v[50:53]
	v_mfma_f32_16x16x32_bf16 v[38:41], v[174:177], v[198:201], v[38:41]
	v_mfma_f32_16x16x32_bf16 v[34:37], v[182:185], v[198:201], v[34:37]
	v_mfma_f32_16x16x32_bf16 v[22:25], v[174:177], v[206:209], v[22:25]
	v_mfma_f32_16x16x32_bf16 v[18:21], v[182:185], v[206:209], v[18:21]
	v_mfma_f32_16x16x32_bf16 v[6:9], v[174:177], v[214:217], v[6:9]
	v_mfma_f32_16x16x32_bf16 v[2:5], v[182:185], v[214:217], v[2:5]
	s_barrier
	s_add_i32 s50, s50, 2
	s_add_u32 s24, s24, 0x100
	s_addc_u32 s25, s25, 0
	s_cmp_gt_u32 s50, 41
	s_cbranch_scc0 .LBB0_619
	s_add_u32 s24, s48, 0xffffff00
	s_addc_u32 s25, s49, -1
	s_and_b64 vcc, exec, s[6:7]
	s_cbranch_vccnz .LBB0_622
	v_mov_b32_e32 v2, 0
	s_mov_b32 s10, s46
	s_mov_b32 s31, s47
	s_mov_b64 s[18:19], s[22:23]
	s_mov_b32 s41, s2
	v_mov_b32_e32 v3, v2
	v_mov_b32_e32 v4, v2
	v_mov_b32_e32 v5, v2
	v_mov_b32_e32 v6, v2
	v_mov_b32_e32 v7, v2
	v_mov_b32_e32 v8, v2
	v_mov_b32_e32 v9, v2
	v_mov_b32_e32 v18, v2
	v_mov_b32_e32 v19, v2
	v_mov_b32_e32 v20, v2
	v_mov_b32_e32 v21, v2
	v_mov_b32_e32 v22, v2
	v_mov_b32_e32 v23, v2
	v_mov_b32_e32 v24, v2
	v_mov_b32_e32 v25, v2
	v_mov_b32_e32 v34, v2
	v_mov_b32_e32 v35, v2
	v_mov_b32_e32 v36, v2
	v_mov_b32_e32 v37, v2
	v_mov_b32_e32 v38, v2
	v_mov_b32_e32 v39, v2
	v_mov_b32_e32 v40, v2
	v_mov_b32_e32 v41, v2
	v_mov_b32_e32 v50, v2
	v_mov_b32_e32 v51, v2
	v_mov_b32_e32 v52, v2
	v_mov_b32_e32 v53, v2
	v_mov_b32_e32 v54, v2
	v_mov_b32_e32 v55, v2
	v_mov_b32_e32 v56, v2
	v_mov_b32_e32 v57, v2
	v_mov_b32_e32 v10, v2
	v_mov_b32_e32 v11, v2
	v_mov_b32_e32 v12, v2
	v_mov_b32_e32 v13, v2
	v_mov_b32_e32 v14, v2
	v_mov_b32_e32 v15, v2
	v_mov_b32_e32 v16, v2
	v_mov_b32_e32 v17, v2
	v_mov_b32_e32 v26, v2
	v_mov_b32_e32 v27, v2
	v_mov_b32_e32 v28, v2
	v_mov_b32_e32 v29, v2
	v_mov_b32_e32 v30, v2
	v_mov_b32_e32 v31, v2
	v_mov_b32_e32 v32, v2
	v_mov_b32_e32 v33, v2
	v_mov_b32_e32 v42, v2
	v_mov_b32_e32 v43, v2
	v_mov_b32_e32 v44, v2
	v_mov_b32_e32 v45, v2
	v_mov_b32_e32 v46, v2
	v_mov_b32_e32 v47, v2
	v_mov_b32_e32 v48, v2
	v_mov_b32_e32 v49, v2
	v_mov_b32_e32 v58, v2
	v_mov_b32_e32 v59, v2
	v_mov_b32_e32 v60, v2
	v_mov_b32_e32 v61, v2
	v_mov_b32_e32 v62, v2
	v_mov_b32_e32 v63, v2
	v_mov_b32_e32 v64, v2
	v_mov_b32_e32 v65, v2
	v_mov_b32_e32 v66, v2
	v_mov_b32_e32 v67, v2
	v_mov_b32_e32 v68, v2
	v_mov_b32_e32 v69, v2
	v_mov_b32_e32 v70, v2
	v_mov_b32_e32 v71, v2
	v_mov_b32_e32 v72, v2
	v_mov_b32_e32 v73, v2
	v_mov_b32_e32 v82, v2
	v_mov_b32_e32 v83, v2
	v_mov_b32_e32 v84, v2
	v_mov_b32_e32 v85, v2
	v_mov_b32_e32 v86, v2
	v_mov_b32_e32 v87, v2
	v_mov_b32_e32 v88, v2
	v_mov_b32_e32 v89, v2
	v_mov_b32_e32 v98, v2
	v_mov_b32_e32 v99, v2
	v_mov_b32_e32 v100, v2
	v_mov_b32_e32 v101, v2
	v_mov_b32_e32 v102, v2
	v_mov_b32_e32 v103, v2
	v_mov_b32_e32 v104, v2
	v_mov_b32_e32 v105, v2
	v_mov_b32_e32 v114, v2
	v_mov_b32_e32 v115, v2
	v_mov_b32_e32 v116, v2
	v_mov_b32_e32 v117, v2
	v_mov_b32_e32 v118, v2
	v_mov_b32_e32 v119, v2
	v_mov_b32_e32 v120, v2
	v_mov_b32_e32 v121, v2
	v_mov_b32_e32 v74, v2
	v_mov_b32_e32 v75, v2
	v_mov_b32_e32 v76, v2
	v_mov_b32_e32 v77, v2
	v_mov_b32_e32 v78, v2
	v_mov_b32_e32 v79, v2
	v_mov_b32_e32 v80, v2
	v_mov_b32_e32 v81, v2
	v_mov_b32_e32 v90, v2
	v_mov_b32_e32 v91, v2
	v_mov_b32_e32 v92, v2
	v_mov_b32_e32 v93, v2
	v_mov_b32_e32 v94, v2
	v_mov_b32_e32 v95, v2
	v_mov_b32_e32 v96, v2
	v_mov_b32_e32 v97, v2
	v_mov_b32_e32 v106, v2
	v_mov_b32_e32 v107, v2
	v_mov_b32_e32 v108, v2
	v_mov_b32_e32 v109, v2
	v_mov_b32_e32 v110, v2
	v_mov_b32_e32 v111, v2
	v_mov_b32_e32 v112, v2
	v_mov_b32_e32 v113, v2
	v_mov_b32_e32 v122, v2
	v_mov_b32_e32 v123, v2
	v_mov_b32_e32 v124, v2
	v_mov_b32_e32 v125, v2
	v_mov_b32_e32 v126, v2
	v_mov_b32_e32 v127, v2
	v_mov_b32_e32 v128, v2
	v_mov_b32_e32 v129, v2
	s_andn2_b64 vcc, exec, s[4:5]
	s_cbranch_vccnz .LBB0_623
	s_branch .LBB0_624

.LBB0_774:
	ds_read_b128 v[38:41], v231
	ds_read_b128 v[42:45], v231 offset:1024
	ds_read_b128 v[54:57], v231 offset:2048
	ds_read_b128 v[58:61], v231 offset:3072
	ds_read_b128 v[126:129], v232
	ds_read_b128 v[146:149], v232 offset:1024
	ds_read_b128 v[166:169], v232 offset:2048
	ds_read_b128 v[170:173], v232 offset:3072
	s_add_u32 s14, s10, 0xfffc0080
	s_addc_u32 s15, s11, -1
	s_cmp_eq_u32 s13, 12
	s_cselect_b32 s59, s0, s15
	s_cselect_b32 s58, s1, s14
	s_cselect_b32 s57, s2, s12
	s_cselect_b32 s56, s7, s9
	s_add_i32 m0, s67, 0xc000
	ds_read_b128 v[174:177], v233
	ds_read_b128 v[194:197], v233 offset:1024
	ds_read_b128 v[198:201], v233 offset:2048
	ds_read_b128 v[202:205], v233 offset:3072
	ds_read_b128 v[206:209], v233 offset:4096
	ds_read_b128 v[210:213], v233 offset:5120
	ds_read_b128 v[214:217], v233 offset:6144
	ds_read_b128 v[218:221], v233 offset:7168
	global_load_lds_dwordx4 v186, s[10:11]
	s_add_i32 m0, s67, 0xe000
	s_nop 0
	global_load_lds_dwordx4 v188, s[10:11]
	s_waitcnt vmcnt(8)
	s_waitcnt lgkmcnt(0)
	s_barrier
	s_waitcnt lgkmcnt(0)
	v_mfma_f32_16x16x32_bf16 v[162:165], v[38:41], v[174:177], v[162:165]
	v_mfma_f32_16x16x32_bf16 v[158:161], v[54:57], v[174:177], v[158:161]
	v_mfma_f32_16x16x32_bf16 v[142:145], v[38:41], v[198:201], v[142:145]
	v_mfma_f32_16x16x32_bf16 v[138:141], v[54:57], v[198:201], v[138:141]
	v_mfma_f32_16x16x32_bf16 v[122:125], v[38:41], v[206:209], v[122:125]
	v_mfma_f32_16x16x32_bf16 v[118:121], v[54:57], v[206:209], v[118:121]
	v_mfma_f32_16x16x32_bf16 v[106:109], v[38:41], v[214:217], v[106:109]
	v_mfma_f32_16x16x32_bf16 v[102:105], v[54:57], v[214:217], v[102:105]
	v_mfma_f32_16x16x32_bf16 v[162:165], v[42:45], v[194:197], v[162:165]
	v_mfma_f32_16x16x32_bf16 v[158:161], v[58:61], v[194:197], v[158:161]
	v_mfma_f32_16x16x32_bf16 v[142:145], v[42:45], v[202:205], v[142:145]
	v_mfma_f32_16x16x32_bf16 v[138:141], v[58:61], v[202:205], v[138:141]
	v_mfma_f32_16x16x32_bf16 v[122:125], v[42:45], v[210:213], v[122:125]
	v_mfma_f32_16x16x32_bf16 v[118:121], v[58:61], v[210:213], v[118:121]
	v_mfma_f32_16x16x32_bf16 v[106:109], v[42:45], v[218:221], v[106:109]
	v_mfma_f32_16x16x32_bf16 v[102:105], v[58:61], v[218:221], v[102:105]
	v_mfma_f32_16x16x32_bf16 v[154:157], v[126:129], v[174:177], v[154:157]
	v_mfma_f32_16x16x32_bf16 v[150:153], v[166:169], v[174:177], v[150:153]
	v_mfma_f32_16x16x32_bf16 v[134:137], v[126:129], v[198:201], v[134:137]
	v_mfma_f32_16x16x32_bf16 v[130:133], v[166:169], v[198:201], v[130:133]
	v_mfma_f32_16x16x32_bf16 v[114:117], v[126:129], v[206:209], v[114:117]
	v_mfma_f32_16x16x32_bf16 v[110:113], v[166:169], v[206:209], v[110:113]
	v_mfma_f32_16x16x32_bf16 v[98:101], v[126:129], v[214:217], v[98:101]
	v_mfma_f32_16x16x32_bf16 v[94:97], v[166:169], v[214:217], v[94:97]
	v_mfma_f32_16x16x32_bf16 v[154:157], v[146:149], v[194:197], v[154:157]
	v_mfma_f32_16x16x32_bf16 v[150:153], v[170:173], v[194:197], v[150:153]
	v_mfma_f32_16x16x32_bf16 v[134:137], v[146:149], v[202:205], v[134:137]
	v_mfma_f32_16x16x32_bf16 v[130:133], v[170:173], v[202:205], v[130:133]
	v_mfma_f32_16x16x32_bf16 v[114:117], v[146:149], v[210:213], v[114:117]
	v_mfma_f32_16x16x32_bf16 v[110:113], v[170:173], v[210:213], v[110:113]
	v_mfma_f32_16x16x32_bf16 v[98:101], v[146:149], v[218:221], v[98:101]
	v_mfma_f32_16x16x32_bf16 v[94:97], v[170:173], v[218:221], v[94:97]
	s_barrier
	s_add_i32 s14, s84, s66
	s_add_u32 s98, s56, s20
	s_addc_u32 s99, s57, s21
	s_mov_b32 m0, s14
	ds_read_b128 v[174:177], v233 offset:16384
	ds_read_b128 v[194:197], v233 offset:17408
	ds_read_b128 v[198:201], v233 offset:18432
	ds_read_b128 v[202:205], v233 offset:19456
	ds_read_b128 v[206:209], v233 offset:20480
	ds_read_b128 v[210:213], v233 offset:21504
	ds_read_b128 v[214:217], v233 offset:22528
	ds_read_b128 v[218:221], v233 offset:23552
	global_load_lds_dwordx4 v180, s[56:57]
	s_add_i32 m0, s14, 0x2000
	s_add_u32 s14, s56, 0x40000
	s_addc_u32 s15, s57, 0
	s_add_i32 s33, s85, s66
	global_load_lds_dwordx4 v184, s[56:57]
	s_mov_b32 m0, s33
	s_add_u32 s100, s58, s20
	s_addc_u32 s101, s59, s21
	global_load_lds_dwordx4 v180, s[14:15]
	s_add_i32 m0, s33, 0x2000
	s_nop 0
	global_load_lds_dwordx4 v184, s[14:15]
	s_mov_b32 m0, s67
	s_nop 0
	global_load_lds_dwordx4 v178, s[58:59]
	s_mov_b32 m0, s68
	s_nop 0
	global_load_lds_dwordx4 v182, s[58:59]
	s_waitcnt vmcnt(8)
	s_waitcnt lgkmcnt(0)
	s_barrier
	s_waitcnt lgkmcnt(0)
	v_mfma_f32_16x16x32_bf16 v[90:93], v[38:41], v[174:177], v[90:93]
	v_mfma_f32_16x16x32_bf16 v[86:89], v[54:57], v[174:177], v[86:89]
	v_mfma_f32_16x16x32_bf16 v[74:77], v[38:41], v[198:201], v[74:77]
	v_mfma_f32_16x16x32_bf16 v[70:73], v[54:57], v[198:201], v[70:73]
	v_mfma_f32_16x16x32_bf16 v[50:53], v[38:41], v[206:209], v[50:53]
	v_mfma_f32_16x16x32_bf16 v[46:49], v[54:57], v[206:209], v[46:49]
	v_mfma_f32_16x16x32_bf16 v[26:29], v[38:41], v[214:217], v[26:29]
	v_mfma_f32_16x16x32_bf16 v[22:25], v[54:57], v[214:217], v[22:25]
	v_mfma_f32_16x16x32_bf16 v[90:93], v[42:45], v[194:197], v[90:93]
	v_mfma_f32_16x16x32_bf16 v[86:89], v[58:61], v[194:197], v[86:89]
	v_mfma_f32_16x16x32_bf16 v[74:77], v[42:45], v[202:205], v[74:77]
	v_mfma_f32_16x16x32_bf16 v[70:73], v[58:61], v[202:205], v[70:73]
	v_mfma_f32_16x16x32_bf16 v[50:53], v[42:45], v[210:213], v[50:53]
	v_mfma_f32_16x16x32_bf16 v[46:49], v[58:61], v[210:213], v[46:49]
	v_mfma_f32_16x16x32_bf16 v[26:29], v[42:45], v[218:221], v[26:29]
	v_mfma_f32_16x16x32_bf16 v[22:25], v[58:61], v[218:221], v[22:25]
	v_mfma_f32_16x16x32_bf16 v[34:37], v[126:129], v[206:209], v[34:37]
	v_mfma_f32_16x16x32_bf16 v[30:33], v[166:169], v[206:209], v[30:33]
	v_mfma_f32_16x16x32_bf16 v[18:21], v[126:129], v[214:217], v[18:21]
	v_mfma_f32_16x16x32_bf16 v[12:15], v[166:169], v[214:217], v[14:17]
	v_mfma_f32_16x16x32_bf16 v[38:41], v[126:129], v[174:177], v[82:85]
	v_mfma_f32_16x16x32_bf16 v[42:45], v[166:169], v[174:177], v[78:81]
	v_mfma_f32_16x16x32_bf16 v[54:57], v[126:129], v[198:201], v[66:69]
	v_mfma_f32_16x16x32_bf16 v[58:61], v[166:169], v[198:201], v[62:65]
	v_mfma_f32_16x16x32_bf16 v[34:37], v[146:149], v[210:213], v[34:37]
	v_mfma_f32_16x16x32_bf16 v[30:33], v[170:173], v[210:213], v[30:33]
	v_mfma_f32_16x16x32_bf16 v[18:21], v[146:149], v[218:221], v[18:21]
	v_mfma_f32_16x16x32_bf16 v[12:15], v[170:173], v[218:221], v[12:15]
	v_mfma_f32_16x16x32_bf16 v[38:41], v[146:149], v[194:197], v[38:41]
	v_mfma_f32_16x16x32_bf16 v[42:45], v[170:173], v[194:197], v[42:45]
	v_mfma_f32_16x16x32_bf16 v[54:57], v[146:149], v[202:205], v[54:57]
	v_mfma_f32_16x16x32_bf16 v[58:61], v[170:173], v[202:205], v[58:61]
	s_barrier
	s_add_i32 s33, 0, 0x18000
	v_add_u32_e32 v3, s33, v230
	s_add_i32 s40, 0, 0x1c000
	ds_read_b128 v[62:65], v3
	ds_read_b128 v[66:69], v3 offset:1024
	ds_read_b128 v[78:81], v3 offset:2048
	ds_read_b128 v[82:85], v3 offset:3072
	v_add_u32_e32 v3, s40, v230
	ds_read_b128 v[126:129], v3
	ds_read_b128 v[146:149], v3 offset:1024
	ds_read_b128 v[166:169], v3 offset:2048
	ds_read_b128 v[170:173], v3 offset:3072
	s_add_u32 s14, s58, 0x40000
	s_addc_u32 s15, s59, 0
	s_mov_b32 m0, s69
	ds_read_b128 v[174:177], v233 offset:32768
	ds_read_b128 v[194:197], v233 offset:33792
	ds_read_b128 v[198:201], v233 offset:34816
	ds_read_b128 v[202:205], v233 offset:35840
	ds_read_b128 v[206:209], v233 offset:36864
	ds_read_b128 v[210:213], v233 offset:37888
	ds_read_b128 v[214:217], v233 offset:38912
	ds_read_b128 v[218:221], v233 offset:39936
	global_load_lds_dwordx4 v178, s[14:15]
	s_mov_b32 m0, s70
	s_nop 0
	global_load_lds_dwordx4 v182, s[14:15]
	s_waitcnt vmcnt(8)
	s_waitcnt lgkmcnt(0)
	s_barrier
	s_waitcnt lgkmcnt(0)
	v_mfma_f32_16x16x32_bf16 v[162:165], v[62:65], v[174:177], v[162:165]
	v_mfma_f32_16x16x32_bf16 v[158:161], v[78:81], v[174:177], v[158:161]
	v_mfma_f32_16x16x32_bf16 v[142:145], v[62:65], v[198:201], v[142:145]
	v_mfma_f32_16x16x32_bf16 v[138:141], v[78:81], v[198:201], v[138:141]
	v_mfma_f32_16x16x32_bf16 v[122:125], v[62:65], v[206:209], v[122:125]
	v_mfma_f32_16x16x32_bf16 v[118:121], v[78:81], v[206:209], v[118:121]
	v_mfma_f32_16x16x32_bf16 v[106:109], v[62:65], v[214:217], v[106:109]
	v_mfma_f32_16x16x32_bf16 v[102:105], v[78:81], v[214:217], v[102:105]
	v_mfma_f32_16x16x32_bf16 v[162:165], v[66:69], v[194:197], v[162:165]
	v_mfma_f32_16x16x32_bf16 v[158:161], v[82:85], v[194:197], v[158:161]
	v_mfma_f32_16x16x32_bf16 v[142:145], v[66:69], v[202:205], v[142:145]
	v_mfma_f32_16x16x32_bf16 v[138:141], v[82:85], v[202:205], v[138:141]
	v_mfma_f32_16x16x32_bf16 v[122:125], v[66:69], v[210:213], v[122:125]
	v_mfma_f32_16x16x32_bf16 v[118:121], v[82:85], v[210:213], v[118:121]
	v_mfma_f32_16x16x32_bf16 v[106:109], v[66:69], v[218:221], v[106:109]
	v_mfma_f32_16x16x32_bf16 v[102:105], v[82:85], v[218:221], v[102:105]
	v_mfma_f32_16x16x32_bf16 v[154:157], v[126:129], v[174:177], v[154:157]
	v_mfma_f32_16x16x32_bf16 v[150:153], v[166:169], v[174:177], v[150:153]
	v_mfma_f32_16x16x32_bf16 v[134:137], v[126:129], v[198:201], v[134:137]
	v_mfma_f32_16x16x32_bf16 v[130:133], v[166:169], v[198:201], v[130:133]
	v_mfma_f32_16x16x32_bf16 v[114:117], v[126:129], v[206:209], v[114:117]
	v_mfma_f32_16x16x32_bf16 v[110:113], v[166:169], v[206:209], v[110:113]
	v_mfma_f32_16x16x32_bf16 v[98:101], v[126:129], v[214:217], v[98:101]
	v_mfma_f32_16x16x32_bf16 v[94:97], v[166:169], v[214:217], v[94:97]
	v_mfma_f32_16x16x32_bf16 v[154:157], v[146:149], v[194:197], v[154:157]
	v_mfma_f32_16x16x32_bf16 v[150:153], v[170:173], v[194:197], v[150:153]
	v_mfma_f32_16x16x32_bf16 v[134:137], v[146:149], v[202:205], v[134:137]
	v_mfma_f32_16x16x32_bf16 v[130:133], v[170:173], v[202:205], v[130:133]
	v_mfma_f32_16x16x32_bf16 v[114:117], v[146:149], v[210:213], v[114:117]
	v_mfma_f32_16x16x32_bf16 v[110:113], v[170:173], v[210:213], v[110:113]
	v_mfma_f32_16x16x32_bf16 v[98:101], v[146:149], v[218:221], v[98:101]
	v_mfma_f32_16x16x32_bf16 v[94:97], v[170:173], v[218:221], v[94:97]
	s_barrier
	s_add_i32 s14, s33, s66
	s_mov_b32 m0, s14
	ds_read_b128 v[174:177], v233 offset:49152
	ds_read_b128 v[194:197], v233 offset:50176
	ds_read_b128 v[198:201], v233 offset:51200
	ds_read_b128 v[202:205], v233 offset:52224
	ds_read_b128 v[206:209], v233 offset:53248
	ds_read_b128 v[210:213], v233 offset:54272
	ds_read_b128 v[214:217], v233 offset:55296
	ds_read_b128 v[218:221], v233 offset:56320
	global_load_lds_dwordx4 v180, s[98:99]
	s_add_i32 m0, s14, 0x2000
	s_add_u32 s14, s56, 0x40080
	s_addc_u32 s15, s57, 0
	s_add_i32 s33, s40, s66
	global_load_lds_dwordx4 v184, s[98:99]
	s_mov_b32 m0, s33
	s_nop 0
	global_load_lds_dwordx4 v180, s[14:15]
	s_add_i32 m0, s33, 0x2000
	s_nop 0
	global_load_lds_dwordx4 v184, s[14:15]
	s_mov_b32 m0, s76
	s_nop 0
	global_load_lds_dwordx4 v178, s[100:101]
	s_mov_b32 m0, s77
	s_nop 0
	global_load_lds_dwordx4 v182, s[100:101]
	s_waitcnt vmcnt(8)
	s_waitcnt lgkmcnt(0)
	s_barrier
	s_waitcnt lgkmcnt(0)
	v_mfma_f32_16x16x32_bf16 v[90:93], v[62:65], v[174:177], v[90:93]
	v_mfma_f32_16x16x32_bf16 v[86:89], v[78:81], v[174:177], v[86:89]
	v_mfma_f32_16x16x32_bf16 v[74:77], v[62:65], v[198:201], v[74:77]
	v_mfma_f32_16x16x32_bf16 v[70:73], v[78:81], v[198:201], v[70:73]
	v_mfma_f32_16x16x32_bf16 v[50:53], v[62:65], v[206:209], v[50:53]
	v_mfma_f32_16x16x32_bf16 v[46:49], v[78:81], v[206:209], v[46:49]
	v_mfma_f32_16x16x32_bf16 v[26:29], v[62:65], v[214:217], v[26:29]
	v_mfma_f32_16x16x32_bf16 v[22:25], v[78:81], v[214:217], v[22:25]
	v_mfma_f32_16x16x32_bf16 v[90:93], v[66:69], v[194:197], v[90:93]
	v_mfma_f32_16x16x32_bf16 v[86:89], v[82:85], v[194:197], v[86:89]
	v_mfma_f32_16x16x32_bf16 v[74:77], v[66:69], v[202:205], v[74:77]
	v_mfma_f32_16x16x32_bf16 v[70:73], v[82:85], v[202:205], v[70:73]
	v_mfma_f32_16x16x32_bf16 v[50:53], v[66:69], v[210:213], v[50:53]
	v_mfma_f32_16x16x32_bf16 v[46:49], v[82:85], v[210:213], v[46:49]
	v_mfma_f32_16x16x32_bf16 v[26:29], v[66:69], v[218:221], v[26:29]
	v_mfma_f32_16x16x32_bf16 v[22:25], v[82:85], v[218:221], v[22:25]
	v_mfma_f32_16x16x32_bf16 v[38:41], v[126:129], v[174:177], v[38:41]
	v_mfma_f32_16x16x32_bf16 v[82:85], v[146:149], v[194:197], v[38:41]
	v_mfma_f32_16x16x32_bf16 v[38:41], v[166:169], v[174:177], v[42:45]
	v_mfma_f32_16x16x32_bf16 v[78:81], v[170:173], v[194:197], v[38:41]
	v_mfma_f32_16x16x32_bf16 v[38:41], v[126:129], v[198:201], v[54:57]
	v_mfma_f32_16x16x32_bf16 v[66:69], v[146:149], v[202:205], v[38:41]
	v_mfma_f32_16x16x32_bf16 v[38:41], v[166:169], v[198:201], v[58:61]
	v_mfma_f32_16x16x32_bf16 v[34:37], v[126:129], v[206:209], v[34:37]
	v_mfma_f32_16x16x32_bf16 v[30:33], v[166:169], v[206:209], v[30:33]
	v_mfma_f32_16x16x32_bf16 v[16:19], v[126:129], v[214:217], v[18:21]
	v_mfma_f32_16x16x32_bf16 v[12:15], v[166:169], v[214:217], v[12:15]
	v_mfma_f32_16x16x32_bf16 v[62:65], v[170:173], v[202:205], v[38:41]
	v_mfma_f32_16x16x32_bf16 v[34:37], v[146:149], v[210:213], v[34:37]
	v_mfma_f32_16x16x32_bf16 v[30:33], v[170:173], v[210:213], v[30:33]
	v_mfma_f32_16x16x32_bf16 v[18:21], v[146:149], v[218:221], v[16:19]
	v_mfma_f32_16x16x32_bf16 v[14:17], v[170:173], v[218:221], v[12:15]
	s_barrier
	s_add_i32 s13, s13, 2
	s_add_u32 s10, s10, 0x100
	s_addc_u32 s11, s11, 0
	s_add_u32 s9, s9, 0x100
	s_addc_u32 s12, s12, 0
	s_cmp_gt_u32 s13, 13
	s_cbranch_scc0 .LBB0_774
	s_and_b64 vcc, exec, s[22:23]
	s_cbranch_vccz .LBB0_777
	s_barrier

.LBB0_1038:
	ds_read_b128 v[26:29], v214
	ds_read_b128 v[30:33], v214 offset:1024
	ds_read_b128 v[34:37], v214 offset:2048
	ds_read_b128 v[38:41], v214 offset:3072
	ds_read_b128 v[122:125], v215
	ds_read_b128 v[142:145], v215 offset:1024
	ds_read_b128 v[162:165], v215 offset:2048
	ds_read_b128 v[166:169], v215 offset:3072
	s_add_i32 s33, s31, 2
	s_add_u32 s40, s6, 0xfffd0080
	s_addc_u32 s41, s7, -1
	s_cmp_eq_u32 s13, s31
	s_cselect_b32 s55, s47, s41
	s_cselect_b32 s54, s46, s40
	s_cselect_b32 s53, s1, s15
	s_cselect_b32 s52, s2, s14
	s_add_i32 m0, s66, 0xc000
	ds_read_b128 v[170:173], v216
	ds_read_b128 v[174:177], v216 offset:1024
	ds_read_b128 v[178:181], v216 offset:2048
	ds_read_b128 v[198:201], v216 offset:3072
	ds_read_b128 v[202:205], v216 offset:4096
	ds_read_b128 v[206:209], v216 offset:5120
	ds_read_b128 v[220:223], v216 offset:6144
	ds_read_b128 v[228:231], v216 offset:7168
	global_load_lds_dwordx4 v190, s[6:7]
	s_add_i32 m0, s66, 0xe000
	s_nop 0
	global_load_lds_dwordx4 v192, s[6:7]
	s_waitcnt vmcnt(8)
	s_waitcnt lgkmcnt(0)
	s_barrier
	s_waitcnt lgkmcnt(0)
	v_mfma_f32_16x16x32_bf16 v[158:161], v[26:29], v[170:173], v[158:161]
	v_mfma_f32_16x16x32_bf16 v[154:157], v[34:37], v[170:173], v[154:157]
	v_mfma_f32_16x16x32_bf16 v[138:141], v[26:29], v[178:181], v[138:141]
	v_mfma_f32_16x16x32_bf16 v[134:137], v[34:37], v[178:181], v[134:137]
	v_mfma_f32_16x16x32_bf16 v[118:121], v[26:29], v[202:205], v[118:121]
	v_mfma_f32_16x16x32_bf16 v[114:117], v[34:37], v[202:205], v[114:117]
	v_mfma_f32_16x16x32_bf16 v[102:105], v[26:29], v[220:223], v[102:105]
	v_mfma_f32_16x16x32_bf16 v[98:101], v[34:37], v[220:223], v[98:101]
	v_mfma_f32_16x16x32_bf16 v[158:161], v[30:33], v[174:177], v[158:161]
	v_mfma_f32_16x16x32_bf16 v[154:157], v[38:41], v[174:177], v[154:157]
	v_mfma_f32_16x16x32_bf16 v[138:141], v[30:33], v[198:201], v[138:141]
	v_mfma_f32_16x16x32_bf16 v[134:137], v[38:41], v[198:201], v[134:137]
	v_mfma_f32_16x16x32_bf16 v[118:121], v[30:33], v[206:209], v[118:121]
	v_mfma_f32_16x16x32_bf16 v[114:117], v[38:41], v[206:209], v[114:117]
	v_mfma_f32_16x16x32_bf16 v[102:105], v[30:33], v[228:231], v[102:105]
	v_mfma_f32_16x16x32_bf16 v[98:101], v[38:41], v[228:231], v[98:101]
	v_mfma_f32_16x16x32_bf16 v[150:153], v[122:125], v[170:173], v[150:153]
	v_mfma_f32_16x16x32_bf16 v[146:149], v[162:165], v[170:173], v[146:149]
	v_mfma_f32_16x16x32_bf16 v[130:133], v[122:125], v[178:181], v[130:133]
	v_mfma_f32_16x16x32_bf16 v[126:129], v[162:165], v[178:181], v[126:129]
	v_mfma_f32_16x16x32_bf16 v[110:113], v[122:125], v[202:205], v[110:113]
	v_mfma_f32_16x16x32_bf16 v[106:109], v[162:165], v[202:205], v[106:109]
	v_mfma_f32_16x16x32_bf16 v[94:97], v[122:125], v[220:223], v[94:97]
	v_mfma_f32_16x16x32_bf16 v[90:93], v[162:165], v[220:223], v[90:93]
	v_mfma_f32_16x16x32_bf16 v[150:153], v[142:145], v[174:177], v[150:153]
	v_mfma_f32_16x16x32_bf16 v[146:149], v[166:169], v[174:177], v[146:149]
	v_mfma_f32_16x16x32_bf16 v[130:133], v[142:145], v[198:201], v[130:133]
	v_mfma_f32_16x16x32_bf16 v[126:129], v[166:169], v[198:201], v[126:129]
	v_mfma_f32_16x16x32_bf16 v[110:113], v[142:145], v[206:209], v[110:113]
	v_mfma_f32_16x16x32_bf16 v[106:109], v[166:169], v[206:209], v[106:109]
	v_mfma_f32_16x16x32_bf16 v[94:97], v[142:145], v[228:231], v[94:97]
	v_mfma_f32_16x16x32_bf16 v[90:93], v[166:169], v[228:231], v[90:93]
	s_barrier
	s_add_i32 s31, s85, s64
	s_add_u32 s98, s52, s18
	s_addc_u32 s99, s53, s19
	s_mov_b32 m0, s31
	ds_read_b128 v[170:173], v216 offset:16384
	ds_read_b128 v[174:177], v216 offset:17408
	ds_read_b128 v[178:181], v216 offset:18432
	ds_read_b128 v[198:201], v216 offset:19456
	ds_read_b128 v[202:205], v216 offset:20480
	ds_read_b128 v[206:209], v216 offset:21504
	ds_read_b128 v[220:223], v216 offset:22528
	ds_read_b128 v[228:231], v216 offset:23552
	global_load_lds_dwordx4 v184, s[52:53]
	s_add_i32 m0, s31, 0x2000
	s_add_u32 s40, s52, 0x10000
	s_addc_u32 s41, s53, 0
	s_add_i32 s31, s86, s64
	global_load_lds_dwordx4 v188, s[52:53]
	s_mov_b32 m0, s31
	s_add_u32 s100, s54, s18
	s_addc_u32 s101, s55, s19
	global_load_lds_dwordx4 v184, s[40:41]
	s_add_i32 m0, s31, 0x2000
	s_nop 0
	global_load_lds_dwordx4 v188, s[40:41]
	s_mov_b32 m0, s66
	s_nop 0
	global_load_lds_dwordx4 v182, s[54:55]
	s_mov_b32 m0, s67
	s_nop 0
	global_load_lds_dwordx4 v186, s[54:55]
	s_waitcnt vmcnt(8)
	s_waitcnt lgkmcnt(0)
	s_barrier
	s_waitcnt lgkmcnt(0)
	v_mfma_f32_16x16x32_bf16 v[86:89], v[26:29], v[170:173], v[86:89]
	v_mfma_f32_16x16x32_bf16 v[82:85], v[34:37], v[170:173], v[82:85]
	v_mfma_f32_16x16x32_bf16 v[70:73], v[26:29], v[178:181], v[70:73]
	v_mfma_f32_16x16x32_bf16 v[66:69], v[34:37], v[178:181], v[66:69]
	v_mfma_f32_16x16x32_bf16 v[54:57], v[26:29], v[202:205], v[54:57]
	v_mfma_f32_16x16x32_bf16 v[50:53], v[34:37], v[202:205], v[50:53]
	v_mfma_f32_16x16x32_bf16 v[22:25], v[26:29], v[220:223], v[22:25]
	v_mfma_f32_16x16x32_bf16 v[18:21], v[34:37], v[220:223], v[18:21]
	v_mfma_f32_16x16x32_bf16 v[86:89], v[30:33], v[174:177], v[86:89]
	v_mfma_f32_16x16x32_bf16 v[82:85], v[38:41], v[174:177], v[82:85]
	v_mfma_f32_16x16x32_bf16 v[70:73], v[30:33], v[198:201], v[70:73]
	v_mfma_f32_16x16x32_bf16 v[66:69], v[38:41], v[198:201], v[66:69]
	v_mfma_f32_16x16x32_bf16 v[54:57], v[30:33], v[206:209], v[54:57]
	v_mfma_f32_16x16x32_bf16 v[50:53], v[38:41], v[206:209], v[50:53]
	v_mfma_f32_16x16x32_bf16 v[22:25], v[30:33], v[228:231], v[22:25]
	v_mfma_f32_16x16x32_bf16 v[18:21], v[38:41], v[228:231], v[18:21]
	v_mfma_f32_16x16x32_bf16 v[46:49], v[122:125], v[202:205], v[46:49]
	v_mfma_f32_16x16x32_bf16 v[42:45], v[162:165], v[202:205], v[42:45]
	v_mfma_f32_16x16x32_bf16 v[14:17], v[122:125], v[220:223], v[14:17]
	v_mfma_f32_16x16x32_bf16 v[8:11], v[162:165], v[220:223], v[10:13]
	v_mfma_f32_16x16x32_bf16 v[26:29], v[122:125], v[170:173], v[78:81]
	v_mfma_f32_16x16x32_bf16 v[30:33], v[162:165], v[170:173], v[74:77]
	v_mfma_f32_16x16x32_bf16 v[34:37], v[122:125], v[178:181], v[62:65]
	v_mfma_f32_16x16x32_bf16 v[38:41], v[162:165], v[178:181], v[58:61]
	v_mfma_f32_16x16x32_bf16 v[46:49], v[142:145], v[206:209], v[46:49]
	v_mfma_f32_16x16x32_bf16 v[42:45], v[166:169], v[206:209], v[42:45]
	v_mfma_f32_16x16x32_bf16 v[14:17], v[142:145], v[228:231], v[14:17]
	v_mfma_f32_16x16x32_bf16 v[8:11], v[166:169], v[228:231], v[8:11]
	v_mfma_f32_16x16x32_bf16 v[26:29], v[142:145], v[174:177], v[26:29]
	v_mfma_f32_16x16x32_bf16 v[30:33], v[166:169], v[174:177], v[30:33]
	v_mfma_f32_16x16x32_bf16 v[34:37], v[142:145], v[198:201], v[34:37]
	v_mfma_f32_16x16x32_bf16 v[38:41], v[166:169], v[198:201], v[38:41]
	s_barrier
	s_add_i32 s31, 0, 0x18000
	v_add_u32_e32 v3, s31, v213
	s_add_i32 s42, 0, 0x1c000
	ds_read_b128 v[58:61], v3
	ds_read_b128 v[62:65], v3 offset:1024
	ds_read_b128 v[74:77], v3 offset:2048
	ds_read_b128 v[78:81], v3 offset:3072
	v_add_u32_e32 v3, s42, v213
	ds_read_b128 v[122:125], v3
	ds_read_b128 v[142:145], v3 offset:1024
	ds_read_b128 v[162:165], v3 offset:2048
	ds_read_b128 v[166:169], v3 offset:3072
	s_add_u32 s40, s54, 0x30000
	s_addc_u32 s41, s55, 0
	s_mov_b32 m0, s68
	ds_read_b128 v[170:173], v216 offset:32768
	ds_read_b128 v[174:177], v216 offset:33792
	ds_read_b128 v[178:181], v216 offset:34816
	ds_read_b128 v[198:201], v216 offset:35840
	ds_read_b128 v[202:205], v216 offset:36864
	ds_read_b128 v[206:209], v216 offset:37888
	ds_read_b128 v[220:223], v216 offset:38912
	ds_read_b128 v[228:231], v216 offset:39936
	global_load_lds_dwordx4 v182, s[40:41]
	s_mov_b32 m0, s69
	s_nop 0
	global_load_lds_dwordx4 v186, s[40:41]
	s_waitcnt vmcnt(8)
	s_waitcnt lgkmcnt(0)
	s_barrier
	s_waitcnt lgkmcnt(0)
	v_mfma_f32_16x16x32_bf16 v[158:161], v[58:61], v[170:173], v[158:161]
	v_mfma_f32_16x16x32_bf16 v[154:157], v[74:77], v[170:173], v[154:157]
	v_mfma_f32_16x16x32_bf16 v[138:141], v[58:61], v[178:181], v[138:141]
	v_mfma_f32_16x16x32_bf16 v[134:137], v[74:77], v[178:181], v[134:137]
	v_mfma_f32_16x16x32_bf16 v[118:121], v[58:61], v[202:205], v[118:121]
	v_mfma_f32_16x16x32_bf16 v[114:117], v[74:77], v[202:205], v[114:117]
	v_mfma_f32_16x16x32_bf16 v[102:105], v[58:61], v[220:223], v[102:105]
	v_mfma_f32_16x16x32_bf16 v[98:101], v[74:77], v[220:223], v[98:101]
	v_mfma_f32_16x16x32_bf16 v[158:161], v[62:65], v[174:177], v[158:161]
	v_mfma_f32_16x16x32_bf16 v[154:157], v[78:81], v[174:177], v[154:157]
	v_mfma_f32_16x16x32_bf16 v[138:141], v[62:65], v[198:201], v[138:141]
	v_mfma_f32_16x16x32_bf16 v[134:137], v[78:81], v[198:201], v[134:137]
	v_mfma_f32_16x16x32_bf16 v[118:121], v[62:65], v[206:209], v[118:121]
	v_mfma_f32_16x16x32_bf16 v[114:117], v[78:81], v[206:209], v[114:117]
	v_mfma_f32_16x16x32_bf16 v[102:105], v[62:65], v[228:231], v[102:105]
	v_mfma_f32_16x16x32_bf16 v[98:101], v[78:81], v[228:231], v[98:101]
	v_mfma_f32_16x16x32_bf16 v[150:153], v[122:125], v[170:173], v[150:153]
	v_mfma_f32_16x16x32_bf16 v[146:149], v[162:165], v[170:173], v[146:149]
	v_mfma_f32_16x16x32_bf16 v[130:133], v[122:125], v[178:181], v[130:133]
	v_mfma_f32_16x16x32_bf16 v[126:129], v[162:165], v[178:181], v[126:129]
	v_mfma_f32_16x16x32_bf16 v[110:113], v[122:125], v[202:205], v[110:113]
	v_mfma_f32_16x16x32_bf16 v[106:109], v[162:165], v[202:205], v[106:109]
	v_mfma_f32_16x16x32_bf16 v[94:97], v[122:125], v[220:223], v[94:97]
	v_mfma_f32_16x16x32_bf16 v[90:93], v[162:165], v[220:223], v[90:93]
	v_mfma_f32_16x16x32_bf16 v[150:153], v[142:145], v[174:177], v[150:153]
	v_mfma_f32_16x16x32_bf16 v[146:149], v[166:169], v[174:177], v[146:149]
	v_mfma_f32_16x16x32_bf16 v[130:133], v[142:145], v[198:201], v[130:133]
	v_mfma_f32_16x16x32_bf16 v[126:129], v[166:169], v[198:201], v[126:129]
	v_mfma_f32_16x16x32_bf16 v[110:113], v[142:145], v[206:209], v[110:113]
	v_mfma_f32_16x16x32_bf16 v[106:109], v[166:169], v[206:209], v[106:109]
	v_mfma_f32_16x16x32_bf16 v[94:97], v[142:145], v[228:231], v[94:97]
	v_mfma_f32_16x16x32_bf16 v[90:93], v[166:169], v[228:231], v[90:93]
	s_barrier
	s_add_i32 s31, s31, s64
	s_mov_b32 m0, s31
	ds_read_b128 v[170:173], v216 offset:49152
	ds_read_b128 v[174:177], v216 offset:50176
	ds_read_b128 v[178:181], v216 offset:51200
	ds_read_b128 v[198:201], v216 offset:52224
	ds_read_b128 v[202:205], v216 offset:53248
	ds_read_b128 v[206:209], v216 offset:54272
	ds_read_b128 v[220:223], v216 offset:55296
	ds_read_b128 v[228:231], v216 offset:56320
	global_load_lds_dwordx4 v184, s[98:99]
	s_add_i32 m0, s31, 0x2000
	s_add_u32 s40, s52, 0x10080
	s_addc_u32 s41, s53, 0
	s_add_i32 s31, s42, s64
	global_load_lds_dwordx4 v188, s[98:99]
	s_mov_b32 m0, s31
	s_nop 0
	global_load_lds_dwordx4 v184, s[40:41]
	s_add_i32 m0, s31, 0x2000
	s_nop 0
	global_load_lds_dwordx4 v188, s[40:41]
	s_mov_b32 m0, s76
	s_nop 0
	global_load_lds_dwordx4 v182, s[100:101]
	s_mov_b32 m0, s77
	s_nop 0
	global_load_lds_dwordx4 v186, s[100:101]
	s_waitcnt vmcnt(8)
	s_waitcnt lgkmcnt(0)
	s_barrier
	s_waitcnt lgkmcnt(0)
	v_mfma_f32_16x16x32_bf16 v[86:89], v[58:61], v[170:173], v[86:89]
	v_mfma_f32_16x16x32_bf16 v[82:85], v[74:77], v[170:173], v[82:85]
	v_mfma_f32_16x16x32_bf16 v[70:73], v[58:61], v[178:181], v[70:73]
	v_mfma_f32_16x16x32_bf16 v[66:69], v[74:77], v[178:181], v[66:69]
	v_mfma_f32_16x16x32_bf16 v[54:57], v[58:61], v[202:205], v[54:57]
	v_mfma_f32_16x16x32_bf16 v[50:53], v[74:77], v[202:205], v[50:53]
	v_mfma_f32_16x16x32_bf16 v[22:25], v[58:61], v[220:223], v[22:25]
	v_mfma_f32_16x16x32_bf16 v[18:21], v[74:77], v[220:223], v[18:21]
	v_mfma_f32_16x16x32_bf16 v[86:89], v[62:65], v[174:177], v[86:89]
	v_mfma_f32_16x16x32_bf16 v[82:85], v[78:81], v[174:177], v[82:85]
	v_mfma_f32_16x16x32_bf16 v[70:73], v[62:65], v[198:201], v[70:73]
	v_mfma_f32_16x16x32_bf16 v[66:69], v[78:81], v[198:201], v[66:69]
	v_mfma_f32_16x16x32_bf16 v[54:57], v[62:65], v[206:209], v[54:57]
	v_mfma_f32_16x16x32_bf16 v[50:53], v[78:81], v[206:209], v[50:53]
	v_mfma_f32_16x16x32_bf16 v[22:25], v[62:65], v[228:231], v[22:25]
	v_mfma_f32_16x16x32_bf16 v[18:21], v[78:81], v[228:231], v[18:21]
	v_mfma_f32_16x16x32_bf16 v[26:29], v[122:125], v[170:173], v[26:29]
	v_mfma_f32_16x16x32_bf16 v[78:81], v[142:145], v[174:177], v[26:29]
	v_mfma_f32_16x16x32_bf16 v[26:29], v[162:165], v[170:173], v[30:33]
	v_mfma_f32_16x16x32_bf16 v[74:77], v[166:169], v[174:177], v[26:29]
	v_mfma_f32_16x16x32_bf16 v[26:29], v[122:125], v[178:181], v[34:37]
	v_mfma_f32_16x16x32_bf16 v[62:65], v[142:145], v[198:201], v[26:29]
	v_mfma_f32_16x16x32_bf16 v[26:29], v[162:165], v[178:181], v[38:41]
	v_mfma_f32_16x16x32_bf16 v[58:61], v[166:169], v[198:201], v[26:29]
	v_mfma_f32_16x16x32_bf16 v[26:29], v[122:125], v[202:205], v[46:49]
	v_mfma_f32_16x16x32_bf16 v[46:49], v[142:145], v[206:209], v[26:29]
	v_mfma_f32_16x16x32_bf16 v[26:29], v[162:165], v[202:205], v[42:45]
	v_mfma_f32_16x16x32_bf16 v[12:15], v[122:125], v[220:223], v[14:17]
	v_mfma_f32_16x16x32_bf16 v[8:11], v[162:165], v[220:223], v[8:11]
	v_mfma_f32_16x16x32_bf16 v[42:45], v[166:169], v[206:209], v[26:29]
	v_mfma_f32_16x16x32_bf16 v[14:17], v[142:145], v[228:231], v[12:15]
	v_mfma_f32_16x16x32_bf16 v[10:13], v[166:169], v[228:231], v[8:11]
	s_barrier
	s_add_u32 s6, s6, 0x100
	s_addc_u32 s7, s7, 0
	s_add_u32 s14, s14, 0x100
	s_addc_u32 s15, s15, 0
	s_cmp_ge_u32 s33, s12
	s_mov_b32 s31, s33
	s_cbranch_scc0 .LBB0_1038
	s_and_b64 vcc, exec, s[20:21]
	s_cbranch_vccz .LBB0_1041
	s_barrier

.LBB0_1523:
	ds_read_b128 v[2:5], v148
	ds_read_b128 v[6:9], v148 offset:1024
	ds_read_b128 v[10:13], v148 offset:2048
	ds_read_b128 v[14:17], v148 offset:3072
	ds_read_b128 v[18:21], v149
	ds_read_b128 v[22:25], v149 offset:1024
	ds_read_b128 v[26:29], v149 offset:2048
	ds_read_b128 v[30:33], v149 offset:3072
	s_ashr_i32 s47, s46, 31
	s_lshl_b64 s[50:51], s[46:47], 17
	s_add_u32 s50, s1, s50
	s_addc_u32 s51, s12, s51
	s_and_b64 s[6:7], s[6:7], exec
	s_cselect_b32 s7, s51, s59
	s_cselect_b32 s6, s50, s58
	s_add_u32 s64, s56, 0x10080
	s_addc_u32 s65, s57, 0
	s_add_i32 s62, s14, 0xc000
	v_lshl_add_u64 v[66:67], s[64:65], 0, v[130:131]
	s_mov_b32 m0, s62
	s_add_i32 s2, s14, 0xe000
	ds_read_b128 v[34:37], v150
	ds_read_b128 v[38:41], v150 offset:1024
	ds_read_b128 v[42:45], v150 offset:2048
	ds_read_b128 v[46:49], v150 offset:3072
	ds_read_b128 v[50:53], v150 offset:4096
	ds_read_b128 v[54:57], v150 offset:5120
	ds_read_b128 v[58:61], v150 offset:6144
	ds_read_b128 v[62:65], v150 offset:7168
	global_load_lds_dwordx4 v[66:67], off
	v_lshl_add_u64 v[66:67], s[64:65], 0, v[134:135]
	s_mov_b32 m0, s2
	s_nop 0
	global_load_lds_dwordx4 v[66:67], off
	s_waitcnt vmcnt(8)
	s_waitcnt lgkmcnt(0)
	s_barrier
	s_waitcnt lgkmcnt(0)
	v_mfma_f32_16x16x32_bf16 v[66:69], v[2:5], v[34:37], 0
	v_mfma_f32_16x16x32_bf16 v[70:73], v[10:13], v[34:37], 0
	v_mfma_f32_16x16x32_bf16 v[74:77], v[2:5], v[42:45], 0
	v_mfma_f32_16x16x32_bf16 v[78:81], v[10:13], v[42:45], 0
	v_mfma_f32_16x16x32_bf16 v[82:85], v[2:5], v[50:53], 0
	v_mfma_f32_16x16x32_bf16 v[86:89], v[10:13], v[50:53], 0
	v_mfma_f32_16x16x32_bf16 v[90:93], v[2:5], v[58:61], 0
	v_mfma_f32_16x16x32_bf16 v[94:97], v[10:13], v[58:61], 0
	v_mfma_f32_16x16x32_bf16 v[66:69], v[6:9], v[38:41], v[66:69]
	v_mfma_f32_16x16x32_bf16 v[70:73], v[14:17], v[38:41], v[70:73]
	v_mfma_f32_16x16x32_bf16 v[74:77], v[6:9], v[46:49], v[74:77]
	v_mfma_f32_16x16x32_bf16 v[78:81], v[14:17], v[46:49], v[78:81]
	v_mfma_f32_16x16x32_bf16 v[82:85], v[6:9], v[54:57], v[82:85]
	v_mfma_f32_16x16x32_bf16 v[86:89], v[14:17], v[54:57], v[86:89]
	v_mfma_f32_16x16x32_bf16 v[90:93], v[6:9], v[62:65], v[90:93]
	v_mfma_f32_16x16x32_bf16 v[94:97], v[14:17], v[62:65], v[94:97]
	v_mfma_f32_16x16x32_bf16 v[98:101], v[18:21], v[34:37], 0
	v_mfma_f32_16x16x32_bf16 v[34:37], v[26:29], v[34:37], 0
	v_mfma_f32_16x16x32_bf16 v[98:101], v[22:25], v[38:41], v[98:101]
	v_mfma_f32_16x16x32_bf16 v[34:37], v[30:33], v[38:41], v[34:37]
	v_mfma_f32_16x16x32_bf16 v[38:41], v[18:21], v[42:45], 0
	v_mfma_f32_16x16x32_bf16 v[42:45], v[26:29], v[42:45], 0
	v_mfma_f32_16x16x32_bf16 v[38:41], v[22:25], v[46:49], v[38:41]
	v_mfma_f32_16x16x32_bf16 v[42:45], v[30:33], v[46:49], v[42:45]
	v_mfma_f32_16x16x32_bf16 v[46:49], v[18:21], v[50:53], 0
	v_mfma_f32_16x16x32_bf16 v[50:53], v[26:29], v[50:53], 0
	v_mfma_f32_16x16x32_bf16 v[46:49], v[22:25], v[54:57], v[46:49]
	v_mfma_f32_16x16x32_bf16 v[50:53], v[30:33], v[54:57], v[50:53]
	v_mfma_f32_16x16x32_bf16 v[54:57], v[18:21], v[58:61], 0
	v_mfma_f32_16x16x32_bf16 v[58:61], v[26:29], v[58:61], 0
	v_mfma_f32_16x16x32_bf16 v[54:57], v[22:25], v[62:65], v[54:57]
	v_mfma_f32_16x16x32_bf16 v[58:61], v[30:33], v[62:65], v[58:61]
	s_barrier
	s_add_i32 s55, s45, s13
	v_lshl_add_u64 v[212:213], s[58:59], 0, v[132:133]
	s_add_i32 s31, s55, 0x2000
	v_lshl_add_u64 v[142:143], v[212:213], 0, s[26:27]
	s_mov_b32 m0, s55
	v_lshl_add_u64 v[214:215], s[58:59], 0, v[136:137]
	s_add_u32 s64, s58, 0x10100
	ds_read_b128 v[62:65], v150 offset:16384
	ds_read_b128 v[102:105], v150 offset:17408
	ds_read_b128 v[106:109], v150 offset:18432
	ds_read_b128 v[110:113], v150 offset:19456
	ds_read_b128 v[114:117], v150 offset:20480
	ds_read_b128 v[118:121], v150 offset:21504
	ds_read_b128 v[122:125], v150 offset:22528
	ds_read_b128 v[126:129], v150 offset:23552
	global_load_lds_dwordx4 v[142:143], off
	v_lshl_add_u64 v[142:143], v[214:215], 0, s[26:27]
	s_mov_b32 m0, s31
	s_addc_u32 s65, s59, 0
	s_add_i32 s47, s60, s13
	global_load_lds_dwordx4 v[142:143], off
	v_lshl_add_u64 v[142:143], s[64:65], 0, v[132:133]
	s_mov_b32 m0, s47
	s_add_i32 s53, s47, 0x2000
	global_load_lds_dwordx4 v[142:143], off
	v_lshl_add_u64 v[142:143], s[64:65], 0, v[136:137]
	s_mov_b32 m0, s53
	v_lshl_add_u64 v[216:217], s[56:57], 0, v[130:131]
	global_load_lds_dwordx4 v[142:143], off
	v_lshl_add_u64 v[142:143], v[216:217], 0, s[26:27]
	s_mov_b32 m0, s14
	v_lshl_add_u64 v[218:219], s[56:57], 0, v[134:135]
	global_load_lds_dwordx4 v[142:143], off
	v_lshl_add_u64 v[142:143], v[218:219], 0, s[26:27]
	s_mov_b32 m0, s15
	s_nop 0
	global_load_lds_dwordx4 v[142:143], off
	s_waitcnt vmcnt(8)
	s_waitcnt lgkmcnt(0)
	s_barrier
	s_waitcnt lgkmcnt(0)
	v_mfma_f32_16x16x32_bf16 v[142:145], v[2:5], v[62:65], 0
	v_mfma_f32_16x16x32_bf16 v[156:159], v[2:5], v[106:109], 0
	v_mfma_f32_16x16x32_bf16 v[164:167], v[2:5], v[114:117], 0
	v_mfma_f32_16x16x32_bf16 v[2:5], v[2:5], v[122:125], 0
	v_mfma_f32_16x16x32_bf16 v[142:145], v[6:9], v[102:105], v[142:145]
	v_mfma_f32_16x16x32_bf16 v[156:159], v[6:9], v[110:113], v[156:159]
	v_mfma_f32_16x16x32_bf16 v[164:167], v[6:9], v[118:121], v[164:167]
	v_mfma_f32_16x16x32_bf16 v[2:5], v[6:9], v[126:129], v[2:5]
	v_mfma_f32_16x16x32_bf16 v[6:9], v[10:13], v[122:125], 0
	v_mfma_f32_16x16x32_bf16 v[152:155], v[10:13], v[62:65], 0
	v_mfma_f32_16x16x32_bf16 v[160:163], v[10:13], v[106:109], 0
	v_mfma_f32_16x16x32_bf16 v[168:171], v[10:13], v[114:117], 0
	v_mfma_f32_16x16x32_bf16 v[6:9], v[14:17], v[126:129], v[6:9]
	v_mfma_f32_16x16x32_bf16 v[152:155], v[14:17], v[102:105], v[152:155]
	v_mfma_f32_16x16x32_bf16 v[160:163], v[14:17], v[110:113], v[160:163]
	v_mfma_f32_16x16x32_bf16 v[168:171], v[14:17], v[118:121], v[168:171]
	v_mfma_f32_16x16x32_bf16 v[10:13], v[18:21], v[62:65], 0
	v_mfma_f32_16x16x32_bf16 v[14:17], v[26:29], v[62:65], 0
	v_mfma_f32_16x16x32_bf16 v[10:13], v[22:25], v[102:105], v[10:13]
	v_mfma_f32_16x16x32_bf16 v[14:17], v[30:33], v[102:105], v[14:17]
	v_mfma_f32_16x16x32_bf16 v[62:65], v[18:21], v[106:109], 0
	v_mfma_f32_16x16x32_bf16 v[102:105], v[26:29], v[106:109], 0
	v_mfma_f32_16x16x32_bf16 v[106:109], v[18:21], v[114:117], 0
	v_mfma_f32_16x16x32_bf16 v[18:21], v[18:21], v[122:125], 0
	v_mfma_f32_16x16x32_bf16 v[62:65], v[22:25], v[110:113], v[62:65]
	v_mfma_f32_16x16x32_bf16 v[102:105], v[30:33], v[110:113], v[102:105]
	v_mfma_f32_16x16x32_bf16 v[106:109], v[22:25], v[118:121], v[106:109]
	v_mfma_f32_16x16x32_bf16 v[110:113], v[26:29], v[114:117], 0
	v_mfma_f32_16x16x32_bf16 v[18:21], v[22:25], v[126:129], v[18:21]
	v_mfma_f32_16x16x32_bf16 v[22:25], v[26:29], v[122:125], 0
	v_mfma_f32_16x16x32_bf16 v[110:113], v[30:33], v[118:121], v[110:113]
	v_mfma_f32_16x16x32_bf16 v[22:25], v[30:33], v[126:129], v[22:25]
	s_barrier
	s_add_i32 s63, 0, 0x18000
	s_add_i32 s66, 0, 0x1c000
	v_add_u32_e32 v151, s63, v147
	v_add_u32_e32 v222, s66, v147
	ds_read_b128 v[26:29], v151
	ds_read_b128 v[30:33], v151 offset:1024
	ds_read_b128 v[114:117], v151 offset:2048
	ds_read_b128 v[118:121], v151 offset:3072
	ds_read_b128 v[122:125], v222
	ds_read_b128 v[126:129], v222 offset:1024
	ds_read_b128 v[172:175], v222 offset:2048
	ds_read_b128 v[176:179], v222 offset:3072
	s_add_u32 s64, s56, 0x10100
	s_addc_u32 s65, s57, 0
	s_mov_b32 m0, s33
	v_lshl_add_u64 v[220:221], s[64:65], 0, v[130:131]
	ds_read_b128 v[180:183], v150 offset:32768
	ds_read_b128 v[184:187], v150 offset:33792
	ds_read_b128 v[188:191], v150 offset:34816
	ds_read_b128 v[192:195], v150 offset:35840
	ds_read_b128 v[196:199], v150 offset:36864
	ds_read_b128 v[200:203], v150 offset:37888
	ds_read_b128 v[204:207], v150 offset:38912
	ds_read_b128 v[208:211], v150 offset:39936
	global_load_lds_dwordx4 v[220:221], off
	v_lshl_add_u64 v[220:221], s[64:65], 0, v[134:135]
	s_mov_b32 m0, s40
	s_nop 0
	global_load_lds_dwordx4 v[220:221], off
	s_waitcnt vmcnt(8)
	s_waitcnt lgkmcnt(0)
	s_barrier
	s_waitcnt lgkmcnt(0)
	v_mfma_f32_16x16x32_bf16 v[66:69], v[26:29], v[180:183], v[66:69]
	v_mfma_f32_16x16x32_bf16 v[70:73], v[114:117], v[180:183], v[70:73]
	v_mfma_f32_16x16x32_bf16 v[74:77], v[26:29], v[188:191], v[74:77]
	v_mfma_f32_16x16x32_bf16 v[78:81], v[114:117], v[188:191], v[78:81]
	v_mfma_f32_16x16x32_bf16 v[82:85], v[26:29], v[196:199], v[82:85]
	v_mfma_f32_16x16x32_bf16 v[86:89], v[114:117], v[196:199], v[86:89]
	v_mfma_f32_16x16x32_bf16 v[90:93], v[26:29], v[204:207], v[90:93]
	v_mfma_f32_16x16x32_bf16 v[94:97], v[114:117], v[204:207], v[94:97]
	v_mfma_f32_16x16x32_bf16 v[66:69], v[30:33], v[184:187], v[66:69]
	v_mfma_f32_16x16x32_bf16 v[70:73], v[118:121], v[184:187], v[70:73]
	v_mfma_f32_16x16x32_bf16 v[74:77], v[30:33], v[192:195], v[74:77]
	v_mfma_f32_16x16x32_bf16 v[78:81], v[118:121], v[192:195], v[78:81]
	v_mfma_f32_16x16x32_bf16 v[82:85], v[30:33], v[200:203], v[82:85]
	v_mfma_f32_16x16x32_bf16 v[86:89], v[118:121], v[200:203], v[86:89]
	v_mfma_f32_16x16x32_bf16 v[90:93], v[30:33], v[208:211], v[90:93]
	v_mfma_f32_16x16x32_bf16 v[94:97], v[118:121], v[208:211], v[94:97]
	v_mfma_f32_16x16x32_bf16 v[98:101], v[122:125], v[180:183], v[98:101]
	v_mfma_f32_16x16x32_bf16 v[34:37], v[172:175], v[180:183], v[34:37]
	v_mfma_f32_16x16x32_bf16 v[38:41], v[122:125], v[188:191], v[38:41]
	v_mfma_f32_16x16x32_bf16 v[42:45], v[172:175], v[188:191], v[42:45]
	v_mfma_f32_16x16x32_bf16 v[46:49], v[122:125], v[196:199], v[46:49]
	v_mfma_f32_16x16x32_bf16 v[50:53], v[172:175], v[196:199], v[50:53]
	v_mfma_f32_16x16x32_bf16 v[54:57], v[122:125], v[204:207], v[54:57]
	v_mfma_f32_16x16x32_bf16 v[58:61], v[172:175], v[204:207], v[58:61]
	v_mfma_f32_16x16x32_bf16 v[98:101], v[126:129], v[184:187], v[98:101]
	v_mfma_f32_16x16x32_bf16 v[34:37], v[176:179], v[184:187], v[34:37]
	v_mfma_f32_16x16x32_bf16 v[38:41], v[126:129], v[192:195], v[38:41]
	v_mfma_f32_16x16x32_bf16 v[42:45], v[176:179], v[192:195], v[42:45]
	v_mfma_f32_16x16x32_bf16 v[46:49], v[126:129], v[200:203], v[46:49]
	v_mfma_f32_16x16x32_bf16 v[50:53], v[176:179], v[200:203], v[50:53]
	v_mfma_f32_16x16x32_bf16 v[54:57], v[126:129], v[208:211], v[54:57]
	v_mfma_f32_16x16x32_bf16 v[58:61], v[176:179], v[208:211], v[58:61]
	s_barrier
	s_add_i32 s63, s63, s13
	s_add_i32 s61, s63, 0x2000
	v_lshl_add_u64 v[212:213], v[212:213], 0, s[28:29]
	s_mov_b32 m0, s63
	s_add_u32 s64, s58, 0x10180
	ds_read_b128 v[180:183], v150 offset:49152
	ds_read_b128 v[184:187], v150 offset:50176
	ds_read_b128 v[188:191], v150 offset:51200
	ds_read_b128 v[192:195], v150 offset:52224
	ds_read_b128 v[196:199], v150 offset:53248
	ds_read_b128 v[200:203], v150 offset:54272
	ds_read_b128 v[204:207], v150 offset:55296
	ds_read_b128 v[208:211], v150 offset:56320
	global_load_lds_dwordx4 v[212:213], off
	v_lshl_add_u64 v[212:213], v[214:215], 0, s[28:29]
	s_mov_b32 m0, s61
	s_addc_u32 s65, s59, 0
	s_add_i32 s58, s66, s13
	global_load_lds_dwordx4 v[212:213], off
	v_lshl_add_u64 v[212:213], s[64:65], 0, v[132:133]
	s_mov_b32 m0, s58
	s_add_i32 s59, s58, 0x2000
	global_load_lds_dwordx4 v[212:213], off
	v_lshl_add_u64 v[212:213], s[64:65], 0, v[136:137]
	s_mov_b32 m0, s59
	s_nop 0
	global_load_lds_dwordx4 v[212:213], off
	v_lshl_add_u64 v[212:213], v[216:217], 0, s[28:29]
	s_mov_b32 m0, s43
	s_nop 0
	global_load_lds_dwordx4 v[212:213], off
	v_lshl_add_u64 v[212:213], v[218:219], 0, s[28:29]
	s_mov_b32 m0, s44
	s_nop 0
	global_load_lds_dwordx4 v[212:213], off
	s_waitcnt vmcnt(8)
	s_waitcnt lgkmcnt(0)
	s_barrier
	s_waitcnt lgkmcnt(0)
	v_mfma_f32_16x16x32_bf16 v[2:5], v[26:29], v[204:207], v[2:5]
	v_mfma_f32_16x16x32_bf16 v[6:9], v[114:117], v[204:207], v[6:9]
	v_mfma_f32_16x16x32_bf16 v[142:145], v[26:29], v[180:183], v[142:145]
	v_mfma_f32_16x16x32_bf16 v[152:155], v[114:117], v[180:183], v[152:155]
	v_mfma_f32_16x16x32_bf16 v[156:159], v[26:29], v[188:191], v[156:159]
	v_mfma_f32_16x16x32_bf16 v[160:163], v[114:117], v[188:191], v[160:163]
	v_mfma_f32_16x16x32_bf16 v[164:167], v[26:29], v[196:199], v[164:167]
	v_mfma_f32_16x16x32_bf16 v[168:171], v[114:117], v[196:199], v[168:171]
	v_mfma_f32_16x16x32_bf16 v[2:5], v[30:33], v[208:211], v[2:5]
	v_mfma_f32_16x16x32_bf16 v[6:9], v[118:121], v[208:211], v[6:9]
	v_mfma_f32_16x16x32_bf16 v[142:145], v[30:33], v[184:187], v[142:145]
	v_mfma_f32_16x16x32_bf16 v[152:155], v[118:121], v[184:187], v[152:155]
	v_mfma_f32_16x16x32_bf16 v[156:159], v[30:33], v[192:195], v[156:159]
	v_mfma_f32_16x16x32_bf16 v[160:163], v[118:121], v[192:195], v[160:163]
	v_mfma_f32_16x16x32_bf16 v[164:167], v[30:33], v[200:203], v[164:167]
	v_mfma_f32_16x16x32_bf16 v[168:171], v[118:121], v[200:203], v[168:171]
	v_mfma_f32_16x16x32_bf16 v[10:13], v[122:125], v[180:183], v[10:13]
	v_mfma_f32_16x16x32_bf16 v[14:17], v[172:175], v[180:183], v[14:17]
	v_mfma_f32_16x16x32_bf16 v[26:29], v[122:125], v[188:191], v[62:65]
	v_mfma_f32_16x16x32_bf16 v[30:33], v[172:175], v[188:191], v[102:105]
	v_mfma_f32_16x16x32_bf16 v[62:65], v[122:125], v[196:199], v[106:109]
	v_mfma_f32_16x16x32_bf16 v[102:105], v[172:175], v[196:199], v[110:113]
	v_mfma_f32_16x16x32_bf16 v[18:21], v[122:125], v[204:207], v[18:21]
	v_mfma_f32_16x16x32_bf16 v[22:25], v[172:175], v[204:207], v[22:25]
	v_mfma_f32_16x16x32_bf16 v[10:13], v[126:129], v[184:187], v[10:13]
	v_mfma_f32_16x16x32_bf16 v[14:17], v[176:179], v[184:187], v[14:17]
	v_mfma_f32_16x16x32_bf16 v[26:29], v[126:129], v[192:195], v[26:29]
	v_mfma_f32_16x16x32_bf16 v[30:33], v[176:179], v[192:195], v[30:33]
	v_mfma_f32_16x16x32_bf16 v[62:65], v[126:129], v[200:203], v[62:65]
	v_mfma_f32_16x16x32_bf16 v[102:105], v[176:179], v[200:203], v[102:105]
	v_mfma_f32_16x16x32_bf16 v[18:21], v[126:129], v[208:211], v[18:21]
	v_mfma_f32_16x16x32_bf16 v[22:25], v[176:179], v[208:211], v[22:25]
	s_barrier
	ds_read_b128 v[106:109], v148
	ds_read_b128 v[110:113], v148 offset:1024
	ds_read_b128 v[114:117], v148 offset:2048
	ds_read_b128 v[118:121], v148 offset:3072
	ds_read_b128 v[122:125], v149
	ds_read_b128 v[126:129], v149 offset:1024
	ds_read_b128 v[172:175], v149 offset:2048
	ds_read_b128 v[176:179], v149 offset:3072
	s_add_u32 s56, s56, 0x10180
	s_addc_u32 s57, s57, 0
	s_mov_b32 m0, s62
	v_lshl_add_u64 v[212:213], s[56:57], 0, v[130:131]
	ds_read_b128 v[180:183], v150
	ds_read_b128 v[184:187], v150 offset:1024
	ds_read_b128 v[188:191], v150 offset:2048
	ds_read_b128 v[192:195], v150 offset:3072
	ds_read_b128 v[196:199], v150 offset:4096
	ds_read_b128 v[200:203], v150 offset:5120
	ds_read_b128 v[204:207], v150 offset:6144
	ds_read_b128 v[208:211], v150 offset:7168
	global_load_lds_dwordx4 v[212:213], off
	v_lshl_add_u64 v[212:213], s[56:57], 0, v[134:135]
	s_mov_b32 m0, s2
	s_nop 0
	global_load_lds_dwordx4 v[212:213], off
	s_waitcnt vmcnt(8)
	s_waitcnt lgkmcnt(0)
	s_barrier
	s_waitcnt lgkmcnt(0)
	v_mfma_f32_16x16x32_bf16 v[90:93], v[106:109], v[204:207], v[90:93]
	v_mfma_f32_16x16x32_bf16 v[66:69], v[106:109], v[180:183], v[66:69]
	v_mfma_f32_16x16x32_bf16 v[70:73], v[114:117], v[180:183], v[70:73]
	v_mfma_f32_16x16x32_bf16 v[74:77], v[106:109], v[188:191], v[74:77]
	v_mfma_f32_16x16x32_bf16 v[78:81], v[114:117], v[188:191], v[78:81]
	v_mfma_f32_16x16x32_bf16 v[82:85], v[106:109], v[196:199], v[82:85]
	v_mfma_f32_16x16x32_bf16 v[86:89], v[114:117], v[196:199], v[86:89]
	v_mfma_f32_16x16x32_bf16 v[212:215], v[110:113], v[208:211], v[90:93]
	v_mfma_f32_16x16x32_bf16 v[90:93], v[114:117], v[204:207], v[94:97]
	v_mfma_f32_16x16x32_bf16 v[66:69], v[110:113], v[184:187], v[66:69]
	v_mfma_f32_16x16x32_bf16 v[70:73], v[118:121], v[184:187], v[70:73]
	v_mfma_f32_16x16x32_bf16 v[74:77], v[110:113], v[192:195], v[74:77]
	v_mfma_f32_16x16x32_bf16 v[78:81], v[118:121], v[192:195], v[78:81]
	v_mfma_f32_16x16x32_bf16 v[82:85], v[110:113], v[200:203], v[82:85]
	v_mfma_f32_16x16x32_bf16 v[86:89], v[118:121], v[200:203], v[86:89]
	v_mfma_f32_16x16x32_bf16 v[94:97], v[118:121], v[208:211], v[90:93]
	v_mfma_f32_16x16x32_bf16 v[34:37], v[172:175], v[180:183], v[34:37]
	v_mfma_f32_16x16x32_bf16 v[38:41], v[122:125], v[188:191], v[38:41]
	v_mfma_f32_16x16x32_bf16 v[42:45], v[172:175], v[188:191], v[42:45]
	v_mfma_f32_16x16x32_bf16 v[46:49], v[122:125], v[196:199], v[46:49]
	v_mfma_f32_16x16x32_bf16 v[50:53], v[172:175], v[196:199], v[50:53]
	v_mfma_f32_16x16x32_bf16 v[54:57], v[122:125], v[204:207], v[54:57]
	v_mfma_f32_16x16x32_bf16 v[58:61], v[172:175], v[204:207], v[58:61]
	v_mfma_f32_16x16x32_bf16 v[90:93], v[122:125], v[180:183], v[98:101]
	v_mfma_f32_16x16x32_bf16 v[34:37], v[176:179], v[184:187], v[34:37]
	v_mfma_f32_16x16x32_bf16 v[38:41], v[126:129], v[192:195], v[38:41]
	v_mfma_f32_16x16x32_bf16 v[42:45], v[176:179], v[192:195], v[42:45]
	v_mfma_f32_16x16x32_bf16 v[46:49], v[126:129], v[200:203], v[46:49]
	v_mfma_f32_16x16x32_bf16 v[50:53], v[176:179], v[200:203], v[50:53]
	v_mfma_f32_16x16x32_bf16 v[54:57], v[126:129], v[208:211], v[54:57]
	v_mfma_f32_16x16x32_bf16 v[58:61], v[176:179], v[208:211], v[58:61]
	v_mfma_f32_16x16x32_bf16 v[216:219], v[126:129], v[184:187], v[90:93]
	s_barrier
	s_mov_b32 m0, s55
	v_lshl_add_u64 v[224:225], s[6:7], 0, v[132:133]
	s_add_u32 s56, s6, 0x10000
	ds_read_b128 v[90:93], v150 offset:16384
	ds_read_b128 v[98:101], v150 offset:17408
	ds_read_b128 v[180:183], v150 offset:18432
	ds_read_b128 v[184:187], v150 offset:19456
	ds_read_b128 v[188:191], v150 offset:20480
	ds_read_b128 v[192:195], v150 offset:21504
	ds_read_b128 v[196:199], v150 offset:22528
	ds_read_b128 v[200:203], v150 offset:23552
	global_load_lds_dwordx4 v[224:225], off
	v_lshl_add_u64 v[226:227], s[6:7], 0, v[136:137]
	s_mov_b32 m0, s31
	s_addc_u32 s57, s7, 0
	global_load_lds_dwordx4 v[226:227], off
	v_lshl_add_u64 v[204:205], s[56:57], 0, v[132:133]
	s_mov_b32 m0, s47
	v_lshl_add_u64 v[248:249], s[48:49], 0, v[130:131]
	global_load_lds_dwordx4 v[204:205], off
	v_lshl_add_u64 v[204:205], s[56:57], 0, v[136:137]
	s_mov_b32 m0, s53
	v_lshl_add_u64 v[250:251], s[48:49], 0, v[134:135]
	global_load_lds_dwordx4 v[204:205], off
	s_mov_b32 m0, s14
	s_nop 0
	global_load_lds_dwordx4 v[248:249], off
	s_mov_b32 m0, s15
	s_nop 0
	global_load_lds_dwordx4 v[250:251], off
	s_waitcnt vmcnt(8)
	s_waitcnt lgkmcnt(0)
	s_barrier
	s_waitcnt lgkmcnt(0)
	v_mfma_f32_16x16x32_bf16 v[2:5], v[106:109], v[196:199], v[2:5]
	v_mfma_f32_16x16x32_bf16 v[6:9], v[114:117], v[196:199], v[6:9]
	v_mfma_f32_16x16x32_bf16 v[142:145], v[106:109], v[90:93], v[142:145]
	v_mfma_f32_16x16x32_bf16 v[152:155], v[114:117], v[90:93], v[152:155]
	v_mfma_f32_16x16x32_bf16 v[156:159], v[106:109], v[180:183], v[156:159]
	v_mfma_f32_16x16x32_bf16 v[160:163], v[114:117], v[180:183], v[160:163]
	v_mfma_f32_16x16x32_bf16 v[164:167], v[106:109], v[188:191], v[164:167]
	v_mfma_f32_16x16x32_bf16 v[168:171], v[114:117], v[188:191], v[168:171]
	v_mfma_f32_16x16x32_bf16 v[2:5], v[110:113], v[200:203], v[2:5]
	v_mfma_f32_16x16x32_bf16 v[6:9], v[118:121], v[200:203], v[6:9]
	v_mfma_f32_16x16x32_bf16 v[142:145], v[110:113], v[98:101], v[142:145]
	v_mfma_f32_16x16x32_bf16 v[152:155], v[118:121], v[98:101], v[152:155]
	v_mfma_f32_16x16x32_bf16 v[156:159], v[110:113], v[184:187], v[156:159]
	v_mfma_f32_16x16x32_bf16 v[160:163], v[118:121], v[184:187], v[160:163]
	v_mfma_f32_16x16x32_bf16 v[164:167], v[110:113], v[192:195], v[164:167]
	v_mfma_f32_16x16x32_bf16 v[168:171], v[118:121], v[192:195], v[168:171]
	v_mfma_f32_16x16x32_bf16 v[10:13], v[122:125], v[90:93], v[10:13]
	v_mfma_f32_16x16x32_bf16 v[204:207], v[126:129], v[98:101], v[10:13]
	v_mfma_f32_16x16x32_bf16 v[10:13], v[172:175], v[90:93], v[14:17]
	v_mfma_f32_16x16x32_bf16 v[14:17], v[176:179], v[98:101], v[10:13]
	v_mfma_f32_16x16x32_bf16 v[10:13], v[122:125], v[180:183], v[26:29]
	v_mfma_f32_16x16x32_bf16 v[208:211], v[126:129], v[184:187], v[10:13]
	v_mfma_f32_16x16x32_bf16 v[10:13], v[172:175], v[180:183], v[30:33]
	v_mfma_f32_16x16x32_bf16 v[30:33], v[176:179], v[184:187], v[10:13]
	v_mfma_f32_16x16x32_bf16 v[10:13], v[122:125], v[188:191], v[62:65]
	v_mfma_f32_16x16x32_bf16 v[180:183], v[126:129], v[192:195], v[10:13]
	v_mfma_f32_16x16x32_bf16 v[10:13], v[172:175], v[188:191], v[102:105]
	v_mfma_f32_16x16x32_bf16 v[184:187], v[176:179], v[192:195], v[10:13]
	v_mfma_f32_16x16x32_bf16 v[10:13], v[122:125], v[196:199], v[18:21]
	v_mfma_f32_16x16x32_bf16 v[188:191], v[126:129], v[200:203], v[10:13]
	v_mfma_f32_16x16x32_bf16 v[10:13], v[172:175], v[196:199], v[22:25]
	v_mfma_f32_16x16x32_bf16 v[172:175], v[176:179], v[200:203], v[10:13]
	s_barrier
	s_nop 4
	ds_read_b128 v[10:13], v151
	ds_read_b128 v[22:25], v151 offset:1024
	ds_read_b128 v[62:65], v151 offset:2048
	ds_read_b128 v[176:179], v151 offset:3072
	ds_read_b128 v[192:195], v222
	ds_read_b128 v[196:199], v222 offset:1024
	ds_read_b128 v[200:203], v222 offset:2048
	ds_read_b128 v[220:223], v222 offset:3072
	s_add_u32 s56, s48, 0x10000
	s_addc_u32 s57, s49, 0
	s_mov_b32 m0, s33
	v_lshl_add_u64 v[90:91], s[56:57], 0, v[130:131]
	ds_read_b128 v[18:21], v150 offset:32768
	ds_read_b128 v[26:29], v150 offset:33792
	ds_read_b128 v[102:105], v150 offset:34816
	ds_read_b128 v[228:231], v150 offset:35840
	ds_read_b128 v[232:235], v150 offset:36864
	ds_read_b128 v[236:239], v150 offset:37888
	ds_read_b128 v[240:243], v150 offset:38912
	ds_read_b128 v[244:247], v150 offset:39936
	global_load_lds_dwordx4 v[90:91], off
	v_lshl_add_u64 v[90:91], s[56:57], 0, v[134:135]
	s_mov_b32 m0, s40
	s_nop 0
	global_load_lds_dwordx4 v[90:91], off
	s_waitcnt vmcnt(8)
	s_waitcnt lgkmcnt(0)
	s_barrier
	s_waitcnt lgkmcnt(0)
	v_mfma_f32_16x16x32_bf16 v[66:69], v[10:13], v[18:21], v[66:69]
	v_mfma_f32_16x16x32_bf16 v[122:125], v[22:25], v[26:29], v[66:69]
	v_mfma_f32_16x16x32_bf16 v[66:69], v[62:65], v[18:21], v[70:73]
	v_mfma_f32_16x16x32_bf16 v[114:117], v[176:179], v[26:29], v[66:69]
	v_mfma_f32_16x16x32_bf16 v[66:69], v[10:13], v[102:105], v[74:77]
	v_mfma_f32_16x16x32_bf16 v[106:109], v[22:25], v[228:231], v[66:69]
	v_mfma_f32_16x16x32_bf16 v[66:69], v[62:65], v[102:105], v[78:81]
	v_mfma_f32_16x16x32_bf16 v[98:101], v[176:179], v[228:231], v[66:69]
	v_mfma_f32_16x16x32_bf16 v[66:69], v[10:13], v[232:235], v[82:85]
	v_mfma_f32_16x16x32_bf16 v[90:93], v[22:25], v[236:239], v[66:69]
	v_mfma_f32_16x16x32_bf16 v[66:69], v[62:65], v[232:235], v[86:89]
	v_mfma_f32_16x16x32_bf16 v[82:85], v[176:179], v[236:239], v[66:69]
	v_mfma_f32_16x16x32_bf16 v[66:69], v[10:13], v[240:243], v[212:215]
	v_mfma_f32_16x16x32_bf16 v[74:77], v[22:25], v[244:247], v[66:69]
	v_mfma_f32_16x16x32_bf16 v[66:69], v[62:65], v[240:243], v[94:97]
	v_mfma_f32_16x16x32_bf16 v[66:69], v[176:179], v[244:247], v[66:69]
	v_mfma_f32_16x16x32_bf16 v[70:73], v[192:195], v[18:21], v[216:219]
	v_mfma_f32_16x16x32_bf16 v[18:21], v[200:203], v[18:21], v[34:37]
	v_mfma_f32_16x16x32_bf16 v[118:121], v[220:223], v[26:29], v[18:21]
	v_mfma_f32_16x16x32_bf16 v[18:21], v[192:195], v[102:105], v[38:41]
	v_mfma_f32_16x16x32_bf16 v[110:113], v[196:199], v[228:231], v[18:21]
	v_mfma_f32_16x16x32_bf16 v[18:21], v[200:203], v[102:105], v[42:45]
	v_mfma_f32_16x16x32_bf16 v[102:105], v[220:223], v[228:231], v[18:21]
	v_mfma_f32_16x16x32_bf16 v[18:21], v[192:195], v[232:235], v[46:49]
	v_mfma_f32_16x16x32_bf16 v[94:97], v[196:199], v[236:239], v[18:21]
	v_mfma_f32_16x16x32_bf16 v[18:21], v[200:203], v[232:235], v[50:53]
	v_mfma_f32_16x16x32_bf16 v[86:89], v[220:223], v[236:239], v[18:21]
	v_mfma_f32_16x16x32_bf16 v[18:21], v[192:195], v[240:243], v[54:57]
	v_mfma_f32_16x16x32_bf16 v[78:81], v[196:199], v[244:247], v[18:21]
	v_mfma_f32_16x16x32_bf16 v[18:21], v[200:203], v[240:243], v[58:61]
	v_mfma_f32_16x16x32_bf16 v[126:129], v[196:199], v[26:29], v[70:73]
	v_mfma_f32_16x16x32_bf16 v[70:73], v[220:223], v[244:247], v[18:21]
	s_barrier
	s_mov_b32 m0, s63
	s_nop 2
	v_lshl_add_u64 v[18:19], v[224:225], 0, s[20:21]
	s_add_u32 s6, s6, 0x10080
	ds_read_b128 v[38:41], v150 offset:49152
	ds_read_b128 v[46:49], v150 offset:50176
	ds_read_b128 v[212:215], v150 offset:51200
	ds_read_b128 v[216:219], v150 offset:52224
	ds_read_b128 v[228:231], v150 offset:53248
	ds_read_b128 v[232:235], v150 offset:54272
	ds_read_b128 v[236:239], v150 offset:55296
	ds_read_b128 v[240:243], v150 offset:56320
	global_load_lds_dwordx4 v[18:19], off
	v_lshl_add_u64 v[18:19], v[226:227], 0, s[20:21]
	s_mov_b32 m0, s61
	s_addc_u32 s7, s7, 0
	global_load_lds_dwordx4 v[18:19], off
	v_lshl_add_u64 v[18:19], s[6:7], 0, v[132:133]
	s_mov_b32 m0, s58
	s_nop 0
	global_load_lds_dwordx4 v[18:19], off
	v_lshl_add_u64 v[18:19], s[6:7], 0, v[136:137]
	s_mov_b32 m0, s59
	s_nop 0
	global_load_lds_dwordx4 v[18:19], off
	v_lshl_add_u64 v[18:19], v[248:249], 0, s[20:21]
	s_mov_b32 m0, s43
	s_nop 0
	global_load_lds_dwordx4 v[18:19], off
	v_lshl_add_u64 v[18:19], v[250:251], 0, s[20:21]
	s_mov_b32 m0, s44
	s_nop 0
	global_load_lds_dwordx4 v[18:19], off
	s_waitcnt vmcnt(8)
	s_waitcnt lgkmcnt(0)
	s_barrier
	s_waitcnt lgkmcnt(0)
	v_mfma_f32_16x16x32_bf16 v[18:21], v[10:13], v[38:41], v[142:145]
	v_mfma_f32_16x16x32_bf16 v[58:61], v[22:25], v[46:49], v[18:21]
	v_mfma_f32_16x16x32_bf16 v[18:21], v[62:65], v[38:41], v[152:155]
	v_mfma_f32_16x16x32_bf16 v[50:53], v[176:179], v[46:49], v[18:21]
	v_mfma_f32_16x16x32_bf16 v[18:21], v[10:13], v[212:215], v[156:159]
	v_mfma_f32_16x16x32_bf16 v[42:45], v[22:25], v[216:219], v[18:21]
	v_mfma_f32_16x16x32_bf16 v[18:21], v[62:65], v[212:215], v[160:163]
	v_mfma_f32_16x16x32_bf16 v[34:37], v[176:179], v[216:219], v[18:21]
	v_mfma_f32_16x16x32_bf16 v[18:21], v[10:13], v[228:231], v[164:167]
	v_mfma_f32_16x16x32_bf16 v[2:5], v[10:13], v[236:239], v[2:5]
	v_mfma_f32_16x16x32_bf16 v[26:29], v[22:25], v[232:235], v[18:21]
	v_mfma_f32_16x16x32_bf16 v[18:21], v[62:65], v[228:231], v[168:171]
	v_mfma_f32_16x16x32_bf16 v[10:13], v[22:25], v[240:243], v[2:5]
	v_mfma_f32_16x16x32_bf16 v[2:5], v[62:65], v[236:239], v[6:9]
	v_mfma_f32_16x16x32_bf16 v[18:21], v[176:179], v[232:235], v[18:21]
	v_mfma_f32_16x16x32_bf16 v[2:5], v[176:179], v[240:243], v[2:5]
	v_mfma_f32_16x16x32_bf16 v[6:9], v[192:195], v[38:41], v[204:207]
	v_mfma_f32_16x16x32_bf16 v[62:65], v[196:199], v[46:49], v[6:9]
	v_mfma_f32_16x16x32_bf16 v[6:9], v[200:203], v[38:41], v[14:17]
	v_mfma_f32_16x16x32_bf16 v[54:57], v[220:223], v[46:49], v[6:9]
	v_mfma_f32_16x16x32_bf16 v[6:9], v[192:195], v[212:215], v[208:211]
	v_mfma_f32_16x16x32_bf16 v[46:49], v[196:199], v[216:219], v[6:9]
	v_mfma_f32_16x16x32_bf16 v[6:9], v[200:203], v[212:215], v[30:33]
	v_mfma_f32_16x16x32_bf16 v[38:41], v[220:223], v[216:219], v[6:9]
	v_mfma_f32_16x16x32_bf16 v[6:9], v[192:195], v[228:231], v[180:183]
	v_mfma_f32_16x16x32_bf16 v[30:33], v[196:199], v[232:235], v[6:9]
	v_mfma_f32_16x16x32_bf16 v[6:9], v[200:203], v[228:231], v[184:187]
	v_mfma_f32_16x16x32_bf16 v[22:25], v[220:223], v[232:235], v[6:9]
	v_mfma_f32_16x16x32_bf16 v[6:9], v[192:195], v[236:239], v[188:191]
	v_mfma_f32_16x16x32_bf16 v[14:17], v[196:199], v[240:243], v[6:9]
	v_mfma_f32_16x16x32_bf16 v[6:9], v[200:203], v[236:239], v[172:175]
	v_mfma_f32_16x16x32_bf16 v[6:9], v[220:223], v[240:243], v[6:9]
	s_barrier
	s_andn2_b64 vcc, exec, s[22:23]
	s_cbranch_vccnz .LBB0_1525
	s_barrier

.LBB0_1631:
	v_add_u32_e32 v153, s44, v151
	ds_read_b128 v[154:157], v153
	ds_read_b128 v[158:161], v153 offset:1024
	ds_read_b128 v[162:165], v153 offset:2048
	ds_read_b128 v[166:169], v153 offset:3072
	v_add_u32_e32 v153, s45, v151
	s_add_u32 s46, s18, s30
	ds_read_b128 v[170:173], v153
	ds_read_b128 v[174:177], v153 offset:1024
	ds_read_b128 v[178:181], v153 offset:2048
	ds_read_b128 v[182:185], v153 offset:3072
	s_addc_u32 s47, s19, s31
	s_add_u32 s46, s46, 0x100
	s_addc_u32 s47, s47, 0
	s_add_u32 s55, s50, s30
	s_addc_u32 s56, s51, s31
	s_cmpk_eq_i32 s30, 0x700
	s_cselect_b32 s49, s25, s47
	s_cselect_b32 s48, s52, s46
	s_cselect_b32 s47, s23, s56
	s_cselect_b32 s46, s53, s55
	v_lshl_add_u64 v[218:219], v[146:147], 0, s[30:31]
	s_add_i32 m0, s33, 0xc000
	ds_read_b128 v[186:189], v152
	ds_read_b128 v[190:193], v152 offset:1024
	ds_read_b128 v[194:197], v152 offset:2048
	ds_read_b128 v[198:201], v152 offset:3072
	ds_read_b128 v[202:205], v152 offset:4096
	ds_read_b128 v[206:209], v152 offset:5120
	ds_read_b128 v[210:213], v152 offset:6144
	ds_read_b128 v[214:217], v152 offset:7168
	global_load_lds_dwordx4 v[218:219], off
	v_lshl_add_u64 v[218:219], v[148:149], 0, s[30:31]
	s_add_i32 m0, s33, 0xe000
	s_nop 0
	global_load_lds_dwordx4 v[218:219], off
	s_waitcnt vmcnt(8)
	s_waitcnt lgkmcnt(0)
	s_barrier
	s_waitcnt lgkmcnt(0)
	v_mfma_f32_16x16x32_bf16 v[126:129], v[154:157], v[186:189], v[126:129]
	v_mfma_f32_16x16x32_bf16 v[122:125], v[162:165], v[186:189], v[122:125]
	v_mfma_f32_16x16x32_bf16 v[110:113], v[154:157], v[194:197], v[110:113]
	v_mfma_f32_16x16x32_bf16 v[106:109], v[162:165], v[194:197], v[106:109]
	v_mfma_f32_16x16x32_bf16 v[94:97], v[154:157], v[202:205], v[94:97]
	v_mfma_f32_16x16x32_bf16 v[90:93], v[162:165], v[202:205], v[90:93]
	v_mfma_f32_16x16x32_bf16 v[78:81], v[154:157], v[210:213], v[78:81]
	v_mfma_f32_16x16x32_bf16 v[74:77], v[162:165], v[210:213], v[74:77]
	v_mfma_f32_16x16x32_bf16 v[126:129], v[158:161], v[190:193], v[126:129]
	v_mfma_f32_16x16x32_bf16 v[122:125], v[166:169], v[190:193], v[122:125]
	v_mfma_f32_16x16x32_bf16 v[110:113], v[158:161], v[198:201], v[110:113]
	v_mfma_f32_16x16x32_bf16 v[106:109], v[166:169], v[198:201], v[106:109]
	v_mfma_f32_16x16x32_bf16 v[94:97], v[158:161], v[206:209], v[94:97]
	v_mfma_f32_16x16x32_bf16 v[90:93], v[166:169], v[206:209], v[90:93]
	v_mfma_f32_16x16x32_bf16 v[78:81], v[158:161], v[214:217], v[78:81]
	v_mfma_f32_16x16x32_bf16 v[74:77], v[166:169], v[214:217], v[74:77]
	v_mfma_f32_16x16x32_bf16 v[118:121], v[170:173], v[186:189], v[118:121]
	v_mfma_f32_16x16x32_bf16 v[114:117], v[178:181], v[186:189], v[114:117]
	v_mfma_f32_16x16x32_bf16 v[102:105], v[170:173], v[194:197], v[102:105]
	v_mfma_f32_16x16x32_bf16 v[98:101], v[178:181], v[194:197], v[98:101]
	v_mfma_f32_16x16x32_bf16 v[86:89], v[170:173], v[202:205], v[86:89]
	v_mfma_f32_16x16x32_bf16 v[82:85], v[178:181], v[202:205], v[82:85]
	v_mfma_f32_16x16x32_bf16 v[70:73], v[170:173], v[210:213], v[70:73]
	v_mfma_f32_16x16x32_bf16 v[66:69], v[178:181], v[210:213], v[66:69]
	v_mfma_f32_16x16x32_bf16 v[118:121], v[174:177], v[190:193], v[118:121]
	v_mfma_f32_16x16x32_bf16 v[114:117], v[182:185], v[190:193], v[114:117]
	v_mfma_f32_16x16x32_bf16 v[102:105], v[174:177], v[198:201], v[102:105]
	v_mfma_f32_16x16x32_bf16 v[98:101], v[182:185], v[198:201], v[98:101]
	v_mfma_f32_16x16x32_bf16 v[86:89], v[174:177], v[206:209], v[86:89]
	v_mfma_f32_16x16x32_bf16 v[82:85], v[182:185], v[206:209], v[82:85]
	v_mfma_f32_16x16x32_bf16 v[70:73], v[174:177], v[214:217], v[70:73]
	v_mfma_f32_16x16x32_bf16 v[66:69], v[182:185], v[214:217], v[66:69]
	s_barrier
	s_add_i32 s55, s44, s13
	s_add_u32 s98, s46, s20
	s_addc_u32 s99, s47, s21
	s_mov_b32 m0, s55
	ds_read_b128 v[186:189], v152 offset:16384
	ds_read_b128 v[190:193], v152 offset:17408
	ds_read_b128 v[194:197], v152 offset:18432
	ds_read_b128 v[198:201], v152 offset:19456
	ds_read_b128 v[202:205], v152 offset:20480
	ds_read_b128 v[206:209], v152 offset:21504
	ds_read_b128 v[210:213], v152 offset:22528
	ds_read_b128 v[214:217], v152 offset:23552
	global_load_lds_dwordx4 v132, s[46:47]
	s_add_i32 m0, s55, 0x2000
	s_add_u32 s56, s46, 0x40000
	s_addc_u32 s57, s47, 0
	s_add_i32 s55, s45, s13
	global_load_lds_dwordx4 v136, s[46:47]
	s_mov_b32 m0, s55
	s_nop 0
	global_load_lds_dwordx4 v132, s[56:57]
	s_add_i32 m0, s55, 0x2000
	s_nop 0
	global_load_lds_dwordx4 v136, s[56:57]
	s_add_u32 s100, s48, s20
	s_addc_u32 s101, s49, s21
	s_mov_b32 m0, s33
	s_nop 0
	global_load_lds_dwordx4 v130, s[48:49]
	s_mov_b32 m0, s14
	s_nop 0
	global_load_lds_dwordx4 v134, s[48:49]
	s_waitcnt vmcnt(8)
	s_waitcnt lgkmcnt(0)
	s_barrier
	s_waitcnt lgkmcnt(0)
	v_mfma_f32_16x16x32_bf16 v[62:65], v[154:157], v[186:189], v[62:65]
	v_mfma_f32_16x16x32_bf16 v[58:61], v[162:165], v[186:189], v[58:61]
	v_mfma_f32_16x16x32_bf16 v[46:49], v[154:157], v[194:197], v[46:49]
	v_mfma_f32_16x16x32_bf16 v[42:45], v[162:165], v[194:197], v[42:45]
	v_mfma_f32_16x16x32_bf16 v[30:33], v[154:157], v[202:205], v[30:33]
	v_mfma_f32_16x16x32_bf16 v[26:29], v[162:165], v[202:205], v[26:29]
	v_mfma_f32_16x16x32_bf16 v[14:17], v[154:157], v[210:213], v[14:17]
	v_mfma_f32_16x16x32_bf16 v[10:13], v[162:165], v[210:213], v[10:13]
	v_mfma_f32_16x16x32_bf16 v[62:65], v[158:161], v[190:193], v[62:65]
	v_mfma_f32_16x16x32_bf16 v[58:61], v[166:169], v[190:193], v[58:61]
	v_mfma_f32_16x16x32_bf16 v[46:49], v[158:161], v[198:201], v[46:49]
	v_mfma_f32_16x16x32_bf16 v[42:45], v[166:169], v[198:201], v[42:45]
	v_mfma_f32_16x16x32_bf16 v[30:33], v[158:161], v[206:209], v[30:33]
	v_mfma_f32_16x16x32_bf16 v[26:29], v[166:169], v[206:209], v[26:29]
	v_mfma_f32_16x16x32_bf16 v[14:17], v[158:161], v[214:217], v[14:17]
	v_mfma_f32_16x16x32_bf16 v[10:13], v[166:169], v[214:217], v[10:13]
	v_mfma_f32_16x16x32_bf16 v[54:57], v[170:173], v[186:189], v[54:57]
	v_mfma_f32_16x16x32_bf16 v[50:53], v[178:181], v[186:189], v[50:53]
	v_mfma_f32_16x16x32_bf16 v[38:41], v[170:173], v[194:197], v[38:41]
	v_mfma_f32_16x16x32_bf16 v[34:37], v[178:181], v[194:197], v[34:37]
	v_mfma_f32_16x16x32_bf16 v[22:25], v[170:173], v[202:205], v[22:25]
	v_mfma_f32_16x16x32_bf16 v[18:21], v[178:181], v[202:205], v[18:21]
	v_mfma_f32_16x16x32_bf16 v[6:9], v[170:173], v[210:213], v[6:9]
	v_mfma_f32_16x16x32_bf16 v[2:5], v[178:181], v[210:213], v[2:5]
	v_mfma_f32_16x16x32_bf16 v[54:57], v[174:177], v[190:193], v[54:57]
	v_mfma_f32_16x16x32_bf16 v[50:53], v[182:185], v[190:193], v[50:53]
	v_mfma_f32_16x16x32_bf16 v[38:41], v[174:177], v[198:201], v[38:41]
	v_mfma_f32_16x16x32_bf16 v[34:37], v[182:185], v[198:201], v[34:37]
	v_mfma_f32_16x16x32_bf16 v[22:25], v[174:177], v[206:209], v[22:25]
	v_mfma_f32_16x16x32_bf16 v[18:21], v[182:185], v[206:209], v[18:21]
	v_mfma_f32_16x16x32_bf16 v[6:9], v[174:177], v[214:217], v[6:9]
	v_mfma_f32_16x16x32_bf16 v[2:5], v[182:185], v[214:217], v[2:5]
	s_barrier
	s_add_i32 s55, 0, 0x18000
	v_add_u32_e32 v153, s55, v151
	s_add_i32 s56, 0, 0x1c000
	ds_read_b128 v[154:157], v153
	ds_read_b128 v[158:161], v153 offset:1024
	ds_read_b128 v[162:165], v153 offset:2048
	ds_read_b128 v[166:169], v153 offset:3072
	v_add_u32_e32 v153, s56, v151
	ds_read_b128 v[170:173], v153
	ds_read_b128 v[174:177], v153 offset:1024
	ds_read_b128 v[178:181], v153 offset:2048
	ds_read_b128 v[182:185], v153 offset:3072
	s_add_u32 s48, s48, 0x40000
	s_addc_u32 s49, s49, 0
	s_mov_b32 m0, s15
	ds_read_b128 v[186:189], v152 offset:32768
	ds_read_b128 v[190:193], v152 offset:33792
	ds_read_b128 v[194:197], v152 offset:34816
	ds_read_b128 v[198:201], v152 offset:35840
	ds_read_b128 v[202:205], v152 offset:36864
	ds_read_b128 v[206:209], v152 offset:37888
	ds_read_b128 v[210:213], v152 offset:38912
	ds_read_b128 v[214:217], v152 offset:39936
	global_load_lds_dwordx4 v130, s[48:49]
	s_mov_b32 m0, s40
	s_nop 0
	global_load_lds_dwordx4 v134, s[48:49]
	s_waitcnt vmcnt(8)
	s_waitcnt lgkmcnt(0)
	s_barrier
	s_waitcnt lgkmcnt(0)
	v_mfma_f32_16x16x32_bf16 v[126:129], v[154:157], v[186:189], v[126:129]
	v_mfma_f32_16x16x32_bf16 v[122:125], v[162:165], v[186:189], v[122:125]
	v_mfma_f32_16x16x32_bf16 v[110:113], v[154:157], v[194:197], v[110:113]
	v_mfma_f32_16x16x32_bf16 v[106:109], v[162:165], v[194:197], v[106:109]
	v_mfma_f32_16x16x32_bf16 v[94:97], v[154:157], v[202:205], v[94:97]
	v_mfma_f32_16x16x32_bf16 v[90:93], v[162:165], v[202:205], v[90:93]
	v_mfma_f32_16x16x32_bf16 v[78:81], v[154:157], v[210:213], v[78:81]
	v_mfma_f32_16x16x32_bf16 v[74:77], v[162:165], v[210:213], v[74:77]
	v_mfma_f32_16x16x32_bf16 v[126:129], v[158:161], v[190:193], v[126:129]
	v_mfma_f32_16x16x32_bf16 v[122:125], v[166:169], v[190:193], v[122:125]
	v_mfma_f32_16x16x32_bf16 v[110:113], v[158:161], v[198:201], v[110:113]
	v_mfma_f32_16x16x32_bf16 v[106:109], v[166:169], v[198:201], v[106:109]
	v_mfma_f32_16x16x32_bf16 v[94:97], v[158:161], v[206:209], v[94:97]
	v_mfma_f32_16x16x32_bf16 v[90:93], v[166:169], v[206:209], v[90:93]
	v_mfma_f32_16x16x32_bf16 v[78:81], v[158:161], v[214:217], v[78:81]
	v_mfma_f32_16x16x32_bf16 v[74:77], v[166:169], v[214:217], v[74:77]
	v_mfma_f32_16x16x32_bf16 v[118:121], v[170:173], v[186:189], v[118:121]
	v_mfma_f32_16x16x32_bf16 v[114:117], v[178:181], v[186:189], v[114:117]
	v_mfma_f32_16x16x32_bf16 v[102:105], v[170:173], v[194:197], v[102:105]
	v_mfma_f32_16x16x32_bf16 v[98:101], v[178:181], v[194:197], v[98:101]
	v_mfma_f32_16x16x32_bf16 v[86:89], v[170:173], v[202:205], v[86:89]
	v_mfma_f32_16x16x32_bf16 v[82:85], v[178:181], v[202:205], v[82:85]
	v_mfma_f32_16x16x32_bf16 v[70:73], v[170:173], v[210:213], v[70:73]
	v_mfma_f32_16x16x32_bf16 v[66:69], v[178:181], v[210:213], v[66:69]
	v_mfma_f32_16x16x32_bf16 v[118:121], v[174:177], v[190:193], v[118:121]
	v_mfma_f32_16x16x32_bf16 v[114:117], v[182:185], v[190:193], v[114:117]
	v_mfma_f32_16x16x32_bf16 v[102:105], v[174:177], v[198:201], v[102:105]
	v_mfma_f32_16x16x32_bf16 v[98:101], v[182:185], v[198:201], v[98:101]
	v_mfma_f32_16x16x32_bf16 v[86:89], v[174:177], v[206:209], v[86:89]
	v_mfma_f32_16x16x32_bf16 v[82:85], v[182:185], v[206:209], v[82:85]
	v_mfma_f32_16x16x32_bf16 v[70:73], v[174:177], v[214:217], v[70:73]
	v_mfma_f32_16x16x32_bf16 v[66:69], v[182:185], v[214:217], v[66:69]
	s_barrier
	s_add_i32 s48, s55, s13
	s_mov_b32 m0, s48
	ds_read_b128 v[186:189], v152 offset:49152
	ds_read_b128 v[190:193], v152 offset:50176
	ds_read_b128 v[194:197], v152 offset:51200
	ds_read_b128 v[198:201], v152 offset:52224
	ds_read_b128 v[202:205], v152 offset:53248
	ds_read_b128 v[206:209], v152 offset:54272
	ds_read_b128 v[210:213], v152 offset:55296
	ds_read_b128 v[214:217], v152 offset:56320
	global_load_lds_dwordx4 v132, s[98:99]
	s_add_i32 m0, s48, 0x2000
	s_add_u32 s46, s46, 0x40080
	s_addc_u32 s47, s47, 0
	s_add_i32 s48, s56, s13
	global_load_lds_dwordx4 v136, s[98:99]
	s_mov_b32 m0, s48
	s_nop 0
	global_load_lds_dwordx4 v132, s[46:47]
	s_add_i32 m0, s48, 0x2000
	s_nop 0
	global_load_lds_dwordx4 v136, s[46:47]
	s_mov_b32 m0, s42
	s_nop 0
	global_load_lds_dwordx4 v130, s[100:101]
	s_mov_b32 m0, s43
	s_nop 0
	global_load_lds_dwordx4 v134, s[100:101]
	s_waitcnt vmcnt(8)
	s_waitcnt lgkmcnt(0)
	s_barrier
	s_waitcnt lgkmcnt(0)
	v_mfma_f32_16x16x32_bf16 v[62:65], v[154:157], v[186:189], v[62:65]
	v_mfma_f32_16x16x32_bf16 v[58:61], v[162:165], v[186:189], v[58:61]
	v_mfma_f32_16x16x32_bf16 v[46:49], v[154:157], v[194:197], v[46:49]
	v_mfma_f32_16x16x32_bf16 v[42:45], v[162:165], v[194:197], v[42:45]
	v_mfma_f32_16x16x32_bf16 v[30:33], v[154:157], v[202:205], v[30:33]
	v_mfma_f32_16x16x32_bf16 v[26:29], v[162:165], v[202:205], v[26:29]
	v_mfma_f32_16x16x32_bf16 v[14:17], v[154:157], v[210:213], v[14:17]
	v_mfma_f32_16x16x32_bf16 v[10:13], v[162:165], v[210:213], v[10:13]
	v_mfma_f32_16x16x32_bf16 v[62:65], v[158:161], v[190:193], v[62:65]
	v_mfma_f32_16x16x32_bf16 v[58:61], v[166:169], v[190:193], v[58:61]
	v_mfma_f32_16x16x32_bf16 v[46:49], v[158:161], v[198:201], v[46:49]
	v_mfma_f32_16x16x32_bf16 v[42:45], v[166:169], v[198:201], v[42:45]
	v_mfma_f32_16x16x32_bf16 v[30:33], v[158:161], v[206:209], v[30:33]
	v_mfma_f32_16x16x32_bf16 v[26:29], v[166:169], v[206:209], v[26:29]
	v_mfma_f32_16x16x32_bf16 v[14:17], v[158:161], v[214:217], v[14:17]
	v_mfma_f32_16x16x32_bf16 v[10:13], v[166:169], v[214:217], v[10:13]
	v_mfma_f32_16x16x32_bf16 v[54:57], v[170:173], v[186:189], v[54:57]
	v_mfma_f32_16x16x32_bf16 v[50:53], v[178:181], v[186:189], v[50:53]
	v_mfma_f32_16x16x32_bf16 v[38:41], v[170:173], v[194:197], v[38:41]
	v_mfma_f32_16x16x32_bf16 v[34:37], v[178:181], v[194:197], v[34:37]
	v_mfma_f32_16x16x32_bf16 v[22:25], v[170:173], v[202:205], v[22:25]
	v_mfma_f32_16x16x32_bf16 v[18:21], v[178:181], v[202:205], v[18:21]
	v_mfma_f32_16x16x32_bf16 v[6:9], v[170:173], v[210:213], v[6:9]
	v_mfma_f32_16x16x32_bf16 v[2:5], v[178:181], v[210:213], v[2:5]
	v_mfma_f32_16x16x32_bf16 v[54:57], v[174:177], v[190:193], v[54:57]
	v_mfma_f32_16x16x32_bf16 v[50:53], v[182:185], v[190:193], v[50:53]
	v_mfma_f32_16x16x32_bf16 v[38:41], v[174:177], v[198:201], v[38:41]
	v_mfma_f32_16x16x32_bf16 v[34:37], v[182:185], v[198:201], v[34:37]
	v_mfma_f32_16x16x32_bf16 v[22:25], v[174:177], v[206:209], v[22:25]
	v_mfma_f32_16x16x32_bf16 v[18:21], v[182:185], v[206:209], v[18:21]
	v_mfma_f32_16x16x32_bf16 v[6:9], v[174:177], v[214:217], v[6:9]
	v_mfma_f32_16x16x32_bf16 v[2:5], v[182:185], v[214:217], v[2:5]
	s_barrier
	s_add_i32 s54, s54, 2
	s_add_u32 s30, s30, 0x100
	s_addc_u32 s31, s31, 0
	s_cmp_gt_u32 s54, 13
	s_cbranch_scc0 .LBB0_1631
	s_add_u32 s30, s50, 0xffffff00
	s_addc_u32 s31, s51, -1
	s_andn2_b64 vcc, exec, s[6:7]
	s_cbranch_vccnz .LBB0_1634
	v_mov_b32_e32 v2, 0
	s_mov_b32 s10, s22
	s_mov_b32 s16, s24
	s_mov_b64 s[18:19], s[28:29]
	s_mov_b32 s41, s2
	v_mov_b32_e32 v3, v2
	v_mov_b32_e32 v4, v2
	v_mov_b32_e32 v5, v2
	v_mov_b32_e32 v6, v2
	v_mov_b32_e32 v7, v2
	v_mov_b32_e32 v8, v2
	v_mov_b32_e32 v9, v2
	v_mov_b32_e32 v18, v2
	v_mov_b32_e32 v19, v2
	v_mov_b32_e32 v20, v2
	v_mov_b32_e32 v21, v2
	v_mov_b32_e32 v22, v2
	v_mov_b32_e32 v23, v2
	v_mov_b32_e32 v24, v2
	v_mov_b32_e32 v25, v2
	v_mov_b32_e32 v34, v2
	v_mov_b32_e32 v35, v2
	v_mov_b32_e32 v36, v2
	v_mov_b32_e32 v37, v2
	v_mov_b32_e32 v38, v2
	v_mov_b32_e32 v39, v2
	v_mov_b32_e32 v40, v2
	v_mov_b32_e32 v41, v2
	v_mov_b32_e32 v50, v2
	v_mov_b32_e32 v51, v2
	v_mov_b32_e32 v52, v2
	v_mov_b32_e32 v53, v2
	v_mov_b32_e32 v54, v2
	v_mov_b32_e32 v55, v2
	v_mov_b32_e32 v56, v2
	v_mov_b32_e32 v57, v2
	v_mov_b32_e32 v10, v2
	v_mov_b32_e32 v11, v2
	v_mov_b32_e32 v12, v2
	v_mov_b32_e32 v13, v2
	v_mov_b32_e32 v14, v2
	v_mov_b32_e32 v15, v2
	v_mov_b32_e32 v16, v2
	v_mov_b32_e32 v17, v2
	v_mov_b32_e32 v26, v2
	v_mov_b32_e32 v27, v2
	v_mov_b32_e32 v28, v2
	v_mov_b32_e32 v29, v2
	v_mov_b32_e32 v30, v2
	v_mov_b32_e32 v31, v2
	v_mov_b32_e32 v32, v2
	v_mov_b32_e32 v33, v2
	v_mov_b32_e32 v42, v2
	v_mov_b32_e32 v43, v2
	v_mov_b32_e32 v44, v2
	v_mov_b32_e32 v45, v2
	v_mov_b32_e32 v46, v2
	v_mov_b32_e32 v47, v2
	v_mov_b32_e32 v48, v2
	v_mov_b32_e32 v49, v2
	v_mov_b32_e32 v58, v2
	v_mov_b32_e32 v59, v2
	v_mov_b32_e32 v60, v2
	v_mov_b32_e32 v61, v2
	v_mov_b32_e32 v62, v2
	v_mov_b32_e32 v63, v2
	v_mov_b32_e32 v64, v2
	v_mov_b32_e32 v65, v2
	v_mov_b32_e32 v66, v2
	v_mov_b32_e32 v67, v2
	v_mov_b32_e32 v68, v2
	v_mov_b32_e32 v69, v2
	v_mov_b32_e32 v70, v2
	v_mov_b32_e32 v71, v2
	v_mov_b32_e32 v72, v2
	v_mov_b32_e32 v73, v2
	v_mov_b32_e32 v82, v2
	v_mov_b32_e32 v83, v2
	v_mov_b32_e32 v84, v2
	v_mov_b32_e32 v85, v2
	v_mov_b32_e32 v86, v2
	v_mov_b32_e32 v87, v2
	v_mov_b32_e32 v88, v2
	v_mov_b32_e32 v89, v2
	v_mov_b32_e32 v98, v2
	v_mov_b32_e32 v99, v2
	v_mov_b32_e32 v100, v2
	v_mov_b32_e32 v101, v2
	v_mov_b32_e32 v102, v2
	v_mov_b32_e32 v103, v2
	v_mov_b32_e32 v104, v2
	v_mov_b32_e32 v105, v2
	v_mov_b32_e32 v114, v2
	v_mov_b32_e32 v115, v2
	v_mov_b32_e32 v116, v2
	v_mov_b32_e32 v117, v2
	v_mov_b32_e32 v118, v2
	v_mov_b32_e32 v119, v2
	v_mov_b32_e32 v120, v2
	v_mov_b32_e32 v121, v2
	v_mov_b32_e32 v74, v2
	v_mov_b32_e32 v75, v2
	v_mov_b32_e32 v76, v2
	v_mov_b32_e32 v77, v2
	v_mov_b32_e32 v78, v2
	v_mov_b32_e32 v79, v2
	v_mov_b32_e32 v80, v2
	v_mov_b32_e32 v81, v2
	v_mov_b32_e32 v90, v2
	v_mov_b32_e32 v91, v2
	v_mov_b32_e32 v92, v2
	v_mov_b32_e32 v93, v2
	v_mov_b32_e32 v94, v2
	v_mov_b32_e32 v95, v2
	v_mov_b32_e32 v96, v2
	v_mov_b32_e32 v97, v2
	v_mov_b32_e32 v106, v2
	v_mov_b32_e32 v107, v2
	v_mov_b32_e32 v108, v2
	v_mov_b32_e32 v109, v2
	v_mov_b32_e32 v110, v2
	v_mov_b32_e32 v111, v2
	v_mov_b32_e32 v112, v2
	v_mov_b32_e32 v113, v2
	v_mov_b32_e32 v122, v2
	v_mov_b32_e32 v123, v2
	v_mov_b32_e32 v124, v2
	v_mov_b32_e32 v125, v2
	v_mov_b32_e32 v126, v2
	v_mov_b32_e32 v127, v2
	v_mov_b32_e32 v128, v2
	v_mov_b32_e32 v129, v2
	s_andn2_b64 vcc, exec, s[4:5]
	s_cbranch_vccnz .LBB0_1635
	s_branch .LBB0_1636

.LBB0_1765:
	s_waitcnt lgkmcnt(0)
	s_barrier
	s_waitcnt lgkmcnt(0)
	v_mfma_f32_16x16x32_bf16 v[66:69], v[150:153], v[190:193], v[66:69]
	v_mfma_f32_16x16x32_bf16 v[58:61], v[158:161], v[190:193], v[58:61]
	v_mfma_f32_16x16x32_bf16 v[50:53], v[150:153], v[182:185], v[50:53]
	v_mfma_f32_16x16x32_bf16 v[42:45], v[158:161], v[182:185], v[42:45]
	v_mfma_f32_16x16x32_bf16 v[34:37], v[150:153], v[174:177], v[34:37]
	v_mfma_f32_16x16x32_bf16 v[26:29], v[158:161], v[174:177], v[26:29]
	v_mfma_f32_16x16x32_bf16 v[18:21], v[150:153], v[166:169], v[18:21]
	v_mfma_f32_16x16x32_bf16 v[10:13], v[158:161], v[166:169], v[10:13]
	v_mfma_f32_16x16x32_bf16 v[66:69], v[154:157], v[194:197], v[66:69]
	v_mfma_f32_16x16x32_bf16 v[58:61], v[162:165], v[194:197], v[58:61]
	v_mfma_f32_16x16x32_bf16 v[50:53], v[154:157], v[186:189], v[50:53]
	v_mfma_f32_16x16x32_bf16 v[42:45], v[162:165], v[186:189], v[42:45]
	v_mfma_f32_16x16x32_bf16 v[34:37], v[154:157], v[178:181], v[34:37]
	v_mfma_f32_16x16x32_bf16 v[26:29], v[162:165], v[178:181], v[26:29]
	v_mfma_f32_16x16x32_bf16 v[18:21], v[154:157], v[170:173], v[18:21]
	v_mfma_f32_16x16x32_bf16 v[10:13], v[162:165], v[170:173], v[10:13]
	v_mfma_f32_16x16x32_bf16 v[62:65], v[134:137], v[190:193], v[62:65]
	v_mfma_f32_16x16x32_bf16 v[54:57], v[142:145], v[190:193], v[54:57]
	v_mfma_f32_16x16x32_bf16 v[46:49], v[134:137], v[182:185], v[46:49]
	v_mfma_f32_16x16x32_bf16 v[38:41], v[142:145], v[182:185], v[38:41]
	v_mfma_f32_16x16x32_bf16 v[30:33], v[134:137], v[174:177], v[30:33]
	v_mfma_f32_16x16x32_bf16 v[22:25], v[142:145], v[174:177], v[22:25]
	v_mfma_f32_16x16x32_bf16 v[14:17], v[134:137], v[166:169], v[14:17]
	v_mfma_f32_16x16x32_bf16 v[6:9], v[142:145], v[166:169], v[6:9]
	v_mfma_f32_16x16x32_bf16 v[62:65], v[138:141], v[194:197], v[62:65]
	v_mfma_f32_16x16x32_bf16 v[54:57], v[146:149], v[194:197], v[54:57]
	v_mfma_f32_16x16x32_bf16 v[46:49], v[138:141], v[186:189], v[46:49]
	v_mfma_f32_16x16x32_bf16 v[38:41], v[146:149], v[186:189], v[38:41]
	v_mfma_f32_16x16x32_bf16 v[30:33], v[138:141], v[178:181], v[30:33]
	v_mfma_f32_16x16x32_bf16 v[22:25], v[146:149], v[178:181], v[22:25]
	v_mfma_f32_16x16x32_bf16 v[14:17], v[138:141], v[170:173], v[14:17]
	v_mfma_f32_16x16x32_bf16 v[6:9], v[146:149], v[170:173], v[6:9]
	s_barrier
	s_add_i32 s61, s61, 2
	s_add_u32 s28, s28, 0x100
	s_addc_u32 s29, s29, 0
	s_add_u32 s59, s59, 0x100
	s_addc_u32 s60, s60, 0
	s_cmp_gt_u32 s61, 13
	s_cbranch_scc1 .LBB0_1771

.LBB0_1768:
	v_add_u32_e32 v146, s53, v217
	v_add_u32_e32 v162, s54, v217
	ds_read_b128 v[134:137], v146
	ds_read_b128 v[138:141], v146 offset:1024
	ds_read_b128 v[142:145], v146 offset:2048
	ds_read_b128 v[146:149], v146 offset:3072
	ds_read_b128 v[150:153], v162
	ds_read_b128 v[154:157], v162 offset:1024
	ds_read_b128 v[158:161], v162 offset:2048
	ds_read_b128 v[162:165], v162 offset:3072
	s_add_u32 s48, s28, 0xfffc0080
	s_addc_u32 s49, s29, -1
	s_and_b64 s[46:47], s[30:31], exec
	s_cselect_b32 s49, s23, s49
	s_cselect_b32 s48, s56, s48
	s_cselect_b32 s47, s57, s60
	s_cselect_b32 s46, s58, s59
	s_add_i32 m0, s40, 0xc000
	ds_read_b128 v[166:169], v220
	ds_read_b128 v[170:173], v220 offset:1024
	ds_read_b128 v[174:177], v220 offset:2048
	ds_read_b128 v[178:181], v220 offset:3072
	ds_read_b128 v[182:185], v220 offset:4096
	ds_read_b128 v[186:189], v220 offset:5120
	ds_read_b128 v[190:193], v220 offset:6144
	ds_read_b128 v[194:197], v220 offset:7168
	global_load_lds_dwordx4 v206, s[28:29]
	s_add_i32 m0, s40, 0xe000
	s_nop 0
	global_load_lds_dwordx4 v208, s[28:29]
	s_waitcnt vmcnt(8)
	s_waitcnt lgkmcnt(0)
	s_barrier
	s_waitcnt lgkmcnt(0)
	v_mfma_f32_16x16x32_bf16 v[130:133], v[134:137], v[166:169], v[130:133]
	v_mfma_f32_16x16x32_bf16 v[122:125], v[142:145], v[166:169], v[122:125]
	v_mfma_f32_16x16x32_bf16 v[114:117], v[134:137], v[174:177], v[114:117]
	v_mfma_f32_16x16x32_bf16 v[106:109], v[142:145], v[174:177], v[106:109]
	v_mfma_f32_16x16x32_bf16 v[98:101], v[134:137], v[182:185], v[98:101]
	v_mfma_f32_16x16x32_bf16 v[90:93], v[142:145], v[182:185], v[90:93]
	v_mfma_f32_16x16x32_bf16 v[82:85], v[134:137], v[190:193], v[82:85]
	v_mfma_f32_16x16x32_bf16 v[74:77], v[142:145], v[190:193], v[74:77]
	v_mfma_f32_16x16x32_bf16 v[130:133], v[138:141], v[170:173], v[130:133]
	v_mfma_f32_16x16x32_bf16 v[122:125], v[146:149], v[170:173], v[122:125]
	v_mfma_f32_16x16x32_bf16 v[114:117], v[138:141], v[178:181], v[114:117]
	v_mfma_f32_16x16x32_bf16 v[106:109], v[146:149], v[178:181], v[106:109]
	v_mfma_f32_16x16x32_bf16 v[98:101], v[138:141], v[186:189], v[98:101]
	v_mfma_f32_16x16x32_bf16 v[90:93], v[146:149], v[186:189], v[90:93]
	v_mfma_f32_16x16x32_bf16 v[82:85], v[138:141], v[194:197], v[82:85]
	v_mfma_f32_16x16x32_bf16 v[74:77], v[146:149], v[194:197], v[74:77]
	v_mfma_f32_16x16x32_bf16 v[126:129], v[150:153], v[166:169], v[126:129]
	v_mfma_f32_16x16x32_bf16 v[118:121], v[158:161], v[166:169], v[118:121]
	v_mfma_f32_16x16x32_bf16 v[110:113], v[150:153], v[174:177], v[110:113]
	v_mfma_f32_16x16x32_bf16 v[102:105], v[158:161], v[174:177], v[102:105]
	v_mfma_f32_16x16x32_bf16 v[94:97], v[150:153], v[182:185], v[94:97]
	v_mfma_f32_16x16x32_bf16 v[86:89], v[158:161], v[182:185], v[86:89]
	v_mfma_f32_16x16x32_bf16 v[78:81], v[150:153], v[190:193], v[78:81]
	v_mfma_f32_16x16x32_bf16 v[70:73], v[158:161], v[190:193], v[70:73]
	v_mfma_f32_16x16x32_bf16 v[126:129], v[154:157], v[170:173], v[126:129]
	v_mfma_f32_16x16x32_bf16 v[118:121], v[162:165], v[170:173], v[118:121]
	v_mfma_f32_16x16x32_bf16 v[110:113], v[154:157], v[178:181], v[110:113]
	v_mfma_f32_16x16x32_bf16 v[102:105], v[162:165], v[178:181], v[102:105]
	v_mfma_f32_16x16x32_bf16 v[94:97], v[154:157], v[186:189], v[94:97]
	v_mfma_f32_16x16x32_bf16 v[86:89], v[162:165], v[186:189], v[86:89]
	v_mfma_f32_16x16x32_bf16 v[78:81], v[154:157], v[194:197], v[78:81]
	v_mfma_f32_16x16x32_bf16 v[70:73], v[162:165], v[194:197], v[70:73]
	s_barrier
	s_add_i32 s62, s53, s12
	s_add_u32 s98, s46, s16
	s_addc_u32 s99, s47, s17
	s_mov_b32 m0, s62
	ds_read_b128 v[166:169], v220 offset:16384
	ds_read_b128 v[170:173], v220 offset:17408
	ds_read_b128 v[174:177], v220 offset:18432
	ds_read_b128 v[178:181], v220 offset:19456
	ds_read_b128 v[182:185], v220 offset:20480
	ds_read_b128 v[186:189], v220 offset:21504
	ds_read_b128 v[190:193], v220 offset:22528
	ds_read_b128 v[194:197], v220 offset:23552
	global_load_lds_dwordx4 v202, s[46:47]
	s_add_i32 m0, s62, 0x2000
	s_add_u32 s62, s46, 0x40000
	s_addc_u32 s63, s47, 0
	s_add_i32 s64, s54, s12
	global_load_lds_dwordx4 v198, s[46:47]
	s_mov_b32 m0, s64
	s_nop 0
	global_load_lds_dwordx4 v202, s[62:63]
	s_add_i32 m0, s64, 0x2000
	s_nop 0
	global_load_lds_dwordx4 v198, s[62:63]
	s_add_u32 s100, s48, s16
	s_addc_u32 s101, s49, s17
	s_mov_b32 m0, s40
	s_nop 0
	global_load_lds_dwordx4 v204, s[48:49]
	s_mov_b32 m0, s41
	s_nop 0
	global_load_lds_dwordx4 v200, s[48:49]
	s_waitcnt vmcnt(8)
	s_waitcnt lgkmcnt(0)
	s_barrier
	s_waitcnt lgkmcnt(0)
	v_mfma_f32_16x16x32_bf16 v[66:69], v[134:137], v[166:169], v[66:69]
	v_mfma_f32_16x16x32_bf16 v[58:61], v[142:145], v[166:169], v[58:61]
	v_mfma_f32_16x16x32_bf16 v[50:53], v[134:137], v[174:177], v[50:53]
	v_mfma_f32_16x16x32_bf16 v[42:45], v[142:145], v[174:177], v[42:45]
	v_mfma_f32_16x16x32_bf16 v[34:37], v[134:137], v[182:185], v[34:37]
	v_mfma_f32_16x16x32_bf16 v[26:29], v[142:145], v[182:185], v[26:29]
	v_mfma_f32_16x16x32_bf16 v[18:21], v[134:137], v[190:193], v[18:21]
	v_mfma_f32_16x16x32_bf16 v[10:13], v[142:145], v[190:193], v[10:13]
	v_mfma_f32_16x16x32_bf16 v[66:69], v[138:141], v[170:173], v[66:69]
	v_mfma_f32_16x16x32_bf16 v[58:61], v[146:149], v[170:173], v[58:61]
	v_mfma_f32_16x16x32_bf16 v[50:53], v[138:141], v[178:181], v[50:53]
	v_mfma_f32_16x16x32_bf16 v[42:45], v[146:149], v[178:181], v[42:45]
	v_mfma_f32_16x16x32_bf16 v[34:37], v[138:141], v[186:189], v[34:37]
	v_mfma_f32_16x16x32_bf16 v[26:29], v[146:149], v[186:189], v[26:29]
	v_mfma_f32_16x16x32_bf16 v[18:21], v[138:141], v[194:197], v[18:21]
	v_mfma_f32_16x16x32_bf16 v[10:13], v[146:149], v[194:197], v[10:13]
	v_mfma_f32_16x16x32_bf16 v[62:65], v[150:153], v[166:169], v[62:65]
	v_mfma_f32_16x16x32_bf16 v[54:57], v[158:161], v[166:169], v[54:57]
	v_mfma_f32_16x16x32_bf16 v[46:49], v[150:153], v[174:177], v[46:49]
	v_mfma_f32_16x16x32_bf16 v[38:41], v[158:161], v[174:177], v[38:41]
	v_mfma_f32_16x16x32_bf16 v[30:33], v[150:153], v[182:185], v[30:33]
	v_mfma_f32_16x16x32_bf16 v[22:25], v[158:161], v[182:185], v[22:25]
	v_mfma_f32_16x16x32_bf16 v[14:17], v[150:153], v[190:193], v[14:17]
	v_mfma_f32_16x16x32_bf16 v[6:9], v[158:161], v[190:193], v[6:9]
	v_mfma_f32_16x16x32_bf16 v[62:65], v[154:157], v[170:173], v[62:65]
	v_mfma_f32_16x16x32_bf16 v[54:57], v[162:165], v[170:173], v[54:57]
	v_mfma_f32_16x16x32_bf16 v[46:49], v[154:157], v[178:181], v[46:49]
	v_mfma_f32_16x16x32_bf16 v[38:41], v[162:165], v[178:181], v[38:41]
	v_mfma_f32_16x16x32_bf16 v[30:33], v[154:157], v[186:189], v[30:33]
	v_mfma_f32_16x16x32_bf16 v[22:25], v[162:165], v[186:189], v[22:25]
	v_mfma_f32_16x16x32_bf16 v[14:17], v[154:157], v[194:197], v[14:17]
	v_mfma_f32_16x16x32_bf16 v[6:9], v[162:165], v[194:197], v[6:9]
	s_barrier
	s_add_i32 s62, 0, 0x18000
	s_add_i32 s63, 0, 0x1c000
	v_add_u32_e32 v134, s62, v217
	v_add_u32_e32 v146, s63, v217
	ds_read_b128 v[150:153], v134
	ds_read_b128 v[154:157], v134 offset:1024
	ds_read_b128 v[158:161], v134 offset:2048
	ds_read_b128 v[162:165], v134 offset:3072
	ds_read_b128 v[134:137], v146
	ds_read_b128 v[138:141], v146 offset:1024
	ds_read_b128 v[142:145], v146 offset:2048
	ds_read_b128 v[146:149], v146 offset:3072
	s_add_u32 s48, s48, 0x40000
	s_addc_u32 s49, s49, 0
	s_mov_b32 m0, s42
	ds_read_b128 v[166:169], v220 offset:32768
	ds_read_b128 v[170:173], v220 offset:33792
	ds_read_b128 v[174:177], v220 offset:34816
	ds_read_b128 v[178:181], v220 offset:35840
	ds_read_b128 v[182:185], v220 offset:36864
	ds_read_b128 v[186:189], v220 offset:37888
	ds_read_b128 v[190:193], v220 offset:38912
	ds_read_b128 v[194:197], v220 offset:39936
	global_load_lds_dwordx4 v204, s[48:49]
	s_mov_b32 m0, s43
	s_nop 0
	global_load_lds_dwordx4 v200, s[48:49]
	s_waitcnt vmcnt(8)
	s_waitcnt lgkmcnt(0)
	s_barrier
	s_waitcnt lgkmcnt(0)
	v_mfma_f32_16x16x32_bf16 v[130:133], v[150:153], v[166:169], v[130:133]
	v_mfma_f32_16x16x32_bf16 v[122:125], v[158:161], v[166:169], v[122:125]
	v_mfma_f32_16x16x32_bf16 v[114:117], v[150:153], v[174:177], v[114:117]
	v_mfma_f32_16x16x32_bf16 v[106:109], v[158:161], v[174:177], v[106:109]
	v_mfma_f32_16x16x32_bf16 v[98:101], v[150:153], v[182:185], v[98:101]
	v_mfma_f32_16x16x32_bf16 v[90:93], v[158:161], v[182:185], v[90:93]
	v_mfma_f32_16x16x32_bf16 v[82:85], v[150:153], v[190:193], v[82:85]
	v_mfma_f32_16x16x32_bf16 v[74:77], v[158:161], v[190:193], v[74:77]
	v_mfma_f32_16x16x32_bf16 v[130:133], v[154:157], v[170:173], v[130:133]
	v_mfma_f32_16x16x32_bf16 v[122:125], v[162:165], v[170:173], v[122:125]
	v_mfma_f32_16x16x32_bf16 v[114:117], v[154:157], v[178:181], v[114:117]
	v_mfma_f32_16x16x32_bf16 v[106:109], v[162:165], v[178:181], v[106:109]
	v_mfma_f32_16x16x32_bf16 v[98:101], v[154:157], v[186:189], v[98:101]
	v_mfma_f32_16x16x32_bf16 v[90:93], v[162:165], v[186:189], v[90:93]
	v_mfma_f32_16x16x32_bf16 v[82:85], v[154:157], v[194:197], v[82:85]
	v_mfma_f32_16x16x32_bf16 v[74:77], v[162:165], v[194:197], v[74:77]
	v_mfma_f32_16x16x32_bf16 v[126:129], v[134:137], v[166:169], v[126:129]
	v_mfma_f32_16x16x32_bf16 v[118:121], v[142:145], v[166:169], v[118:121]
	v_mfma_f32_16x16x32_bf16 v[110:113], v[134:137], v[174:177], v[110:113]
	v_mfma_f32_16x16x32_bf16 v[102:105], v[142:145], v[174:177], v[102:105]
	v_mfma_f32_16x16x32_bf16 v[94:97], v[134:137], v[182:185], v[94:97]
	v_mfma_f32_16x16x32_bf16 v[86:89], v[142:145], v[182:185], v[86:89]
	v_mfma_f32_16x16x32_bf16 v[78:81], v[134:137], v[190:193], v[78:81]
	v_mfma_f32_16x16x32_bf16 v[70:73], v[142:145], v[190:193], v[70:73]
	v_mfma_f32_16x16x32_bf16 v[126:129], v[138:141], v[170:173], v[126:129]
	v_mfma_f32_16x16x32_bf16 v[118:121], v[146:149], v[170:173], v[118:121]
	v_mfma_f32_16x16x32_bf16 v[110:113], v[138:141], v[178:181], v[110:113]
	v_mfma_f32_16x16x32_bf16 v[102:105], v[146:149], v[178:181], v[102:105]
	v_mfma_f32_16x16x32_bf16 v[94:97], v[138:141], v[186:189], v[94:97]
	v_mfma_f32_16x16x32_bf16 v[86:89], v[146:149], v[186:189], v[86:89]
	v_mfma_f32_16x16x32_bf16 v[78:81], v[138:141], v[194:197], v[78:81]
	v_mfma_f32_16x16x32_bf16 v[70:73], v[146:149], v[194:197], v[70:73]
	s_barrier
	s_add_i32 s48, s62, s12
	s_mov_b32 m0, s48
	ds_read_b128 v[190:193], v220 offset:49152
	ds_read_b128 v[194:197], v220 offset:50176
	ds_read_b128 v[182:185], v220 offset:51200
	ds_read_b128 v[186:189], v220 offset:52224
	ds_read_b128 v[174:177], v220 offset:53248
	ds_read_b128 v[178:181], v220 offset:54272
	ds_read_b128 v[166:169], v220 offset:55296
	ds_read_b128 v[170:173], v220 offset:56320
	global_load_lds_dwordx4 v202, s[98:99]
	s_add_i32 m0, s48, 0x2000
	s_add_u32 s46, s46, 0x40080
	s_addc_u32 s47, s47, 0
	s_add_i32 s48, s63, s12
	global_load_lds_dwordx4 v198, s[98:99]
	s_mov_b32 m0, s48
	s_andn2_b64 vcc, exec, s[30:31]
	global_load_lds_dwordx4 v202, s[46:47]
	s_add_i32 m0, s48, 0x2000
	s_nop 0
	global_load_lds_dwordx4 v198, s[46:47]
	s_mov_b32 m0, s51
	s_nop 0
	global_load_lds_dwordx4 v204, s[100:101]
	s_mov_b32 m0, s52
	s_nop 0
	global_load_lds_dwordx4 v200, s[100:101]
	s_waitcnt vmcnt(8)
	s_cbranch_vccnz .LBB0_1765
	s_and_saveexec_b64 s[30:31], s[4:5]
	s_cbranch_execz .LBB0_1764
	v_mov_b32_e32 v222, v3
	v_mov_b32_e32 v223, v4
	v_mov_b32_e32 v224, v2
	v_mov_b32_e32 v225, v5
	v_pk_add_f32 v[222:223], v[222:223], v[224:225]
	s_nop 0
	v_add_f32_e32 v222, v222, v223
	v_fmamk_f32 v222, v222, 0x3a800000, v221
	ds_write_b32 v219, v222
	s_branch .LBB0_1764

.LBB0_1894:
	v_add_u32_e32 v153, s44, v151
	ds_read_b128 v[154:157], v153
	ds_read_b128 v[158:161], v153 offset:1024
	ds_read_b128 v[162:165], v153 offset:2048
	ds_read_b128 v[166:169], v153 offset:3072
	v_add_u32_e32 v153, s45, v151
	s_add_u32 s26, s18, s24
	ds_read_b128 v[170:173], v153
	ds_read_b128 v[174:177], v153 offset:1024
	ds_read_b128 v[178:181], v153 offset:2048
	ds_read_b128 v[182:185], v153 offset:3072
	s_addc_u32 s27, s19, s25
	s_add_u32 s26, s26, 0x100
	s_addc_u32 s27, s27, 0
	s_add_u32 s51, s48, s24
	s_addc_u32 s52, s49, s25
	s_cmpk_eq_i32 s24, 0x1500
	s_cselect_b32 s29, s23, s27
	s_cselect_b32 s28, s22, s26
	s_cselect_b32 s27, s9, s52
	s_cselect_b32 s26, s8, s51
	v_lshl_add_u64 v[218:219], v[146:147], 0, s[24:25]
	s_add_i32 m0, s33, 0xc000
	ds_read_b128 v[186:189], v152
	ds_read_b128 v[190:193], v152 offset:1024
	ds_read_b128 v[194:197], v152 offset:2048
	ds_read_b128 v[198:201], v152 offset:3072
	ds_read_b128 v[202:205], v152 offset:4096
	ds_read_b128 v[206:209], v152 offset:5120
	ds_read_b128 v[210:213], v152 offset:6144
	ds_read_b128 v[214:217], v152 offset:7168
	global_load_lds_dwordx4 v[218:219], off
	v_lshl_add_u64 v[218:219], v[148:149], 0, s[24:25]
	s_add_i32 m0, s33, 0xe000
	s_nop 0
	global_load_lds_dwordx4 v[218:219], off
	s_waitcnt vmcnt(8)
	s_waitcnt lgkmcnt(0)
	s_barrier
	s_waitcnt lgkmcnt(0)
	v_mfma_f32_16x16x32_bf16 v[126:129], v[154:157], v[186:189], v[126:129]
	v_mfma_f32_16x16x32_bf16 v[122:125], v[162:165], v[186:189], v[122:125]
	v_mfma_f32_16x16x32_bf16 v[110:113], v[154:157], v[194:197], v[110:113]
	v_mfma_f32_16x16x32_bf16 v[106:109], v[162:165], v[194:197], v[106:109]
	v_mfma_f32_16x16x32_bf16 v[94:97], v[154:157], v[202:205], v[94:97]
	v_mfma_f32_16x16x32_bf16 v[90:93], v[162:165], v[202:205], v[90:93]
	v_mfma_f32_16x16x32_bf16 v[78:81], v[154:157], v[210:213], v[78:81]
	v_mfma_f32_16x16x32_bf16 v[74:77], v[162:165], v[210:213], v[74:77]
	v_mfma_f32_16x16x32_bf16 v[126:129], v[158:161], v[190:193], v[126:129]
	v_mfma_f32_16x16x32_bf16 v[122:125], v[166:169], v[190:193], v[122:125]
	v_mfma_f32_16x16x32_bf16 v[110:113], v[158:161], v[198:201], v[110:113]
	v_mfma_f32_16x16x32_bf16 v[106:109], v[166:169], v[198:201], v[106:109]
	v_mfma_f32_16x16x32_bf16 v[94:97], v[158:161], v[206:209], v[94:97]
	v_mfma_f32_16x16x32_bf16 v[90:93], v[166:169], v[206:209], v[90:93]
	v_mfma_f32_16x16x32_bf16 v[78:81], v[158:161], v[214:217], v[78:81]
	v_mfma_f32_16x16x32_bf16 v[74:77], v[166:169], v[214:217], v[74:77]
	v_mfma_f32_16x16x32_bf16 v[118:121], v[170:173], v[186:189], v[118:121]
	v_mfma_f32_16x16x32_bf16 v[114:117], v[178:181], v[186:189], v[114:117]
	v_mfma_f32_16x16x32_bf16 v[102:105], v[170:173], v[194:197], v[102:105]
	v_mfma_f32_16x16x32_bf16 v[98:101], v[178:181], v[194:197], v[98:101]
	v_mfma_f32_16x16x32_bf16 v[86:89], v[170:173], v[202:205], v[86:89]
	v_mfma_f32_16x16x32_bf16 v[82:85], v[178:181], v[202:205], v[82:85]
	v_mfma_f32_16x16x32_bf16 v[70:73], v[170:173], v[210:213], v[70:73]
	v_mfma_f32_16x16x32_bf16 v[66:69], v[178:181], v[210:213], v[66:69]
	v_mfma_f32_16x16x32_bf16 v[118:121], v[174:177], v[190:193], v[118:121]
	v_mfma_f32_16x16x32_bf16 v[114:117], v[182:185], v[190:193], v[114:117]
	v_mfma_f32_16x16x32_bf16 v[102:105], v[174:177], v[198:201], v[102:105]
	v_mfma_f32_16x16x32_bf16 v[98:101], v[182:185], v[198:201], v[98:101]
	v_mfma_f32_16x16x32_bf16 v[86:89], v[174:177], v[206:209], v[86:89]
	v_mfma_f32_16x16x32_bf16 v[82:85], v[182:185], v[206:209], v[82:85]
	v_mfma_f32_16x16x32_bf16 v[70:73], v[174:177], v[214:217], v[70:73]
	v_mfma_f32_16x16x32_bf16 v[66:69], v[182:185], v[214:217], v[66:69]
	s_barrier
	s_add_i32 s51, s44, s13
	s_add_u32 s98, s26, s20
	s_addc_u32 s99, s27, s21
	s_mov_b32 m0, s51
	ds_read_b128 v[186:189], v152 offset:16384
	ds_read_b128 v[190:193], v152 offset:17408
	ds_read_b128 v[194:197], v152 offset:18432
	ds_read_b128 v[198:201], v152 offset:19456
	ds_read_b128 v[202:205], v152 offset:20480
	ds_read_b128 v[206:209], v152 offset:21504
	ds_read_b128 v[210:213], v152 offset:22528
	ds_read_b128 v[214:217], v152 offset:23552
	global_load_lds_dwordx4 v132, s[26:27]
	s_add_i32 m0, s51, 0x2000
	s_add_u32 s52, s26, 0xb0000
	s_addc_u32 s53, s27, 0
	s_add_i32 s51, s45, s13
	global_load_lds_dwordx4 v136, s[26:27]
	s_mov_b32 m0, s51
	s_nop 0
	global_load_lds_dwordx4 v132, s[52:53]
	s_add_i32 m0, s51, 0x2000
	s_nop 0
	global_load_lds_dwordx4 v136, s[52:53]
	s_add_u32 s100, s28, s20
	s_addc_u32 s101, s29, s21
	s_mov_b32 m0, s33
	s_nop 0
	global_load_lds_dwordx4 v130, s[28:29]
	s_mov_b32 m0, s14
	s_nop 0
	global_load_lds_dwordx4 v134, s[28:29]
	s_waitcnt vmcnt(8)
	s_waitcnt lgkmcnt(0)
	s_barrier
	s_waitcnt lgkmcnt(0)
	v_mfma_f32_16x16x32_bf16 v[62:65], v[154:157], v[186:189], v[62:65]
	v_mfma_f32_16x16x32_bf16 v[58:61], v[162:165], v[186:189], v[58:61]
	v_mfma_f32_16x16x32_bf16 v[46:49], v[154:157], v[194:197], v[46:49]
	v_mfma_f32_16x16x32_bf16 v[42:45], v[162:165], v[194:197], v[42:45]
	v_mfma_f32_16x16x32_bf16 v[30:33], v[154:157], v[202:205], v[30:33]
	v_mfma_f32_16x16x32_bf16 v[26:29], v[162:165], v[202:205], v[26:29]
	v_mfma_f32_16x16x32_bf16 v[14:17], v[154:157], v[210:213], v[14:17]
	v_mfma_f32_16x16x32_bf16 v[10:13], v[162:165], v[210:213], v[10:13]
	v_mfma_f32_16x16x32_bf16 v[62:65], v[158:161], v[190:193], v[62:65]
	v_mfma_f32_16x16x32_bf16 v[58:61], v[166:169], v[190:193], v[58:61]
	v_mfma_f32_16x16x32_bf16 v[46:49], v[158:161], v[198:201], v[46:49]
	v_mfma_f32_16x16x32_bf16 v[42:45], v[166:169], v[198:201], v[42:45]
	v_mfma_f32_16x16x32_bf16 v[30:33], v[158:161], v[206:209], v[30:33]
	v_mfma_f32_16x16x32_bf16 v[26:29], v[166:169], v[206:209], v[26:29]
	v_mfma_f32_16x16x32_bf16 v[14:17], v[158:161], v[214:217], v[14:17]
	v_mfma_f32_16x16x32_bf16 v[10:13], v[166:169], v[214:217], v[10:13]
	v_mfma_f32_16x16x32_bf16 v[54:57], v[170:173], v[186:189], v[54:57]
	v_mfma_f32_16x16x32_bf16 v[50:53], v[178:181], v[186:189], v[50:53]
	v_mfma_f32_16x16x32_bf16 v[38:41], v[170:173], v[194:197], v[38:41]
	v_mfma_f32_16x16x32_bf16 v[34:37], v[178:181], v[194:197], v[34:37]
	v_mfma_f32_16x16x32_bf16 v[22:25], v[170:173], v[202:205], v[22:25]
	v_mfma_f32_16x16x32_bf16 v[18:21], v[178:181], v[202:205], v[18:21]
	v_mfma_f32_16x16x32_bf16 v[6:9], v[170:173], v[210:213], v[6:9]
	v_mfma_f32_16x16x32_bf16 v[2:5], v[178:181], v[210:213], v[2:5]
	v_mfma_f32_16x16x32_bf16 v[54:57], v[174:177], v[190:193], v[54:57]
	v_mfma_f32_16x16x32_bf16 v[50:53], v[182:185], v[190:193], v[50:53]
	v_mfma_f32_16x16x32_bf16 v[38:41], v[174:177], v[198:201], v[38:41]
	v_mfma_f32_16x16x32_bf16 v[34:37], v[182:185], v[198:201], v[34:37]
	v_mfma_f32_16x16x32_bf16 v[22:25], v[174:177], v[206:209], v[22:25]
	v_mfma_f32_16x16x32_bf16 v[18:21], v[182:185], v[206:209], v[18:21]
	v_mfma_f32_16x16x32_bf16 v[6:9], v[174:177], v[214:217], v[6:9]
	v_mfma_f32_16x16x32_bf16 v[2:5], v[182:185], v[214:217], v[2:5]
	s_barrier
	s_add_i32 s51, 0, 0x18000
	v_add_u32_e32 v153, s51, v151
	s_add_i32 s52, 0, 0x1c000
	ds_read_b128 v[154:157], v153
	ds_read_b128 v[158:161], v153 offset:1024
	ds_read_b128 v[162:165], v153 offset:2048
	ds_read_b128 v[166:169], v153 offset:3072
	v_add_u32_e32 v153, s52, v151
	ds_read_b128 v[170:173], v153
	ds_read_b128 v[174:177], v153 offset:1024
	ds_read_b128 v[178:181], v153 offset:2048
	ds_read_b128 v[182:185], v153 offset:3072
	s_add_u32 s28, s28, 0xb0000
	s_addc_u32 s29, s29, 0
	s_mov_b32 m0, s15
	ds_read_b128 v[186:189], v152 offset:32768
	ds_read_b128 v[190:193], v152 offset:33792
	ds_read_b128 v[194:197], v152 offset:34816
	ds_read_b128 v[198:201], v152 offset:35840
	ds_read_b128 v[202:205], v152 offset:36864
	ds_read_b128 v[206:209], v152 offset:37888
	ds_read_b128 v[210:213], v152 offset:38912
	ds_read_b128 v[214:217], v152 offset:39936
	global_load_lds_dwordx4 v130, s[28:29]
	s_mov_b32 m0, s40
	s_nop 0
	global_load_lds_dwordx4 v134, s[28:29]
	s_waitcnt vmcnt(8)
	s_waitcnt lgkmcnt(0)
	s_barrier
	s_waitcnt lgkmcnt(0)
	v_mfma_f32_16x16x32_bf16 v[126:129], v[154:157], v[186:189], v[126:129]
	v_mfma_f32_16x16x32_bf16 v[122:125], v[162:165], v[186:189], v[122:125]
	v_mfma_f32_16x16x32_bf16 v[110:113], v[154:157], v[194:197], v[110:113]
	v_mfma_f32_16x16x32_bf16 v[106:109], v[162:165], v[194:197], v[106:109]
	v_mfma_f32_16x16x32_bf16 v[94:97], v[154:157], v[202:205], v[94:97]
	v_mfma_f32_16x16x32_bf16 v[90:93], v[162:165], v[202:205], v[90:93]
	v_mfma_f32_16x16x32_bf16 v[78:81], v[154:157], v[210:213], v[78:81]
	v_mfma_f32_16x16x32_bf16 v[74:77], v[162:165], v[210:213], v[74:77]
	v_mfma_f32_16x16x32_bf16 v[126:129], v[158:161], v[190:193], v[126:129]
	v_mfma_f32_16x16x32_bf16 v[122:125], v[166:169], v[190:193], v[122:125]
	v_mfma_f32_16x16x32_bf16 v[110:113], v[158:161], v[198:201], v[110:113]
	v_mfma_f32_16x16x32_bf16 v[106:109], v[166:169], v[198:201], v[106:109]
	v_mfma_f32_16x16x32_bf16 v[94:97], v[158:161], v[206:209], v[94:97]
	v_mfma_f32_16x16x32_bf16 v[90:93], v[166:169], v[206:209], v[90:93]
	v_mfma_f32_16x16x32_bf16 v[78:81], v[158:161], v[214:217], v[78:81]
	v_mfma_f32_16x16x32_bf16 v[74:77], v[166:169], v[214:217], v[74:77]
	v_mfma_f32_16x16x32_bf16 v[118:121], v[170:173], v[186:189], v[118:121]
	v_mfma_f32_16x16x32_bf16 v[114:117], v[178:181], v[186:189], v[114:117]
	v_mfma_f32_16x16x32_bf16 v[102:105], v[170:173], v[194:197], v[102:105]
	v_mfma_f32_16x16x32_bf16 v[98:101], v[178:181], v[194:197], v[98:101]
	v_mfma_f32_16x16x32_bf16 v[86:89], v[170:173], v[202:205], v[86:89]
	v_mfma_f32_16x16x32_bf16 v[82:85], v[178:181], v[202:205], v[82:85]
	v_mfma_f32_16x16x32_bf16 v[70:73], v[170:173], v[210:213], v[70:73]
	v_mfma_f32_16x16x32_bf16 v[66:69], v[178:181], v[210:213], v[66:69]
	v_mfma_f32_16x16x32_bf16 v[118:121], v[174:177], v[190:193], v[118:121]
	v_mfma_f32_16x16x32_bf16 v[114:117], v[182:185], v[190:193], v[114:117]
	v_mfma_f32_16x16x32_bf16 v[102:105], v[174:177], v[198:201], v[102:105]
	v_mfma_f32_16x16x32_bf16 v[98:101], v[182:185], v[198:201], v[98:101]
	v_mfma_f32_16x16x32_bf16 v[86:89], v[174:177], v[206:209], v[86:89]
	v_mfma_f32_16x16x32_bf16 v[82:85], v[182:185], v[206:209], v[82:85]
	v_mfma_f32_16x16x32_bf16 v[70:73], v[174:177], v[214:217], v[70:73]
	v_mfma_f32_16x16x32_bf16 v[66:69], v[182:185], v[214:217], v[66:69]
	s_barrier
	s_add_i32 s28, s51, s13
	s_mov_b32 m0, s28
	ds_read_b128 v[186:189], v152 offset:49152
	ds_read_b128 v[190:193], v152 offset:50176
	ds_read_b128 v[194:197], v152 offset:51200
	ds_read_b128 v[198:201], v152 offset:52224
	ds_read_b128 v[202:205], v152 offset:53248
	ds_read_b128 v[206:209], v152 offset:54272
	ds_read_b128 v[210:213], v152 offset:55296
	ds_read_b128 v[214:217], v152 offset:56320
	global_load_lds_dwordx4 v132, s[98:99]
	s_add_i32 m0, s28, 0x2000
	s_add_u32 s26, s26, 0xb0080
	s_addc_u32 s27, s27, 0
	s_add_i32 s28, s52, s13
	global_load_lds_dwordx4 v136, s[98:99]
	s_mov_b32 m0, s28
	s_nop 0
	global_load_lds_dwordx4 v132, s[26:27]
	s_add_i32 m0, s28, 0x2000
	s_nop 0
	global_load_lds_dwordx4 v136, s[26:27]
	s_mov_b32 m0, s42
	s_nop 0
	global_load_lds_dwordx4 v130, s[100:101]
	s_mov_b32 m0, s43
	s_nop 0
	global_load_lds_dwordx4 v134, s[100:101]
	s_waitcnt vmcnt(8)
	s_waitcnt lgkmcnt(0)
	s_barrier
	s_waitcnt lgkmcnt(0)
	v_mfma_f32_16x16x32_bf16 v[62:65], v[154:157], v[186:189], v[62:65]
	v_mfma_f32_16x16x32_bf16 v[58:61], v[162:165], v[186:189], v[58:61]
	v_mfma_f32_16x16x32_bf16 v[46:49], v[154:157], v[194:197], v[46:49]
	v_mfma_f32_16x16x32_bf16 v[42:45], v[162:165], v[194:197], v[42:45]
	v_mfma_f32_16x16x32_bf16 v[30:33], v[154:157], v[202:205], v[30:33]
	v_mfma_f32_16x16x32_bf16 v[26:29], v[162:165], v[202:205], v[26:29]
	v_mfma_f32_16x16x32_bf16 v[14:17], v[154:157], v[210:213], v[14:17]
	v_mfma_f32_16x16x32_bf16 v[10:13], v[162:165], v[210:213], v[10:13]
	v_mfma_f32_16x16x32_bf16 v[62:65], v[158:161], v[190:193], v[62:65]
	v_mfma_f32_16x16x32_bf16 v[58:61], v[166:169], v[190:193], v[58:61]
	v_mfma_f32_16x16x32_bf16 v[46:49], v[158:161], v[198:201], v[46:49]
	v_mfma_f32_16x16x32_bf16 v[42:45], v[166:169], v[198:201], v[42:45]
	v_mfma_f32_16x16x32_bf16 v[30:33], v[158:161], v[206:209], v[30:33]
	v_mfma_f32_16x16x32_bf16 v[26:29], v[166:169], v[206:209], v[26:29]
	v_mfma_f32_16x16x32_bf16 v[14:17], v[158:161], v[214:217], v[14:17]
	v_mfma_f32_16x16x32_bf16 v[10:13], v[166:169], v[214:217], v[10:13]
	v_mfma_f32_16x16x32_bf16 v[54:57], v[170:173], v[186:189], v[54:57]
	v_mfma_f32_16x16x32_bf16 v[50:53], v[178:181], v[186:189], v[50:53]
	v_mfma_f32_16x16x32_bf16 v[38:41], v[170:173], v[194:197], v[38:41]
	v_mfma_f32_16x16x32_bf16 v[34:37], v[178:181], v[194:197], v[34:37]
	v_mfma_f32_16x16x32_bf16 v[22:25], v[170:173], v[202:205], v[22:25]
	v_mfma_f32_16x16x32_bf16 v[18:21], v[178:181], v[202:205], v[18:21]
	v_mfma_f32_16x16x32_bf16 v[6:9], v[170:173], v[210:213], v[6:9]
	v_mfma_f32_16x16x32_bf16 v[2:5], v[178:181], v[210:213], v[2:5]
	v_mfma_f32_16x16x32_bf16 v[54:57], v[174:177], v[190:193], v[54:57]
	v_mfma_f32_16x16x32_bf16 v[50:53], v[182:185], v[190:193], v[50:53]
	v_mfma_f32_16x16x32_bf16 v[38:41], v[174:177], v[198:201], v[38:41]
	v_mfma_f32_16x16x32_bf16 v[34:37], v[182:185], v[198:201], v[34:37]
	v_mfma_f32_16x16x32_bf16 v[22:25], v[174:177], v[206:209], v[22:25]
	v_mfma_f32_16x16x32_bf16 v[18:21], v[182:185], v[206:209], v[18:21]
	v_mfma_f32_16x16x32_bf16 v[6:9], v[174:177], v[214:217], v[6:9]
	v_mfma_f32_16x16x32_bf16 v[2:5], v[182:185], v[214:217], v[2:5]
	s_barrier
	s_add_i32 s50, s50, 2
	s_add_u32 s24, s24, 0x100
	s_addc_u32 s25, s25, 0
	s_cmp_gt_u32 s50, 41
	s_cbranch_scc0 .LBB0_1894
	s_add_u32 s24, s48, 0xffffff00
	s_addc_u32 s25, s49, -1
	s_and_b64 vcc, exec, s[6:7]
	s_cbranch_vccnz .LBB0_1897
	v_mov_b32_e32 v2, 0
	s_mov_b32 s16, s46
	s_mov_b32 s31, s47
	s_mov_b64 s[18:19], s[22:23]
	s_mov_b32 s41, s2
	v_mov_b32_e32 v3, v2
	v_mov_b32_e32 v4, v2
	v_mov_b32_e32 v5, v2
	v_mov_b32_e32 v6, v2
	v_mov_b32_e32 v7, v2
	v_mov_b32_e32 v8, v2
	v_mov_b32_e32 v9, v2
	v_mov_b32_e32 v18, v2
	v_mov_b32_e32 v19, v2
	v_mov_b32_e32 v20, v2
	v_mov_b32_e32 v21, v2
	v_mov_b32_e32 v22, v2
	v_mov_b32_e32 v23, v2
	v_mov_b32_e32 v24, v2
	v_mov_b32_e32 v25, v2
	v_mov_b32_e32 v34, v2
	v_mov_b32_e32 v35, v2
	v_mov_b32_e32 v36, v2
	v_mov_b32_e32 v37, v2
	v_mov_b32_e32 v38, v2
	v_mov_b32_e32 v39, v2
	v_mov_b32_e32 v40, v2
	v_mov_b32_e32 v41, v2
	v_mov_b32_e32 v50, v2
	v_mov_b32_e32 v51, v2
	v_mov_b32_e32 v52, v2
	v_mov_b32_e32 v53, v2
	v_mov_b32_e32 v54, v2
	v_mov_b32_e32 v55, v2
	v_mov_b32_e32 v56, v2
	v_mov_b32_e32 v57, v2
	v_mov_b32_e32 v10, v2
	v_mov_b32_e32 v11, v2
	v_mov_b32_e32 v12, v2
	v_mov_b32_e32 v13, v2
	v_mov_b32_e32 v14, v2
	v_mov_b32_e32 v15, v2
	v_mov_b32_e32 v16, v2
	v_mov_b32_e32 v17, v2
	v_mov_b32_e32 v26, v2
	v_mov_b32_e32 v27, v2
	v_mov_b32_e32 v28, v2
	v_mov_b32_e32 v29, v2
	v_mov_b32_e32 v30, v2
	v_mov_b32_e32 v31, v2
	v_mov_b32_e32 v32, v2
	v_mov_b32_e32 v33, v2
	v_mov_b32_e32 v42, v2
	v_mov_b32_e32 v43, v2
	v_mov_b32_e32 v44, v2
	v_mov_b32_e32 v45, v2
	v_mov_b32_e32 v46, v2
	v_mov_b32_e32 v47, v2
	v_mov_b32_e32 v48, v2
	v_mov_b32_e32 v49, v2
	v_mov_b32_e32 v58, v2
	v_mov_b32_e32 v59, v2
	v_mov_b32_e32 v60, v2
	v_mov_b32_e32 v61, v2
	v_mov_b32_e32 v62, v2
	v_mov_b32_e32 v63, v2
	v_mov_b32_e32 v64, v2
	v_mov_b32_e32 v65, v2
	v_mov_b32_e32 v66, v2
	v_mov_b32_e32 v67, v2
	v_mov_b32_e32 v68, v2
	v_mov_b32_e32 v69, v2
	v_mov_b32_e32 v70, v2
	v_mov_b32_e32 v71, v2
	v_mov_b32_e32 v72, v2
	v_mov_b32_e32 v73, v2
	v_mov_b32_e32 v82, v2
	v_mov_b32_e32 v83, v2
	v_mov_b32_e32 v84, v2
	v_mov_b32_e32 v85, v2
	v_mov_b32_e32 v86, v2
	v_mov_b32_e32 v87, v2
	v_mov_b32_e32 v88, v2
	v_mov_b32_e32 v89, v2
	v_mov_b32_e32 v98, v2
	v_mov_b32_e32 v99, v2
	v_mov_b32_e32 v100, v2
	v_mov_b32_e32 v101, v2
	v_mov_b32_e32 v102, v2
	v_mov_b32_e32 v103, v2
	v_mov_b32_e32 v104, v2
	v_mov_b32_e32 v105, v2
	v_mov_b32_e32 v114, v2
	v_mov_b32_e32 v115, v2
	v_mov_b32_e32 v116, v2
	v_mov_b32_e32 v117, v2
	v_mov_b32_e32 v118, v2
	v_mov_b32_e32 v119, v2
	v_mov_b32_e32 v120, v2
	v_mov_b32_e32 v121, v2
	v_mov_b32_e32 v74, v2
	v_mov_b32_e32 v75, v2
	v_mov_b32_e32 v76, v2
	v_mov_b32_e32 v77, v2
	v_mov_b32_e32 v78, v2
	v_mov_b32_e32 v79, v2
	v_mov_b32_e32 v80, v2
	v_mov_b32_e32 v81, v2
	v_mov_b32_e32 v90, v2
	v_mov_b32_e32 v91, v2
	v_mov_b32_e32 v92, v2
	v_mov_b32_e32 v93, v2
	v_mov_b32_e32 v94, v2
	v_mov_b32_e32 v95, v2
	v_mov_b32_e32 v96, v2
	v_mov_b32_e32 v97, v2
	v_mov_b32_e32 v106, v2
	v_mov_b32_e32 v107, v2
	v_mov_b32_e32 v108, v2
	v_mov_b32_e32 v109, v2
	v_mov_b32_e32 v110, v2
	v_mov_b32_e32 v111, v2
	v_mov_b32_e32 v112, v2
	v_mov_b32_e32 v113, v2
	v_mov_b32_e32 v122, v2
	v_mov_b32_e32 v123, v2
	v_mov_b32_e32 v124, v2
	v_mov_b32_e32 v125, v2
	v_mov_b32_e32 v126, v2
	v_mov_b32_e32 v127, v2
	v_mov_b32_e32 v128, v2
	v_mov_b32_e32 v129, v2
	s_andn2_b64 vcc, exec, s[4:5]
	s_cbranch_vccnz .LBB0_1898
	s_branch .LBB0_1899

.LBB0_2031:
	ds_read_b128 v[36:39], v203
	ds_read_b128 v[44:47], v203 offset:1024
	ds_read_b128 v[48:51], v203 offset:2048
	ds_read_b128 v[56:59], v203 offset:3072
	ds_read_b128 v[144:147], v207
	ds_read_b128 v[148:151], v207 offset:1024
	ds_read_b128 v[152:155], v207 offset:2048
	ds_read_b128 v[156:159], v207 offset:3072
	s_add_u32 s34, s30, 0xfffc0080
	s_addc_u32 s35, s31, -1
	s_cmp_eq_u32 s63, 12
	s_cselect_b32 s39, s14, s35
	s_cselect_b32 s38, s15, s34
	s_cselect_b32 s35, s21, s62
	s_cselect_b32 s34, s23, s61
	s_add_i32 m0, s29, 0xc000
	ds_read_b128 v[172:175], v209
	ds_read_b128 v[176:179], v209 offset:1024
	ds_read_b128 v[180:183], v209 offset:2048
	ds_read_b128 v[184:187], v209 offset:3072
	ds_read_b128 v[188:191], v209 offset:4096
	ds_read_b128 v[192:195], v209 offset:5120
	ds_read_b128 v[196:199], v209 offset:6144
	ds_read_b128 v[214:217], v209 offset:7168
	global_load_lds_dwordx4 v168, s[30:31]
	s_add_i32 m0, s29, 0xe000
	s_nop 0
	global_load_lds_dwordx4 v170, s[30:31]
	s_waitcnt vmcnt(8)
	s_waitcnt lgkmcnt(0)
	s_barrier
	s_waitcnt lgkmcnt(0)
	v_mfma_f32_16x16x32_bf16 v[140:143], v[36:39], v[172:175], v[140:143]
	v_mfma_f32_16x16x32_bf16 v[136:139], v[48:51], v[172:175], v[136:139]
	v_mfma_f32_16x16x32_bf16 v[124:127], v[36:39], v[180:183], v[124:127]
	v_mfma_f32_16x16x32_bf16 v[120:123], v[48:51], v[180:183], v[120:123]
	v_mfma_f32_16x16x32_bf16 v[108:111], v[36:39], v[188:191], v[108:111]
	v_mfma_f32_16x16x32_bf16 v[104:107], v[48:51], v[188:191], v[104:107]
	v_mfma_f32_16x16x32_bf16 v[92:95], v[36:39], v[196:199], v[92:95]
	v_mfma_f32_16x16x32_bf16 v[88:91], v[48:51], v[196:199], v[88:91]
	v_mfma_f32_16x16x32_bf16 v[140:143], v[44:47], v[176:179], v[140:143]
	v_mfma_f32_16x16x32_bf16 v[136:139], v[56:59], v[176:179], v[136:139]
	v_mfma_f32_16x16x32_bf16 v[124:127], v[44:47], v[184:187], v[124:127]
	v_mfma_f32_16x16x32_bf16 v[120:123], v[56:59], v[184:187], v[120:123]
	v_mfma_f32_16x16x32_bf16 v[108:111], v[44:47], v[192:195], v[108:111]
	v_mfma_f32_16x16x32_bf16 v[104:107], v[56:59], v[192:195], v[104:107]
	v_mfma_f32_16x16x32_bf16 v[92:95], v[44:47], v[214:217], v[92:95]
	v_mfma_f32_16x16x32_bf16 v[88:91], v[56:59], v[214:217], v[88:91]
	v_mfma_f32_16x16x32_bf16 v[132:135], v[144:147], v[172:175], v[132:135]
	v_mfma_f32_16x16x32_bf16 v[128:131], v[152:155], v[172:175], v[128:131]
	v_mfma_f32_16x16x32_bf16 v[116:119], v[144:147], v[180:183], v[116:119]
	v_mfma_f32_16x16x32_bf16 v[112:115], v[152:155], v[180:183], v[112:115]
	v_mfma_f32_16x16x32_bf16 v[100:103], v[144:147], v[188:191], v[100:103]
	v_mfma_f32_16x16x32_bf16 v[96:99], v[152:155], v[188:191], v[96:99]
	v_mfma_f32_16x16x32_bf16 v[84:87], v[144:147], v[196:199], v[84:87]
	v_mfma_f32_16x16x32_bf16 v[80:83], v[152:155], v[196:199], v[80:83]
	v_mfma_f32_16x16x32_bf16 v[132:135], v[148:151], v[176:179], v[132:135]
	v_mfma_f32_16x16x32_bf16 v[128:131], v[156:159], v[176:179], v[128:131]
	v_mfma_f32_16x16x32_bf16 v[116:119], v[148:151], v[184:187], v[116:119]
	v_mfma_f32_16x16x32_bf16 v[112:115], v[156:159], v[184:187], v[112:115]
	v_mfma_f32_16x16x32_bf16 v[100:103], v[148:151], v[192:195], v[100:103]
	v_mfma_f32_16x16x32_bf16 v[96:99], v[156:159], v[192:195], v[96:99]
	v_mfma_f32_16x16x32_bf16 v[84:87], v[148:151], v[214:217], v[84:87]
	v_mfma_f32_16x16x32_bf16 v[80:83], v[156:159], v[214:217], v[80:83]
	s_barrier
	s_add_i32 s64, s55, s42
	s_add_u32 s98, s34, s16
	s_addc_u32 s99, s35, s17
	s_mov_b32 m0, s64
	ds_read_b128 v[172:175], v209 offset:16384
	ds_read_b128 v[176:179], v209 offset:17408
	ds_read_b128 v[180:183], v209 offset:18432
	ds_read_b128 v[184:187], v209 offset:19456
	ds_read_b128 v[188:191], v209 offset:20480
	ds_read_b128 v[192:195], v209 offset:21504
	ds_read_b128 v[196:199], v209 offset:22528
	ds_read_b128 v[214:217], v209 offset:23552
	global_load_lds_dwordx4 v162, s[34:35]
	s_add_i32 m0, s64, 0x2000
	s_add_u32 s64, s34, 0x40000
	s_addc_u32 s65, s35, 0
	s_add_i32 s66, s56, s42
	global_load_lds_dwordx4 v166, s[34:35]
	s_mov_b32 m0, s66
	s_nop 0
	global_load_lds_dwordx4 v162, s[64:65]
	s_add_i32 m0, s66, 0x2000
	s_nop 0
	global_load_lds_dwordx4 v166, s[64:65]
	s_add_u32 s100, s38, s16
	s_addc_u32 s101, s39, s17
	s_mov_b32 m0, s29
	s_nop 0
	global_load_lds_dwordx4 v160, s[38:39]
	s_mov_b32 m0, s43
	s_nop 0
	global_load_lds_dwordx4 v164, s[38:39]
	s_waitcnt vmcnt(8)
	s_waitcnt lgkmcnt(0)
	s_barrier
	s_waitcnt lgkmcnt(0)
	v_mfma_f32_16x16x32_bf16 v[76:79], v[36:39], v[172:175], v[76:79]
	v_mfma_f32_16x16x32_bf16 v[72:75], v[48:51], v[172:175], v[72:75]
	v_mfma_f32_16x16x32_bf16 v[60:63], v[36:39], v[180:183], v[60:63]
	v_mfma_f32_16x16x32_bf16 v[52:55], v[48:51], v[180:183], v[52:55]
	v_mfma_f32_16x16x32_bf16 v[28:31], v[36:39], v[188:191], v[28:31]
	v_mfma_f32_16x16x32_bf16 v[24:27], v[48:51], v[188:191], v[24:27]
	v_mfma_f32_16x16x32_bf16 v[12:15], v[36:39], v[196:199], v[12:15]
	v_mfma_f32_16x16x32_bf16 v[8:11], v[48:51], v[196:199], v[8:11]
	v_mfma_f32_16x16x32_bf16 v[76:79], v[44:47], v[176:179], v[76:79]
	v_mfma_f32_16x16x32_bf16 v[72:75], v[56:59], v[176:179], v[72:75]
	v_mfma_f32_16x16x32_bf16 v[60:63], v[44:47], v[184:187], v[60:63]
	v_mfma_f32_16x16x32_bf16 v[52:55], v[56:59], v[184:187], v[52:55]
	v_mfma_f32_16x16x32_bf16 v[28:31], v[44:47], v[192:195], v[28:31]
	v_mfma_f32_16x16x32_bf16 v[24:27], v[56:59], v[192:195], v[24:27]
	v_mfma_f32_16x16x32_bf16 v[12:15], v[44:47], v[214:217], v[12:15]
	v_mfma_f32_16x16x32_bf16 v[8:11], v[56:59], v[214:217], v[8:11]
	v_mfma_f32_16x16x32_bf16 v[40:43], v[144:147], v[180:183], v[40:43]
	v_mfma_f32_16x16x32_bf16 v[32:35], v[152:155], v[180:183], v[32:35]
	v_mfma_f32_16x16x32_bf16 v[20:23], v[144:147], v[188:191], v[20:23]
	v_mfma_f32_16x16x32_bf16 v[16:19], v[152:155], v[188:191], v[16:19]
	v_mfma_f32_16x16x32_bf16 v[4:7], v[144:147], v[196:199], v[4:7]
	v_mfma_f32_16x16x32_bf16 v[0:3], v[152:155], v[196:199], v[0:3]
	v_mfma_f32_16x16x32_bf16 v[36:39], v[144:147], v[172:175], v[68:71]
	v_mfma_f32_16x16x32_bf16 v[44:47], v[152:155], v[172:175], v[64:67]
	v_mfma_f32_16x16x32_bf16 v[40:43], v[148:151], v[184:187], v[40:43]
	v_mfma_f32_16x16x32_bf16 v[32:35], v[156:159], v[184:187], v[32:35]
	v_mfma_f32_16x16x32_bf16 v[20:23], v[148:151], v[192:195], v[20:23]
	v_mfma_f32_16x16x32_bf16 v[16:19], v[156:159], v[192:195], v[16:19]
	v_mfma_f32_16x16x32_bf16 v[4:7], v[148:151], v[214:217], v[4:7]
	v_mfma_f32_16x16x32_bf16 v[0:3], v[156:159], v[214:217], v[0:3]
	v_mfma_f32_16x16x32_bf16 v[36:39], v[148:151], v[176:179], v[36:39]
	v_mfma_f32_16x16x32_bf16 v[44:47], v[156:159], v[176:179], v[44:47]
	s_barrier
	s_add_i32 s64, 0, 0x18000
	s_add_i32 s65, 0, 0x1c000
	v_add_u32_e32 v68, s64, v201
	v_add_u32_e32 v156, s65, v201
	ds_read_b128 v[48:51], v68
	ds_read_b128 v[56:59], v68 offset:1024
	ds_read_b128 v[64:67], v68 offset:2048
	ds_read_b128 v[68:71], v68 offset:3072
	ds_read_b128 v[144:147], v156
	ds_read_b128 v[148:151], v156 offset:1024
	ds_read_b128 v[152:155], v156 offset:2048
	ds_read_b128 v[156:159], v156 offset:3072
	s_add_u32 s38, s38, 0x40000
	s_addc_u32 s39, s39, 0
	s_mov_b32 m0, s44
	ds_read_b128 v[172:175], v209 offset:32768
	ds_read_b128 v[176:179], v209 offset:33792
	ds_read_b128 v[180:183], v209 offset:34816
	ds_read_b128 v[184:187], v209 offset:35840
	ds_read_b128 v[188:191], v209 offset:36864
	ds_read_b128 v[192:195], v209 offset:37888
	ds_read_b128 v[196:199], v209 offset:38912
	ds_read_b128 v[214:217], v209 offset:39936
	global_load_lds_dwordx4 v160, s[38:39]
	s_mov_b32 m0, s45
	s_nop 0
	global_load_lds_dwordx4 v164, s[38:39]
	s_waitcnt vmcnt(8)
	s_waitcnt lgkmcnt(0)
	s_barrier
	s_waitcnt lgkmcnt(0)
	v_mfma_f32_16x16x32_bf16 v[140:143], v[48:51], v[172:175], v[140:143]
	v_mfma_f32_16x16x32_bf16 v[136:139], v[64:67], v[172:175], v[136:139]
	v_mfma_f32_16x16x32_bf16 v[124:127], v[48:51], v[180:183], v[124:127]
	v_mfma_f32_16x16x32_bf16 v[120:123], v[64:67], v[180:183], v[120:123]
	v_mfma_f32_16x16x32_bf16 v[108:111], v[48:51], v[188:191], v[108:111]
	v_mfma_f32_16x16x32_bf16 v[104:107], v[64:67], v[188:191], v[104:107]
	v_mfma_f32_16x16x32_bf16 v[92:95], v[48:51], v[196:199], v[92:95]
	v_mfma_f32_16x16x32_bf16 v[88:91], v[64:67], v[196:199], v[88:91]
	v_mfma_f32_16x16x32_bf16 v[140:143], v[56:59], v[176:179], v[140:143]
	v_mfma_f32_16x16x32_bf16 v[136:139], v[68:71], v[176:179], v[136:139]
	v_mfma_f32_16x16x32_bf16 v[124:127], v[56:59], v[184:187], v[124:127]
	v_mfma_f32_16x16x32_bf16 v[120:123], v[68:71], v[184:187], v[120:123]
	v_mfma_f32_16x16x32_bf16 v[108:111], v[56:59], v[192:195], v[108:111]
	v_mfma_f32_16x16x32_bf16 v[104:107], v[68:71], v[192:195], v[104:107]
	v_mfma_f32_16x16x32_bf16 v[92:95], v[56:59], v[214:217], v[92:95]
	v_mfma_f32_16x16x32_bf16 v[88:91], v[68:71], v[214:217], v[88:91]
	v_mfma_f32_16x16x32_bf16 v[132:135], v[144:147], v[172:175], v[132:135]
	v_mfma_f32_16x16x32_bf16 v[128:131], v[152:155], v[172:175], v[128:131]
	v_mfma_f32_16x16x32_bf16 v[116:119], v[144:147], v[180:183], v[116:119]
	v_mfma_f32_16x16x32_bf16 v[112:115], v[152:155], v[180:183], v[112:115]
	v_mfma_f32_16x16x32_bf16 v[100:103], v[144:147], v[188:191], v[100:103]
	v_mfma_f32_16x16x32_bf16 v[96:99], v[152:155], v[188:191], v[96:99]
	v_mfma_f32_16x16x32_bf16 v[84:87], v[144:147], v[196:199], v[84:87]
	v_mfma_f32_16x16x32_bf16 v[80:83], v[152:155], v[196:199], v[80:83]
	v_mfma_f32_16x16x32_bf16 v[132:135], v[148:151], v[176:179], v[132:135]
	v_mfma_f32_16x16x32_bf16 v[128:131], v[156:159], v[176:179], v[128:131]
	v_mfma_f32_16x16x32_bf16 v[116:119], v[148:151], v[184:187], v[116:119]
	v_mfma_f32_16x16x32_bf16 v[112:115], v[156:159], v[184:187], v[112:115]
	v_mfma_f32_16x16x32_bf16 v[100:103], v[148:151], v[192:195], v[100:103]
	v_mfma_f32_16x16x32_bf16 v[96:99], v[156:159], v[192:195], v[96:99]
	v_mfma_f32_16x16x32_bf16 v[84:87], v[148:151], v[214:217], v[84:87]
	v_mfma_f32_16x16x32_bf16 v[80:83], v[156:159], v[214:217], v[80:83]
	s_barrier
	s_add_i32 s38, s64, s42
	s_mov_b32 m0, s38
	ds_read_b128 v[172:175], v209 offset:49152
	ds_read_b128 v[176:179], v209 offset:50176
	ds_read_b128 v[180:183], v209 offset:51200
	ds_read_b128 v[184:187], v209 offset:52224
	ds_read_b128 v[188:191], v209 offset:53248
	ds_read_b128 v[192:195], v209 offset:54272
	ds_read_b128 v[196:199], v209 offset:55296
	ds_read_b128 v[214:217], v209 offset:56320
	global_load_lds_dwordx4 v162, s[98:99]
	s_add_i32 m0, s38, 0x2000
	s_add_u32 s34, s34, 0x40080
	s_addc_u32 s35, s35, 0
	s_add_i32 s38, s65, s42
	global_load_lds_dwordx4 v166, s[98:99]
	s_mov_b32 m0, s38
	s_nop 0
	global_load_lds_dwordx4 v162, s[34:35]
	s_add_i32 m0, s38, 0x2000
	s_nop 0
	global_load_lds_dwordx4 v166, s[34:35]
	s_mov_b32 m0, s50
	s_nop 0
	global_load_lds_dwordx4 v160, s[100:101]
	s_mov_b32 m0, s51
	s_nop 0
	global_load_lds_dwordx4 v164, s[100:101]
	s_waitcnt vmcnt(8)
	s_waitcnt lgkmcnt(0)
	s_barrier
	s_waitcnt lgkmcnt(0)
	v_mfma_f32_16x16x32_bf16 v[76:79], v[48:51], v[172:175], v[76:79]
	v_mfma_f32_16x16x32_bf16 v[72:75], v[64:67], v[172:175], v[72:75]
	v_mfma_f32_16x16x32_bf16 v[60:63], v[48:51], v[180:183], v[60:63]
	v_mfma_f32_16x16x32_bf16 v[52:55], v[64:67], v[180:183], v[52:55]
	v_mfma_f32_16x16x32_bf16 v[28:31], v[48:51], v[188:191], v[28:31]
	v_mfma_f32_16x16x32_bf16 v[24:27], v[64:67], v[188:191], v[24:27]
	v_mfma_f32_16x16x32_bf16 v[12:15], v[48:51], v[196:199], v[12:15]
	v_mfma_f32_16x16x32_bf16 v[8:11], v[64:67], v[196:199], v[8:11]
	v_mfma_f32_16x16x32_bf16 v[76:79], v[56:59], v[176:179], v[76:79]
	v_mfma_f32_16x16x32_bf16 v[72:75], v[68:71], v[176:179], v[72:75]
	v_mfma_f32_16x16x32_bf16 v[60:63], v[56:59], v[184:187], v[60:63]
	v_mfma_f32_16x16x32_bf16 v[52:55], v[68:71], v[184:187], v[52:55]
	v_mfma_f32_16x16x32_bf16 v[28:31], v[56:59], v[192:195], v[28:31]
	v_mfma_f32_16x16x32_bf16 v[24:27], v[68:71], v[192:195], v[24:27]
	v_mfma_f32_16x16x32_bf16 v[12:15], v[56:59], v[214:217], v[12:15]
	v_mfma_f32_16x16x32_bf16 v[8:11], v[68:71], v[214:217], v[8:11]
	v_mfma_f32_16x16x32_bf16 v[36:39], v[144:147], v[172:175], v[36:39]
	v_mfma_f32_16x16x32_bf16 v[68:71], v[148:151], v[176:179], v[36:39]
	v_mfma_f32_16x16x32_bf16 v[36:39], v[152:155], v[172:175], v[44:47]
	v_mfma_f32_16x16x32_bf16 v[64:67], v[156:159], v[176:179], v[36:39]
	v_mfma_f32_16x16x32_bf16 v[36:39], v[144:147], v[180:183], v[40:43]
	v_mfma_f32_16x16x32_bf16 v[32:35], v[152:155], v[180:183], v[32:35]
	v_mfma_f32_16x16x32_bf16 v[20:23], v[144:147], v[188:191], v[20:23]
	v_mfma_f32_16x16x32_bf16 v[16:19], v[152:155], v[188:191], v[16:19]
	v_mfma_f32_16x16x32_bf16 v[4:7], v[144:147], v[196:199], v[4:7]
	v_mfma_f32_16x16x32_bf16 v[0:3], v[152:155], v[196:199], v[0:3]
	v_mfma_f32_16x16x32_bf16 v[40:43], v[148:151], v[184:187], v[36:39]
	v_mfma_f32_16x16x32_bf16 v[32:35], v[156:159], v[184:187], v[32:35]
	v_mfma_f32_16x16x32_bf16 v[20:23], v[148:151], v[192:195], v[20:23]
	v_mfma_f32_16x16x32_bf16 v[16:19], v[156:159], v[192:195], v[16:19]
	v_mfma_f32_16x16x32_bf16 v[4:7], v[148:151], v[214:217], v[4:7]
	v_mfma_f32_16x16x32_bf16 v[0:3], v[156:159], v[214:217], v[0:3]
	s_barrier
	s_add_i32 s63, s63, 2
	s_add_u32 s30, s30, 0x100
	s_addc_u32 s31, s31, 0
	s_add_u32 s61, s61, 0x100
	s_addc_u32 s62, s62, 0
	s_cmp_gt_u32 s63, 13
	s_cbranch_scc0 .LBB0_2031
	s_lshl_b32 s2, s2, 8
	v_mov_b32_e32 v154, v229
	v_mov_b32_e32 v155, v231
	s_or_b32 s2, s2, s49
	s_mov_b64 s[34:35], s[26:27]
	v_lshl_add_u32 v144, v155, 3, s2
	v_ashrrev_i32_e32 v145, 31, v144
	v_lshlrev_b64 v[188:189], 2, v[144:145]
	v_lshl_add_u64 v[150:151], s[4:5], 0, v[188:189]
	global_load_dwordx4 v[36:39], v[150:151], off offset:16
	global_load_dwordx4 v[44:47], v[150:151], off
	v_lshl_add_u64 v[152:153], s[6:7], 0, v[188:189]
	global_load_dwordx4 v[48:51], v[152:153], off offset:16
	global_load_dwordx4 v[56:59], v[152:153], off
	s_lshl_b32 s2, s28, 8
	s_add_i32 s2, s2, s48
	s_mov_b32 s28, s22
	s_mov_b64 s[30:31], s[24:25]
	s_waitcnt vmcnt(0)
	v_pk_mul_f32 v[184:185], v[38:39], s[18:19] op_sel_hi:[1,0]
	v_pk_mul_f32 v[186:187], v[36:37], s[18:19] op_sel_hi:[1,0]
	global_load_dwordx4 v[146:149], v[150:151], off offset:528
	global_load_dwordx4 v[36:39], v[150:151], off offset:512
	v_pk_mul_f32 v[190:191], v[46:47], s[18:19] op_sel_hi:[1,0]
	v_pk_mul_f32 v[192:193], v[44:45], s[18:19] op_sel_hi:[1,0]
	s_waitcnt vmcnt(1)
	v_pk_mul_f32 v[176:177], v[148:149], s[18:19] op_sel_hi:[1,0]
	v_pk_mul_f32 v[178:179], v[146:147], s[18:19] op_sel_hi:[1,0]
	v_add_u32_e32 v146, s2, v154
	v_lshlrev_b32_e32 v148, 2, v155
	v_ashrrev_i32_e32 v149, 31, v148
	v_ashrrev_i32_e32 v147, 31, v146
	v_lshl_add_u64 v[194:195], v[148:149], 2, s[12:13]
	v_lshl_add_u64 v[148:149], v[146:147], 4, s[10:11]
	s_waitcnt vmcnt(0)
	v_pk_mul_f32 v[180:181], v[38:39], s[18:19] op_sel_hi:[1,0]
	v_pk_mul_f32 v[182:183], v[36:37], s[18:19] op_sel_hi:[1,0]
	global_load_dwordx4 v[36:39], v[152:153], off offset:528
	global_load_dwordx4 v[44:47], v[152:153], off offset:512
	v_lshlrev_b64 v[152:153], 6, v[146:147]
	global_load_dwordx4 v[148:151], v[148:149], off
	v_lshl_add_u64 v[152:153], v[194:195], 0, v[152:153]
	global_load_dwordx4 v[152:155], v[152:153], off
	v_add_u32_e32 v238, 16, v146
	v_ashrrev_i32_e32 v239, 31, v238
	v_lshl_add_u64 v[156:157], v[238:239], 4, s[10:11]
	global_load_dwordx4 v[156:159], v[156:157], off
	v_lshlrev_b64 v[172:173], 6, v[238:239]
	v_lshl_add_u64 v[172:173], v[194:195], 0, v[172:173]
	global_load_dwordx4 v[214:217], v[172:173], off
	v_add_u32_e32 v232, 32, v146
	v_ashrrev_i32_e32 v233, 31, v232
	v_lshl_add_u64 v[172:173], v[232:233], 4, s[10:11]
	global_load_dwordx4 v[218:221], v[172:173], off
	v_lshlrev_b64 v[172:173], 6, v[232:233]
	v_lshl_add_u64 v[172:173], v[194:195], 0, v[172:173]
	global_load_dwordx4 v[222:225], v[172:173], off
	v_add_u32_e32 v226, 48, v146
	v_ashrrev_i32_e32 v227, 31, v226
	v_lshl_add_u64 v[172:173], v[226:227], 4, s[10:11]
	global_load_dwordx4 v[244:247], v[172:173], off
	v_lshlrev_b64 v[172:173], 6, v[226:227]
	v_lshl_add_u64 v[172:173], v[194:195], 0, v[172:173]
	global_load_dwordx4 v[248:251], v[172:173], off
	v_add_u32_e32 v210, 0x90, v146
	v_ashrrev_i32_e32 v211, 31, v210
	v_add_u32_e32 v204, 0xa0, v146
	v_ashrrev_i32_e32 v205, 31, v204
	v_add_u32_e32 v198, 0xb0, v146
	v_ashrrev_i32_e32 v199, 31, v198
	v_lshlrev_b64 v[196:197], 6, v[198:199]
	s_mov_b32 s2, s20
	s_waitcnt vmcnt(7)
	v_mov_b32_e32 v172, v149
	v_mov_b32_e32 v173, v150
	v_mov_b32_e32 v149, v151
	v_pk_add_f32 v[148:149], v[172:173], v[148:149]
	v_lshlrev_b64 v[172:173], 6, v[210:211]
	v_add_f32_e32 v148, v148, v149
	v_fmamk_f32 v148, v148, 0x3a800000, v213
	v_rsq_f32_e32 v148, v148
	s_waitcnt vmcnt(6)
	v_add_f32_e32 v149, v154, v155
	v_lshl_add_u64 v[172:173], v[194:195], 0, v[172:173]
	v_mul_f32_e32 v242, 0xbfb8aa3b, v148
	v_add_f32_e32 v148, v152, v153
	v_add_f32_e32 v148, v148, v149
	v_mov_b32_e32 v149, v148
	s_nop 1
	v_permlane16_swap_b32_e32 v148, v149
	v_add_f32_e32 v148, v148, v149
	v_mov_b32_e32 v149, v148
	s_nop 1
	v_permlane32_swap_b32_e32 v148, v149
	v_add_f32_e32 v148, v148, v149
	v_fmamk_f32 v148, v148, 0x3a800000, v213
	v_rsq_f32_e32 v240, v148
	s_waitcnt vmcnt(5)
	v_mov_b32_e32 v148, v157
	v_mov_b32_e32 v149, v158
	v_mov_b32_e32 v157, v159
	v_pk_add_f32 v[148:149], v[148:149], v[156:157]
	v_lshl_add_u64 v[156:157], v[210:211], 4, s[10:11]
	v_add_f32_e32 v148, v148, v149
	v_fmamk_f32 v148, v148, 0x3a800000, v213
	v_rsq_f32_e32 v148, v148
	s_waitcnt vmcnt(4)
	v_add_f32_e32 v149, v216, v217
	global_load_dwordx4 v[156:159], v[156:157], off
	v_pk_fma_f32 v[142:143], v[142:143], v[242:243], v[190:191] op_sel_hi:[1,0,1]
	v_mul_f32_e32 v236, 0xbfb8aa3b, v148
	v_add_f32_e32 v148, v214, v215
	v_add_f32_e32 v148, v148, v149
	v_mov_b32_e32 v149, v148
	s_nop 1
	v_permlane16_swap_b32_e32 v148, v149
	v_add_f32_e32 v148, v148, v149
	v_mov_b32_e32 v149, v148
	s_nop 1
	v_permlane32_swap_b32_e32 v148, v149
	v_add_f32_e32 v148, v148, v149
	v_fmamk_f32 v148, v148, 0x3a800000, v213
	v_rsq_f32_e32 v234, v148
	s_waitcnt vmcnt(4)
	v_mov_b32_e32 v148, v219
	v_mov_b32_e32 v149, v220
	v_mov_b32_e32 v219, v221
	v_pk_add_f32 v[148:149], v[148:149], v[218:219]
	v_add_u32_e32 v220, 0x80, v146
	v_add_f32_e32 v148, v148, v149
	v_fmamk_f32 v148, v148, 0x3a800000, v213
	v_rsq_f32_e32 v148, v148
	s_waitcnt vmcnt(3)
	v_add_f32_e32 v149, v224, v225
	v_ashrrev_i32_e32 v221, 31, v220
	v_lshlrev_b64 v[152:153], 6, v[220:221]
	v_mul_f32_e32 v230, 0xbfb8aa3b, v148
	v_add_f32_e32 v148, v222, v223
	v_add_f32_e32 v148, v148, v149
	v_mov_b32_e32 v149, v148
	s_nop 1
	v_permlane16_swap_b32_e32 v148, v149
	v_add_f32_e32 v148, v148, v149
	v_mov_b32_e32 v149, v148
	s_nop 1
	v_permlane32_swap_b32_e32 v148, v149
	v_add_f32_e32 v148, v148, v149
	v_fmamk_f32 v148, v148, 0x3a800000, v213
	v_rsq_f32_e32 v228, v148
	s_waitcnt vmcnt(2)
	v_mov_b32_e32 v148, v245
	v_mov_b32_e32 v149, v246
	v_mov_b32_e32 v245, v247
	v_pk_add_f32 v[148:149], v[148:149], v[244:245]
	v_lshl_add_u64 v[152:153], v[194:195], 0, v[152:153]
	v_add_f32_e32 v148, v148, v149
	v_fmamk_f32 v148, v148, 0x3a800000, v213
	v_rsq_f32_e32 v148, v148
	s_waitcnt vmcnt(1)
	v_add_f32_e32 v149, v250, v251
	global_load_dwordx4 v[152:155], v[152:153], off
	v_pk_fma_f32 v[140:141], v[140:141], v[242:243], v[192:193] op_sel_hi:[1,0,1]
	v_mul_f32_e32 v224, 0xbfb8aa3b, v148
	v_add_f32_e32 v148, v248, v249
	v_add_f32_e32 v148, v148, v149
	v_mov_b32_e32 v149, v148
	s_nop 1
	v_permlane16_swap_b32_e32 v148, v149
	v_add_f32_e32 v148, v148, v149
	v_mov_b32_e32 v149, v148
	s_nop 1
	v_permlane32_swap_b32_e32 v148, v149
	v_add_f32_e32 v148, v148, v149
	v_fmamk_f32 v148, v148, 0x3a800000, v213
	v_rsq_f32_e32 v222, v148
	v_lshl_add_u64 v[148:149], v[220:221], 4, s[10:11]
	global_load_dwordx4 v[148:151], v[148:149], off
	v_exp_f32_e32 v142, v142
	global_load_dwordx4 v[216:219], v[172:173], off
	v_lshl_add_u64 v[172:173], v[204:205], 4, s[10:11]
	global_load_dwordx4 v[244:247], v[172:173], off
	v_lshlrev_b64 v[172:173], 6, v[204:205]
	v_lshl_add_u64 v[172:173], v[194:195], 0, v[172:173]
	global_load_dwordx4 v[248:251], v[172:173], off
	v_lshl_add_u64 v[194:195], v[194:195], 0, v[196:197]
	global_load_dwordx4 v[194:197], v[194:195], off
	v_lshl_add_u64 v[172:173], v[198:199], 4, s[10:11]
	global_load_dwordx4 v[172:175], v[172:173], off
	v_exp_f32_e32 v143, v143
	v_exp_f32_e32 v140, v140
	v_exp_f32_e32 v141, v141
	v_pk_fma_f32 v[138:139], v[138:139], v[242:243], v[184:185] op_sel_hi:[1,0,1]
	v_pk_add_f32 v[142:143], v[142:143], 1.0 op_sel_hi:[1,0]
	v_exp_f32_e32 v138, v138
	v_exp_f32_e32 v139, v139
	v_pk_fma_f32 v[136:137], v[136:137], v[242:243], v[186:187] op_sel_hi:[1,0,1]
	v_pk_add_f32 v[140:141], v[140:141], 1.0 op_sel_hi:[1,0]
	v_rcp_f32_e32 v142, v142
	v_rcp_f32_e32 v143, v143
	v_exp_f32_e32 v136, v136
	v_exp_f32_e32 v137, v137
	v_rcp_f32_e32 v140, v140
	v_rcp_f32_e32 v141, v141
	v_pk_add_f32 v[138:139], v[138:139], 1.0 op_sel_hi:[1,0]
	v_pk_add_f32 v[136:137], v[136:137], 1.0 op_sel_hi:[1,0]
	v_rcp_f32_e32 v138, v138
	v_rcp_f32_e32 v139, v139
	v_rcp_f32_e32 v136, v136
	v_rcp_f32_e32 v137, v137
	v_pk_fma_f32 v[132:133], v[132:133], v[242:243], v[182:183] op_sel_hi:[1,0,1]
	v_pk_fma_f32 v[134:135], v[134:135], v[242:243], v[180:181] op_sel_hi:[1,0,1]
	v_exp_f32_e32 v132, v132
	v_exp_f32_e32 v133, v133
	v_exp_f32_e32 v134, v134
	v_exp_f32_e32 v135, v135
	v_pk_fma_f32 v[128:129], v[128:129], v[242:243], v[178:179] op_sel_hi:[1,0,1]
	v_pk_fma_f32 v[130:131], v[130:131], v[242:243], v[176:177] op_sel_hi:[1,0,1]
	v_pk_add_f32 v[132:133], v[132:133], 1.0 op_sel_hi:[1,0]
	v_pk_add_f32 v[134:135], v[134:135], 1.0 op_sel_hi:[1,0]
	v_exp_f32_e32 v128, v128
	v_exp_f32_e32 v129, v129
	v_exp_f32_e32 v130, v130
	v_exp_f32_e32 v131, v131
	v_rcp_f32_e32 v132, v132
	v_rcp_f32_e32 v133, v133
	v_rcp_f32_e32 v134, v134
	v_rcp_f32_e32 v135, v135
	v_pk_add_f32 v[128:129], v[128:129], 1.0 op_sel_hi:[1,0]
	v_pk_add_f32 v[130:131], v[130:131], 1.0 op_sel_hi:[1,0]
	v_rcp_f32_e32 v128, v128
	v_rcp_f32_e32 v129, v129
	v_rcp_f32_e32 v130, v130
	v_rcp_f32_e32 v131, v131
	v_pk_fma_f32 v[126:127], v[126:127], v[236:237], v[190:191] op_sel_hi:[1,0,1]
	v_pk_fma_f32 v[124:125], v[124:125], v[236:237], v[192:193] op_sel_hi:[1,0,1]
	v_exp_f32_e32 v126, v126
	v_exp_f32_e32 v127, v127
	v_exp_f32_e32 v124, v124
	v_exp_f32_e32 v125, v125
	v_pk_fma_f32 v[122:123], v[122:123], v[236:237], v[184:185] op_sel_hi:[1,0,1]
	v_pk_add_f32 v[126:127], v[126:127], 1.0 op_sel_hi:[1,0]
	v_exp_f32_e32 v122, v122
	v_exp_f32_e32 v123, v123
	v_pk_fma_f32 v[120:121], v[120:121], v[236:237], v[186:187] op_sel_hi:[1,0,1]
	v_pk_add_f32 v[124:125], v[124:125], 1.0 op_sel_hi:[1,0]
	v_rcp_f32_e32 v126, v126
	v_rcp_f32_e32 v127, v127
	v_exp_f32_e32 v120, v120
	v_exp_f32_e32 v121, v121
	v_rcp_f32_e32 v124, v124
	v_rcp_f32_e32 v125, v125
	v_pk_add_f32 v[122:123], v[122:123], 1.0 op_sel_hi:[1,0]
	v_pk_add_f32 v[120:121], v[120:121], 1.0 op_sel_hi:[1,0]
	v_rcp_f32_e32 v122, v122
	v_rcp_f32_e32 v123, v123
	v_rcp_f32_e32 v120, v120
	s_waitcnt vmcnt(5)
	v_mov_b32_e32 v214, v149
	v_mov_b32_e32 v215, v150
	v_mov_b32_e32 v149, v151
	v_pk_add_f32 v[148:149], v[214:215], v[148:149]
	v_rcp_f32_e32 v121, v121
	v_add_f32_e32 v148, v148, v149
	v_fmamk_f32 v148, v148, 0x3a800000, v213
	v_rsq_f32_e32 v148, v148
	v_add_f32_e32 v149, v154, v155
	v_pk_fma_f32 v[116:117], v[116:117], v[236:237], v[182:183] op_sel_hi:[1,0,1]
	v_pk_fma_f32 v[118:119], v[118:119], v[236:237], v[180:181] op_sel_hi:[1,0,1]
	v_mul_f32_e32 v214, 0xbfb8aa3b, v148
	v_add_f32_e32 v148, v152, v153
	v_add_f32_e32 v148, v148, v149
	v_mov_b32_e32 v149, v148
	s_nop 1
	v_permlane16_swap_b32_e32 v148, v149
	v_add_f32_e32 v148, v148, v149
	v_mov_b32_e32 v149, v148
	s_nop 1
	v_permlane32_swap_b32_e32 v148, v149
	v_add_f32_e32 v148, v148, v149
	v_fmamk_f32 v148, v148, 0x3a800000, v213
	v_rsq_f32_e32 v212, v148
	v_mov_b32_e32 v148, v157
	v_mov_b32_e32 v149, v158
	v_mov_b32_e32 v157, v159
	v_pk_add_f32 v[148:149], v[148:149], v[156:157]
	v_exp_f32_e32 v116, v116
	v_add_f32_e32 v148, v148, v149
	v_fmamk_f32 v148, v148, 0x3a800000, v213
	v_rsq_f32_e32 v148, v148
	s_waitcnt vmcnt(4)
	v_add_f32_e32 v149, v218, v219
	v_exp_f32_e32 v117, v117
	v_exp_f32_e32 v118, v118
	v_mul_f32_e32 v208, 0xbfb8aa3b, v148
	v_add_f32_e32 v148, v216, v217
	v_add_f32_e32 v148, v148, v149
	v_mov_b32_e32 v149, v148
	s_nop 1
	v_permlane16_swap_b32_e32 v148, v149
	v_add_f32_e32 v148, v148, v149
	v_mov_b32_e32 v149, v148
	s_nop 1
	v_permlane32_swap_b32_e32 v148, v149
	v_add_f32_e32 v148, v148, v149
	v_fmamk_f32 v148, v148, 0x3a800000, v213
	v_rsq_f32_e32 v206, v148
	s_waitcnt vmcnt(3)
	v_mov_b32_e32 v148, v245
	v_mov_b32_e32 v149, v246
	v_mov_b32_e32 v245, v247
	v_pk_add_f32 v[148:149], v[148:149], v[244:245]
	v_lshlrev_b64 v[244:245], 12, v[146:147]
	v_add_f32_e32 v148, v148, v149
	v_fmamk_f32 v148, v148, 0x3a800000, v213
	v_rsq_f32_e32 v148, v148
	s_waitcnt vmcnt(2)
	v_add_f32_e32 v149, v250, v251
	v_exp_f32_e32 v119, v119
	v_pk_fma_f32 v[112:113], v[112:113], v[236:237], v[178:179] op_sel_hi:[1,0,1]
	v_mul_f32_e32 v202, 0xbfb8aa3b, v148
	v_add_f32_e32 v148, v248, v249
	v_add_f32_e32 v148, v148, v149
	v_mov_b32_e32 v149, v148
	s_nop 1
	v_permlane16_swap_b32_e32 v148, v149
	v_add_f32_e32 v148, v148, v149
	v_mov_b32_e32 v149, v148
	s_nop 1
	v_permlane32_swap_b32_e32 v148, v149
	v_add_f32_e32 v148, v148, v149
	v_fmamk_f32 v148, v148, 0x3a800000, v213
	v_rsq_f32_e32 v200, v148
	s_waitcnt vmcnt(0)
	v_mov_b32_e32 v148, v173
	v_mov_b32_e32 v149, v174
	v_mov_b32_e32 v173, v175
	v_pk_add_f32 v[148:149], v[148:149], v[172:173]
	v_pk_fma_f32 v[114:115], v[114:115], v[236:237], v[176:177] op_sel_hi:[1,0,1]
	v_add_f32_e32 v148, v148, v149
	v_fmamk_f32 v148, v148, 0x3a800000, v213
	v_rsq_f32_e32 v148, v148
	v_add_f32_e32 v149, v196, v197
	v_pk_add_f32 v[116:117], v[116:117], 1.0 op_sel_hi:[1,0]
	v_pk_add_f32 v[118:119], v[118:119], 1.0 op_sel_hi:[1,0]
	v_mul_f32_e32 v172, 0xbfb8aa3b, v148
	v_add_f32_e32 v148, v194, v195
	v_add_f32_e32 v148, v148, v149
	v_mov_b32_e32 v149, v148
	s_nop 1
	v_permlane16_swap_b32_e32 v148, v149
	v_add_f32_e32 v148, v148, v149
	v_mov_b32_e32 v149, v148
	s_nop 1
	v_permlane32_swap_b32_e32 v148, v149
	v_add_f32_e32 v148, v148, v149
	v_fmamk_f32 v148, v148, 0x3a800000, v213
	v_rsq_f32_e32 v194, v148
	v_lshlrev_b64 v[148:149], 10, v[146:147]
	v_lshl_add_u64 v[144:145], v[148:149], 0, v[144:145]
	v_lshlrev_b64 v[144:145], 1, v[144:145]
	v_lshl_add_u64 v[216:217], s[68:69], 0, v[144:145]
	v_lshl_add_u64 v[218:219], s[8:9], 0, v[144:145]
	global_load_dwordx4 v[152:155], v[216:217], off
	global_load_dwordx4 v[156:159], v[218:219], off
	global_load_dwordx4 v[148:151], v[216:217], off offset:256
	global_load_dwordx4 v[144:147], v[218:219], off offset:256
	v_exp_f32_e32 v112, v112
	v_exp_f32_e32 v113, v113
	v_exp_f32_e32 v114, v114
	v_exp_f32_e32 v115, v115
	v_rcp_f32_e32 v116, v116
	v_rcp_f32_e32 v117, v117
	v_rcp_f32_e32 v118, v118
	v_rcp_f32_e32 v119, v119
	v_pk_add_f32 v[112:113], v[112:113], 1.0 op_sel_hi:[1,0]
	v_pk_add_f32 v[114:115], v[114:115], 1.0 op_sel_hi:[1,0]
	v_rcp_f32_e32 v112, v112
	v_rcp_f32_e32 v113, v113
	v_rcp_f32_e32 v114, v114
	v_rcp_f32_e32 v115, v115
	v_pk_fma_f32 v[110:111], v[110:111], v[230:231], v[190:191] op_sel_hi:[1,0,1]
	v_pk_fma_f32 v[108:109], v[108:109], v[230:231], v[192:193] op_sel_hi:[1,0,1]
	v_exp_f32_e32 v110, v110
	v_exp_f32_e32 v111, v111
	v_exp_f32_e32 v108, v108
	v_exp_f32_e32 v109, v109
	v_pk_fma_f32 v[106:107], v[106:107], v[230:231], v[184:185] op_sel_hi:[1,0,1]
	v_pk_add_f32 v[110:111], v[110:111], 1.0 op_sel_hi:[1,0]
	v_exp_f32_e32 v106, v106
	v_exp_f32_e32 v107, v107
	v_pk_fma_f32 v[104:105], v[104:105], v[230:231], v[186:187] op_sel_hi:[1,0,1]
	v_pk_add_f32 v[108:109], v[108:109], 1.0 op_sel_hi:[1,0]
	v_rcp_f32_e32 v110, v110
	v_rcp_f32_e32 v111, v111
	v_exp_f32_e32 v104, v104
	v_exp_f32_e32 v105, v105
	v_rcp_f32_e32 v108, v108
	v_rcp_f32_e32 v109, v109
	v_pk_add_f32 v[106:107], v[106:107], 1.0 op_sel_hi:[1,0]
	v_pk_add_f32 v[104:105], v[104:105], 1.0 op_sel_hi:[1,0]
	v_rcp_f32_e32 v106, v106
	v_rcp_f32_e32 v107, v107
	v_rcp_f32_e32 v104, v104
	v_rcp_f32_e32 v105, v105
	v_pk_fma_f32 v[100:101], v[100:101], v[230:231], v[182:183] op_sel_hi:[1,0,1]
	v_pk_fma_f32 v[102:103], v[102:103], v[230:231], v[180:181] op_sel_hi:[1,0,1]
	v_exp_f32_e32 v100, v100
	v_exp_f32_e32 v101, v101
	v_exp_f32_e32 v102, v102
	v_exp_f32_e32 v103, v103
	v_pk_fma_f32 v[96:97], v[96:97], v[230:231], v[178:179] op_sel_hi:[1,0,1]
	v_pk_fma_f32 v[98:99], v[98:99], v[230:231], v[176:177] op_sel_hi:[1,0,1]
	v_pk_add_f32 v[100:101], v[100:101], 1.0 op_sel_hi:[1,0]
	v_pk_add_f32 v[102:103], v[102:103], 1.0 op_sel_hi:[1,0]
	v_exp_f32_e32 v96, v96
	v_exp_f32_e32 v97, v97
	v_exp_f32_e32 v98, v98
	v_exp_f32_e32 v99, v99
	v_rcp_f32_e32 v100, v100
	v_rcp_f32_e32 v101, v101
	v_rcp_f32_e32 v102, v102
	v_rcp_f32_e32 v103, v103
	v_pk_add_f32 v[96:97], v[96:97], 1.0 op_sel_hi:[1,0]
	v_pk_add_f32 v[98:99], v[98:99], 1.0 op_sel_hi:[1,0]
	v_rcp_f32_e32 v96, v96
	v_rcp_f32_e32 v97, v97
	v_rcp_f32_e32 v98, v98
	v_rcp_f32_e32 v99, v99
	v_pk_fma_f32 v[94:95], v[94:95], v[224:225], v[190:191] op_sel_hi:[1,0,1]
	v_pk_fma_f32 v[92:93], v[92:93], v[224:225], v[192:193] op_sel_hi:[1,0,1]
	v_exp_f32_e32 v94, v94
	v_exp_f32_e32 v95, v95
	v_exp_f32_e32 v92, v92
	v_exp_f32_e32 v93, v93
	v_pk_fma_f32 v[90:91], v[90:91], v[224:225], v[184:185] op_sel_hi:[1,0,1]
	v_pk_add_f32 v[94:95], v[94:95], 1.0 op_sel_hi:[1,0]
	v_exp_f32_e32 v90, v90
	v_exp_f32_e32 v91, v91
	v_pk_fma_f32 v[88:89], v[88:89], v[224:225], v[186:187] op_sel_hi:[1,0,1]
	v_pk_add_f32 v[92:93], v[92:93], 1.0 op_sel_hi:[1,0]
	v_rcp_f32_e32 v94, v94
	v_rcp_f32_e32 v95, v95
	s_waitcnt vmcnt(3)
	v_lshlrev_b32_e32 v246, 16, v152
	s_waitcnt vmcnt(2)
	v_lshlrev_b32_e32 v174, 16, v156
	v_and_b32_e32 v175, 0xffff0000, v156
	v_lshlrev_b32_e32 v156, 16, v157
	v_and_b32_e32 v157, 0xffff0000, v157
	v_pk_mul_f32 v[156:157], v[240:241], v[156:157] op_sel_hi:[0,1]
	v_and_b32_e32 v247, 0xffff0000, v152
	v_lshlrev_b32_e32 v152, 16, v153
	v_and_b32_e32 v153, 0xffff0000, v153
	v_pk_mul_f32 v[174:175], v[240:241], v[174:175] op_sel_hi:[0,1]
	v_pk_mul_f32 v[156:157], v[58:59], v[156:157]
	v_pk_mul_f32 v[174:175], v[56:57], v[174:175]
	v_pk_fma_f32 v[142:143], v[142:143], v[156:157], v[152:153]
	v_lshl_add_u64 v[152:153], s[36:37], 0, v[244:245]
	v_lshlrev_b32_e32 v156, 16, v159
	v_and_b32_e32 v157, 0xffff0000, v159
	v_pk_fma_f32 v[140:141], v[140:141], v[174:175], v[246:247]
	v_lshl_add_u64 v[152:153], v[152:153], 0, v[188:189]
	v_pk_mul_f32 v[156:157], v[240:241], v[156:157] op_sel_hi:[0,1]
	global_store_dwordx4 v[152:153], v[140:143], off nt
	v_pk_mul_f32 v[156:157], v[50:51], v[156:157]
	s_waitcnt vmcnt(1)
	v_lshlrev_b32_e32 v174, 16, v144
	v_lshlrev_b32_e32 v140, 16, v154
	v_and_b32_e32 v141, 0xffff0000, v154
	v_lshlrev_b32_e32 v142, 16, v158
	v_and_b32_e32 v143, 0xffff0000, v158
	v_lshlrev_b32_e32 v154, 16, v155
	v_and_b32_e32 v155, 0xffff0000, v155
	v_pk_mul_f32 v[142:143], v[240:241], v[142:143] op_sel_hi:[0,1]
	v_pk_fma_f32 v[138:139], v[138:139], v[156:157], v[154:155]
	v_add_co_u32_e32 v154, vcc, s53, v216
	v_pk_mul_f32 v[142:143], v[48:49], v[142:143]
	s_nop 0
	v_addc_co_u32_e32 v155, vcc, 0, v217, vcc
	v_pk_fma_f32 v[136:137], v[136:137], v[142:143], v[140:141]
	v_add_co_u32_e32 v156, vcc, s53, v218
	global_store_dwordx4 v[152:153], v[136:139], off offset:16 nt
	s_nop 0
	v_addc_co_u32_e32 v157, vcc, 0, v219, vcc
	global_load_dwordx4 v[136:139], v[154:155], off
	global_load_dwordx4 v[140:143], v[156:157], off
	v_and_b32_e32 v175, 0xffff0000, v144
	v_lshlrev_b32_e32 v144, 16, v145
	v_and_b32_e32 v145, 0xffff0000, v145
	v_pk_mul_f32 v[144:145], v[240:241], v[144:145] op_sel_hi:[0,1]
	v_pk_mul_f32 v[174:175], v[240:241], v[174:175] op_sel_hi:[0,1]
	v_lshlrev_b32_e32 v158, 16, v148
	v_and_b32_e32 v159, 0xffff0000, v148
	v_lshlrev_b32_e32 v148, 16, v149
	v_and_b32_e32 v149, 0xffff0000, v149
	v_pk_mul_f32 v[174:175], v[44:45], v[174:175]
	v_pk_mul_f32 v[144:145], v[46:47], v[144:145]
	v_pk_fma_f32 v[132:133], v[132:133], v[174:175], v[158:159]
	v_pk_fma_f32 v[134:135], v[134:135], v[144:145], v[148:149]
	global_store_dwordx4 v[152:153], v[132:135], off offset:512 nt
	v_lshlrev_b32_e32 v144, 16, v151
	v_and_b32_e32 v145, 0xffff0000, v151
	v_lshlrev_b32_e32 v134, 16, v146
	v_and_b32_e32 v135, 0xffff0000, v146
	v_lshlrev_b32_e32 v146, 16, v147
	v_and_b32_e32 v147, 0xffff0000, v147
	v_pk_mul_f32 v[146:147], v[240:241], v[146:147] op_sel_hi:[0,1]
	v_pk_mul_f32 v[134:135], v[240:241], v[134:135] op_sel_hi:[0,1]
	v_lshlrev_b32_e32 v132, 16, v150
	v_and_b32_e32 v133, 0xffff0000, v150
	v_pk_mul_f32 v[134:135], v[36:37], v[134:135]
	v_pk_mul_f32 v[146:147], v[38:39], v[146:147]
	v_pk_fma_f32 v[128:129], v[128:129], v[134:135], v[132:133]
	v_pk_fma_f32 v[130:131], v[130:131], v[146:147], v[144:145]
	global_store_dwordx4 v[152:153], v[128:131], off offset:528 nt
	global_load_dwordx4 v[132:135], v[154:155], off offset:256
	s_nop 0
	global_load_dwordx4 v[128:131], v[156:157], off offset:256
	v_lshlrev_b64 v[144:145], 12, v[238:239]
	v_exp_f32_e32 v88, v88
	v_exp_f32_e32 v89, v89
	v_rcp_f32_e32 v92, v92
	v_rcp_f32_e32 v93, v93
	v_pk_add_f32 v[90:91], v[90:91], 1.0 op_sel_hi:[1,0]
	v_pk_add_f32 v[88:89], v[88:89], 1.0 op_sel_hi:[1,0]
	v_rcp_f32_e32 v90, v90
	v_rcp_f32_e32 v91, v91
	v_rcp_f32_e32 v88, v88
	v_rcp_f32_e32 v89, v89
	v_pk_fma_f32 v[84:85], v[84:85], v[224:225], v[182:183] op_sel_hi:[1,0,1]
	v_pk_fma_f32 v[86:87], v[86:87], v[224:225], v[180:181] op_sel_hi:[1,0,1]
	v_exp_f32_e32 v84, v84
	v_exp_f32_e32 v85, v85
	v_exp_f32_e32 v86, v86
	v_exp_f32_e32 v87, v87
	v_pk_fma_f32 v[80:81], v[80:81], v[224:225], v[178:179] op_sel_hi:[1,0,1]
	v_pk_fma_f32 v[82:83], v[82:83], v[224:225], v[176:177] op_sel_hi:[1,0,1]
	v_pk_add_f32 v[84:85], v[84:85], 1.0 op_sel_hi:[1,0]
	v_pk_add_f32 v[86:87], v[86:87], 1.0 op_sel_hi:[1,0]
	v_exp_f32_e32 v80, v80
	v_exp_f32_e32 v81, v81
	v_exp_f32_e32 v82, v82
	v_exp_f32_e32 v83, v83
	v_rcp_f32_e32 v84, v84
	v_rcp_f32_e32 v85, v85
	v_rcp_f32_e32 v86, v86
	v_rcp_f32_e32 v87, v87
	v_pk_add_f32 v[80:81], v[80:81], 1.0 op_sel_hi:[1,0]
	v_pk_add_f32 v[82:83], v[82:83], 1.0 op_sel_hi:[1,0]
	v_rcp_f32_e32 v80, v80
	v_rcp_f32_e32 v81, v81
	v_rcp_f32_e32 v82, v82
	v_rcp_f32_e32 v83, v83
	v_pk_fma_f32 v[78:79], v[78:79], v[214:215], v[190:191] op_sel_hi:[1,0,1]
	v_pk_fma_f32 v[76:77], v[76:77], v[214:215], v[192:193] op_sel_hi:[1,0,1]
	v_exp_f32_e32 v78, v78
	v_exp_f32_e32 v79, v79
	v_exp_f32_e32 v76, v76
	v_exp_f32_e32 v77, v77
	v_pk_fma_f32 v[74:75], v[74:75], v[214:215], v[184:185] op_sel_hi:[1,0,1]
	v_pk_add_f32 v[78:79], v[78:79], 1.0 op_sel_hi:[1,0]
	v_exp_f32_e32 v74, v74
	v_exp_f32_e32 v75, v75
	v_pk_fma_f32 v[72:73], v[72:73], v[214:215], v[186:187] op_sel_hi:[1,0,1]
	s_waitcnt vmcnt(5)
	v_lshlrev_b32_e32 v146, 16, v136
	s_waitcnt vmcnt(4)
	v_lshlrev_b32_e32 v148, 16, v140
	v_and_b32_e32 v149, 0xffff0000, v140
	v_lshlrev_b32_e32 v140, 16, v141
	v_and_b32_e32 v141, 0xffff0000, v141
	v_pk_mul_f32 v[140:141], v[234:235], v[140:141] op_sel_hi:[0,1]
	v_and_b32_e32 v147, 0xffff0000, v136
	v_lshlrev_b32_e32 v136, 16, v137
	v_and_b32_e32 v137, 0xffff0000, v137
	v_pk_mul_f32 v[148:149], v[234:235], v[148:149] op_sel_hi:[0,1]
	v_pk_mul_f32 v[140:141], v[58:59], v[140:141]
	v_pk_mul_f32 v[148:149], v[56:57], v[148:149]
	v_pk_fma_f32 v[126:127], v[126:127], v[140:141], v[136:137]
	v_lshl_add_u64 v[136:137], s[36:37], 0, v[144:145]
	v_lshlrev_b32_e32 v140, 16, v143
	v_and_b32_e32 v141, 0xffff0000, v143
	v_pk_fma_f32 v[124:125], v[124:125], v[148:149], v[146:147]
	v_lshl_add_u64 v[136:137], v[136:137], 0, v[188:189]
	v_pk_mul_f32 v[140:141], v[234:235], v[140:141] op_sel_hi:[0,1]
	global_store_dwordx4 v[136:137], v[124:127], off nt
	v_pk_mul_f32 v[140:141], v[50:51], v[140:141]
	v_pk_add_f32 v[76:77], v[76:77], 1.0 op_sel_hi:[1,0]
	v_lshlrev_b32_e32 v124, 16, v138
	v_and_b32_e32 v125, 0xffff0000, v138
	v_lshlrev_b32_e32 v126, 16, v142
	v_and_b32_e32 v127, 0xffff0000, v142
	v_lshlrev_b32_e32 v138, 16, v139
	v_and_b32_e32 v139, 0xffff0000, v139
	v_pk_mul_f32 v[126:127], v[234:235], v[126:127] op_sel_hi:[0,1]
	v_pk_fma_f32 v[122:123], v[122:123], v[140:141], v[138:139]
	v_add_co_u32_e32 v138, vcc, s47, v216
	v_pk_mul_f32 v[126:127], v[48:49], v[126:127]
	s_nop 0
	v_addc_co_u32_e32 v139, vcc, 0, v217, vcc
	v_pk_fma_f32 v[120:121], v[120:121], v[126:127], v[124:125]
	v_add_co_u32_e32 v140, vcc, s47, v218
	global_store_dwordx4 v[136:137], v[120:123], off offset:16 nt
	s_nop 0
	v_addc_co_u32_e32 v141, vcc, 0, v219, vcc
	global_load_dwordx4 v[120:123], v[138:139], off
	global_load_dwordx4 v[124:127], v[140:141], off
	s_waitcnt vmcnt(4)
	v_lshlrev_b32_e32 v144, 16, v128
	v_and_b32_e32 v145, 0xffff0000, v128
	v_lshlrev_b32_e32 v128, 16, v129
	v_and_b32_e32 v129, 0xffff0000, v129
	v_pk_mul_f32 v[128:129], v[234:235], v[128:129] op_sel_hi:[0,1]
	v_pk_mul_f32 v[144:145], v[234:235], v[144:145] op_sel_hi:[0,1]
	v_lshlrev_b32_e32 v142, 16, v132
	v_and_b32_e32 v143, 0xffff0000, v132
	v_lshlrev_b32_e32 v132, 16, v133
	v_and_b32_e32 v133, 0xffff0000, v133
	v_pk_mul_f32 v[144:145], v[44:45], v[144:145]
	v_pk_mul_f32 v[128:129], v[46:47], v[128:129]
	v_pk_fma_f32 v[116:117], v[116:117], v[144:145], v[142:143]
	v_pk_fma_f32 v[118:119], v[118:119], v[128:129], v[132:133]
	global_store_dwordx4 v[136:137], v[116:119], off offset:512 nt
	v_lshlrev_b32_e32 v128, 16, v135
	v_and_b32_e32 v129, 0xffff0000, v135
	v_lshlrev_b32_e32 v118, 16, v130
	v_and_b32_e32 v119, 0xffff0000, v130
	v_lshlrev_b32_e32 v130, 16, v131
	v_and_b32_e32 v131, 0xffff0000, v131
	v_pk_mul_f32 v[130:131], v[234:235], v[130:131] op_sel_hi:[0,1]
	v_pk_mul_f32 v[118:119], v[234:235], v[118:119] op_sel_hi:[0,1]
	v_lshlrev_b32_e32 v116, 16, v134
	v_and_b32_e32 v117, 0xffff0000, v134
	v_pk_mul_f32 v[118:119], v[36:37], v[118:119]
	v_pk_mul_f32 v[130:131], v[38:39], v[130:131]
	v_pk_fma_f32 v[112:113], v[112:113], v[118:119], v[116:117]
	v_pk_fma_f32 v[114:115], v[114:115], v[130:131], v[128:129]
	global_store_dwordx4 v[136:137], v[112:115], off offset:528 nt
	global_load_dwordx4 v[116:119], v[138:139], off offset:256
	s_nop 0
	global_load_dwordx4 v[112:115], v[140:141], off offset:256
	v_lshlrev_b64 v[128:129], 12, v[232:233]
	v_rcp_f32_e32 v78, v78
	v_rcp_f32_e32 v79, v79
	v_exp_f32_e32 v72, v72
	v_exp_f32_e32 v73, v73
	v_rcp_f32_e32 v76, v76
	v_rcp_f32_e32 v77, v77
	v_pk_add_f32 v[74:75], v[74:75], 1.0 op_sel_hi:[1,0]
	v_pk_add_f32 v[72:73], v[72:73], 1.0 op_sel_hi:[1,0]
	v_rcp_f32_e32 v74, v74
	v_rcp_f32_e32 v75, v75
	v_pk_fma_f32 v[68:69], v[68:69], v[214:215], v[182:183] op_sel_hi:[1,0,1]
	v_pk_fma_f32 v[70:71], v[70:71], v[214:215], v[180:181] op_sel_hi:[1,0,1]
	v_rcp_f32_e32 v72, v72
	v_rcp_f32_e32 v73, v73
	v_exp_f32_e32 v68, v68
	v_exp_f32_e32 v69, v69
	v_exp_f32_e32 v70, v70
	v_exp_f32_e32 v71, v71
	v_pk_fma_f32 v[64:65], v[64:65], v[214:215], v[178:179] op_sel_hi:[1,0,1]
	v_pk_fma_f32 v[66:67], v[66:67], v[214:215], v[176:177] op_sel_hi:[1,0,1]
	v_pk_add_f32 v[68:69], v[68:69], 1.0 op_sel_hi:[1,0]
	v_pk_add_f32 v[70:71], v[70:71], 1.0 op_sel_hi:[1,0]
	v_exp_f32_e32 v64, v64
	v_exp_f32_e32 v65, v65
	v_exp_f32_e32 v66, v66
	v_exp_f32_e32 v67, v67
	v_rcp_f32_e32 v68, v68
	v_rcp_f32_e32 v69, v69
	v_rcp_f32_e32 v70, v70
	v_rcp_f32_e32 v71, v71
	v_pk_add_f32 v[64:65], v[64:65], 1.0 op_sel_hi:[1,0]
	v_pk_add_f32 v[66:67], v[66:67], 1.0 op_sel_hi:[1,0]
	v_rcp_f32_e32 v64, v64
	v_rcp_f32_e32 v65, v65
	v_rcp_f32_e32 v66, v66
	v_rcp_f32_e32 v67, v67
	v_pk_fma_f32 v[62:63], v[62:63], v[208:209], v[190:191] op_sel_hi:[1,0,1]
	v_pk_fma_f32 v[60:61], v[60:61], v[208:209], v[192:193] op_sel_hi:[1,0,1]
	v_exp_f32_e32 v62, v62
	v_exp_f32_e32 v63, v63
	v_exp_f32_e32 v60, v60
	v_exp_f32_e32 v61, v61
	v_pk_fma_f32 v[54:55], v[54:55], v[208:209], v[184:185] op_sel_hi:[1,0,1]
	v_pk_add_f32 v[62:63], v[62:63], 1.0 op_sel_hi:[1,0]
	s_waitcnt vmcnt(5)
	v_lshlrev_b32_e32 v130, 16, v120
	s_waitcnt vmcnt(4)
	v_lshlrev_b32_e32 v132, 16, v124
	v_and_b32_e32 v133, 0xffff0000, v124
	v_lshlrev_b32_e32 v124, 16, v125
	v_and_b32_e32 v125, 0xffff0000, v125
	v_pk_mul_f32 v[124:125], v[228:229], v[124:125] op_sel_hi:[0,1]
	v_and_b32_e32 v131, 0xffff0000, v120
	v_lshlrev_b32_e32 v120, 16, v121
	v_and_b32_e32 v121, 0xffff0000, v121
	v_pk_mul_f32 v[132:133], v[228:229], v[132:133] op_sel_hi:[0,1]
	v_pk_mul_f32 v[124:125], v[58:59], v[124:125]
	v_pk_mul_f32 v[132:133], v[56:57], v[132:133]
	v_pk_fma_f32 v[110:111], v[110:111], v[124:125], v[120:121]
	v_lshl_add_u64 v[120:121], s[36:37], 0, v[128:129]
	v_lshlrev_b32_e32 v124, 16, v127
	v_and_b32_e32 v125, 0xffff0000, v127
	v_pk_fma_f32 v[108:109], v[108:109], v[132:133], v[130:131]
	v_lshl_add_u64 v[120:121], v[120:121], 0, v[188:189]
	v_pk_mul_f32 v[124:125], v[228:229], v[124:125] op_sel_hi:[0,1]
	global_store_dwordx4 v[120:121], v[108:111], off nt
	v_pk_mul_f32 v[124:125], v[50:51], v[124:125]
	v_exp_f32_e32 v54, v54
	v_lshlrev_b32_e32 v108, 16, v122
	v_and_b32_e32 v109, 0xffff0000, v122
	v_lshlrev_b32_e32 v110, 16, v126
	v_and_b32_e32 v111, 0xffff0000, v126
	v_lshlrev_b32_e32 v122, 16, v123
	v_and_b32_e32 v123, 0xffff0000, v123
	v_pk_mul_f32 v[110:111], v[228:229], v[110:111] op_sel_hi:[0,1]
	v_pk_fma_f32 v[106:107], v[106:107], v[124:125], v[122:123]
	v_add_co_u32_e32 v122, vcc, s52, v216
	v_pk_mul_f32 v[110:111], v[48:49], v[110:111]
	s_nop 0
	v_addc_co_u32_e32 v123, vcc, 0, v217, vcc
	v_pk_fma_f32 v[104:105], v[104:105], v[110:111], v[108:109]
	v_add_co_u32_e32 v124, vcc, s52, v218
	global_store_dwordx4 v[120:121], v[104:107], off offset:16 nt
	s_nop 0
	v_addc_co_u32_e32 v125, vcc, 0, v219, vcc
	global_load_dwordx4 v[104:107], v[122:123], off
	global_load_dwordx4 v[108:111], v[124:125], off
	s_waitcnt vmcnt(4)
	v_lshlrev_b32_e32 v128, 16, v112
	v_and_b32_e32 v129, 0xffff0000, v112
	v_lshlrev_b32_e32 v112, 16, v113
	v_and_b32_e32 v113, 0xffff0000, v113
	v_pk_mul_f32 v[112:113], v[228:229], v[112:113] op_sel_hi:[0,1]
	v_pk_mul_f32 v[128:129], v[228:229], v[128:129] op_sel_hi:[0,1]
	v_lshlrev_b32_e32 v126, 16, v116
	v_and_b32_e32 v127, 0xffff0000, v116
	v_lshlrev_b32_e32 v116, 16, v117
	v_and_b32_e32 v117, 0xffff0000, v117
	v_pk_mul_f32 v[128:129], v[44:45], v[128:129]
	v_pk_mul_f32 v[112:113], v[46:47], v[112:113]
	v_pk_fma_f32 v[100:101], v[100:101], v[128:129], v[126:127]
	v_pk_fma_f32 v[102:103], v[102:103], v[112:113], v[116:117]
	global_store_dwordx4 v[120:121], v[100:103], off offset:512 nt
	v_lshlrev_b32_e32 v112, 16, v119
	v_and_b32_e32 v113, 0xffff0000, v119
	v_lshlrev_b32_e32 v102, 16, v114
	v_and_b32_e32 v103, 0xffff0000, v114
	v_lshlrev_b32_e32 v114, 16, v115
	v_and_b32_e32 v115, 0xffff0000, v115
	v_pk_mul_f32 v[114:115], v[228:229], v[114:115] op_sel_hi:[0,1]
	v_pk_mul_f32 v[102:103], v[228:229], v[102:103] op_sel_hi:[0,1]
	v_lshlrev_b32_e32 v100, 16, v118
	v_and_b32_e32 v101, 0xffff0000, v118
	v_pk_mul_f32 v[102:103], v[36:37], v[102:103]
	v_pk_mul_f32 v[114:115], v[38:39], v[114:115]
	v_pk_fma_f32 v[96:97], v[96:97], v[102:103], v[100:101]
	v_pk_fma_f32 v[98:99], v[98:99], v[114:115], v[112:113]
	global_store_dwordx4 v[120:121], v[96:99], off offset:528 nt
	global_load_dwordx4 v[100:103], v[122:123], off offset:256
	s_nop 0
	global_load_dwordx4 v[96:99], v[124:125], off offset:256
	v_lshlrev_b64 v[112:113], 12, v[226:227]
	v_exp_f32_e32 v55, v55
	v_pk_fma_f32 v[52:53], v[52:53], v[208:209], v[186:187] op_sel_hi:[1,0,1]
	v_pk_add_f32 v[60:61], v[60:61], 1.0 op_sel_hi:[1,0]
	v_rcp_f32_e32 v62, v62
	v_rcp_f32_e32 v63, v63
	v_exp_f32_e32 v52, v52
	v_exp_f32_e32 v53, v53
	v_rcp_f32_e32 v60, v60
	v_rcp_f32_e32 v61, v61
	v_pk_add_f32 v[54:55], v[54:55], 1.0 op_sel_hi:[1,0]
	v_pk_fma_f32 v[40:41], v[40:41], v[208:209], v[182:183] op_sel_hi:[1,0,1]
	v_rcp_f32_e32 v54, v54
	v_rcp_f32_e32 v55, v55
	v_pk_fma_f32 v[42:43], v[42:43], v[208:209], v[180:181] op_sel_hi:[1,0,1]
	v_pk_add_f32 v[52:53], v[52:53], 1.0 op_sel_hi:[1,0]
	v_exp_f32_e32 v40, v40
	v_exp_f32_e32 v41, v41
	v_exp_f32_e32 v42, v42
	v_exp_f32_e32 v43, v43
	v_rcp_f32_e32 v52, v52
	v_rcp_f32_e32 v53, v53
	v_pk_fma_f32 v[32:33], v[32:33], v[208:209], v[178:179] op_sel_hi:[1,0,1]
	v_pk_fma_f32 v[34:35], v[34:35], v[208:209], v[176:177] op_sel_hi:[1,0,1]
	v_pk_add_f32 v[40:41], v[40:41], 1.0 op_sel_hi:[1,0]
	v_pk_add_f32 v[42:43], v[42:43], 1.0 op_sel_hi:[1,0]
	v_exp_f32_e32 v32, v32
	v_exp_f32_e32 v33, v33
	v_exp_f32_e32 v34, v34
	v_exp_f32_e32 v35, v35
	v_rcp_f32_e32 v40, v40
	v_rcp_f32_e32 v41, v41
	v_rcp_f32_e32 v42, v42
	v_rcp_f32_e32 v43, v43
	v_pk_add_f32 v[32:33], v[32:33], 1.0 op_sel_hi:[1,0]
	v_pk_add_f32 v[34:35], v[34:35], 1.0 op_sel_hi:[1,0]
	v_rcp_f32_e32 v32, v32
	v_rcp_f32_e32 v33, v33
	v_rcp_f32_e32 v34, v34
	v_rcp_f32_e32 v35, v35
	v_pk_fma_f32 v[30:31], v[30:31], v[202:203], v[190:191] op_sel_hi:[1,0,1]
	v_pk_fma_f32 v[28:29], v[28:29], v[202:203], v[192:193] op_sel_hi:[1,0,1]
	v_exp_f32_e32 v30, v30
	v_exp_f32_e32 v31, v31
	v_exp_f32_e32 v28, v28
	s_waitcnt vmcnt(5)
	v_lshlrev_b32_e32 v114, 16, v104
	s_waitcnt vmcnt(4)
	v_lshlrev_b32_e32 v116, 16, v108
	v_and_b32_e32 v117, 0xffff0000, v108
	v_lshlrev_b32_e32 v108, 16, v109
	v_and_b32_e32 v109, 0xffff0000, v109
	v_pk_mul_f32 v[108:109], v[222:223], v[108:109] op_sel_hi:[0,1]
	v_and_b32_e32 v115, 0xffff0000, v104
	v_lshlrev_b32_e32 v104, 16, v105
	v_and_b32_e32 v105, 0xffff0000, v105
	v_pk_mul_f32 v[116:117], v[222:223], v[116:117] op_sel_hi:[0,1]
	v_pk_mul_f32 v[108:109], v[58:59], v[108:109]
	v_pk_mul_f32 v[116:117], v[56:57], v[116:117]
	v_pk_fma_f32 v[94:95], v[94:95], v[108:109], v[104:105]
	v_lshl_add_u64 v[104:105], s[36:37], 0, v[112:113]
	v_lshlrev_b32_e32 v108, 16, v111
	v_and_b32_e32 v109, 0xffff0000, v111
	v_pk_fma_f32 v[92:93], v[92:93], v[116:117], v[114:115]
	v_lshl_add_u64 v[104:105], v[104:105], 0, v[188:189]
	v_pk_mul_f32 v[108:109], v[222:223], v[108:109] op_sel_hi:[0,1]
	global_store_dwordx4 v[104:105], v[92:95], off nt
	v_pk_mul_f32 v[108:109], v[50:51], v[108:109]
	v_exp_f32_e32 v29, v29
	v_lshlrev_b32_e32 v92, 16, v106
	v_and_b32_e32 v93, 0xffff0000, v106
	v_lshlrev_b32_e32 v94, 16, v110
	v_and_b32_e32 v95, 0xffff0000, v110
	v_lshlrev_b32_e32 v106, 16, v107
	v_and_b32_e32 v107, 0xffff0000, v107
	v_pk_mul_f32 v[94:95], v[222:223], v[94:95] op_sel_hi:[0,1]
	v_pk_fma_f32 v[90:91], v[90:91], v[108:109], v[106:107]
	v_add_co_u32_e32 v106, vcc, s57, v216
	v_pk_mul_f32 v[94:95], v[48:49], v[94:95]
	s_nop 0
	v_addc_co_u32_e32 v107, vcc, 0, v217, vcc
	v_pk_fma_f32 v[88:89], v[88:89], v[94:95], v[92:93]
	v_add_co_u32_e32 v108, vcc, s57, v218
	global_store_dwordx4 v[104:105], v[88:91], off offset:16 nt
	s_nop 0
	v_addc_co_u32_e32 v109, vcc, 0, v219, vcc
	global_load_dwordx4 v[88:91], v[106:107], off
	global_load_dwordx4 v[92:95], v[108:109], off
	s_waitcnt vmcnt(4)
	v_lshlrev_b32_e32 v112, 16, v96
	v_and_b32_e32 v113, 0xffff0000, v96
	v_lshlrev_b32_e32 v96, 16, v97
	v_and_b32_e32 v97, 0xffff0000, v97
	v_pk_mul_f32 v[96:97], v[222:223], v[96:97] op_sel_hi:[0,1]
	v_pk_mul_f32 v[112:113], v[222:223], v[112:113] op_sel_hi:[0,1]
	v_lshlrev_b32_e32 v110, 16, v100
	v_and_b32_e32 v111, 0xffff0000, v100
	v_lshlrev_b32_e32 v100, 16, v101
	v_and_b32_e32 v101, 0xffff0000, v101
	v_pk_mul_f32 v[112:113], v[44:45], v[112:113]
	v_pk_mul_f32 v[96:97], v[46:47], v[96:97]
	v_pk_fma_f32 v[84:85], v[84:85], v[112:113], v[110:111]
	v_pk_fma_f32 v[86:87], v[86:87], v[96:97], v[100:101]
	global_store_dwordx4 v[104:105], v[84:87], off offset:512 nt
	v_lshlrev_b32_e32 v96, 16, v103
	v_and_b32_e32 v97, 0xffff0000, v103
	v_lshlrev_b32_e32 v86, 16, v98
	v_and_b32_e32 v87, 0xffff0000, v98
	v_lshlrev_b32_e32 v98, 16, v99
	v_and_b32_e32 v99, 0xffff0000, v99
	v_pk_mul_f32 v[98:99], v[222:223], v[98:99] op_sel_hi:[0,1]
	v_pk_mul_f32 v[86:87], v[222:223], v[86:87] op_sel_hi:[0,1]
	v_lshlrev_b32_e32 v84, 16, v102
	v_and_b32_e32 v85, 0xffff0000, v102
	v_pk_mul_f32 v[86:87], v[36:37], v[86:87]
	v_pk_mul_f32 v[98:99], v[38:39], v[98:99]
	v_pk_fma_f32 v[80:81], v[80:81], v[86:87], v[84:85]
	v_pk_fma_f32 v[82:83], v[82:83], v[98:99], v[96:97]
	global_store_dwordx4 v[104:105], v[80:83], off offset:528 nt
	global_load_dwordx4 v[84:87], v[106:107], off offset:256
	s_nop 0
	global_load_dwordx4 v[80:83], v[108:109], off offset:256
	v_lshlrev_b64 v[96:97], 12, v[220:221]
	v_pk_fma_f32 v[26:27], v[26:27], v[202:203], v[184:185] op_sel_hi:[1,0,1]
	v_pk_add_f32 v[30:31], v[30:31], 1.0 op_sel_hi:[1,0]
	v_exp_f32_e32 v26, v26
	v_exp_f32_e32 v27, v27
	v_pk_fma_f32 v[24:25], v[24:25], v[202:203], v[186:187] op_sel_hi:[1,0,1]
	v_pk_add_f32 v[28:29], v[28:29], 1.0 op_sel_hi:[1,0]
	v_rcp_f32_e32 v30, v30
	v_rcp_f32_e32 v31, v31
	v_exp_f32_e32 v24, v24
	v_exp_f32_e32 v25, v25
	v_rcp_f32_e32 v28, v28
	v_rcp_f32_e32 v29, v29
	v_pk_add_f32 v[26:27], v[26:27], 1.0 op_sel_hi:[1,0]
	v_pk_fma_f32 v[20:21], v[20:21], v[202:203], v[182:183] op_sel_hi:[1,0,1]
	v_pk_fma_f32 v[22:23], v[22:23], v[202:203], v[180:181] op_sel_hi:[1,0,1]
	v_rcp_f32_e32 v26, v26
	v_rcp_f32_e32 v27, v27
	v_exp_f32_e32 v20, v20
	v_exp_f32_e32 v21, v21
	v_exp_f32_e32 v22, v22
	v_exp_f32_e32 v23, v23
	v_pk_add_f32 v[24:25], v[24:25], 1.0 op_sel_hi:[1,0]
	v_pk_fma_f32 v[16:17], v[16:17], v[202:203], v[178:179] op_sel_hi:[1,0,1]
	v_rcp_f32_e32 v24, v24
	v_rcp_f32_e32 v25, v25
	v_pk_fma_f32 v[18:19], v[18:19], v[202:203], v[176:177] op_sel_hi:[1,0,1]
	v_pk_add_f32 v[20:21], v[20:21], 1.0 op_sel_hi:[1,0]
	v_pk_add_f32 v[22:23], v[22:23], 1.0 op_sel_hi:[1,0]
	v_exp_f32_e32 v16, v16
	v_exp_f32_e32 v17, v17
	v_exp_f32_e32 v18, v18
	v_exp_f32_e32 v19, v19
	v_rcp_f32_e32 v20, v20
	v_rcp_f32_e32 v21, v21
	v_rcp_f32_e32 v22, v22
	v_rcp_f32_e32 v23, v23
	v_pk_add_f32 v[16:17], v[16:17], 1.0 op_sel_hi:[1,0]
	v_pk_add_f32 v[18:19], v[18:19], 1.0 op_sel_hi:[1,0]
	v_rcp_f32_e32 v16, v16
	v_rcp_f32_e32 v17, v17
	v_rcp_f32_e32 v18, v18
	v_rcp_f32_e32 v19, v19
	v_pk_fma_f32 v[14:15], v[14:15], v[172:173], v[190:191] op_sel_hi:[1,0,1]
	v_pk_fma_f32 v[12:13], v[12:13], v[172:173], v[192:193] op_sel_hi:[1,0,1]
	s_waitcnt vmcnt(5)
	v_lshlrev_b32_e32 v98, 16, v88
	s_waitcnt vmcnt(4)
	v_lshlrev_b32_e32 v100, 16, v92
	v_and_b32_e32 v101, 0xffff0000, v92
	v_lshlrev_b32_e32 v92, 16, v93
	v_and_b32_e32 v93, 0xffff0000, v93
	v_pk_mul_f32 v[92:93], v[212:213], v[92:93] op_sel_hi:[0,1]
	v_and_b32_e32 v99, 0xffff0000, v88
	v_lshlrev_b32_e32 v88, 16, v89
	v_and_b32_e32 v89, 0xffff0000, v89
	v_pk_mul_f32 v[100:101], v[212:213], v[100:101] op_sel_hi:[0,1]
	v_pk_mul_f32 v[92:93], v[58:59], v[92:93]
	v_pk_mul_f32 v[100:101], v[56:57], v[100:101]
	v_pk_fma_f32 v[78:79], v[78:79], v[92:93], v[88:89]
	v_lshl_add_u64 v[88:89], s[36:37], 0, v[96:97]
	v_lshlrev_b32_e32 v92, 16, v95
	v_and_b32_e32 v93, 0xffff0000, v95
	v_pk_fma_f32 v[76:77], v[76:77], v[100:101], v[98:99]
	v_lshl_add_u64 v[88:89], v[88:89], 0, v[188:189]
	v_pk_mul_f32 v[92:93], v[212:213], v[92:93] op_sel_hi:[0,1]
	global_store_dwordx4 v[88:89], v[76:79], off nt
	v_pk_mul_f32 v[92:93], v[50:51], v[92:93]
	v_exp_f32_e32 v14, v14
	v_lshlrev_b32_e32 v76, 16, v90
	v_and_b32_e32 v77, 0xffff0000, v90
	v_lshlrev_b32_e32 v78, 16, v94
	v_and_b32_e32 v79, 0xffff0000, v94
	v_lshlrev_b32_e32 v90, 16, v91
	v_and_b32_e32 v91, 0xffff0000, v91
	v_pk_mul_f32 v[78:79], v[212:213], v[78:79] op_sel_hi:[0,1]
	v_pk_fma_f32 v[74:75], v[74:75], v[92:93], v[90:91]
	v_add_co_u32_e32 v90, vcc, s58, v216
	v_pk_mul_f32 v[78:79], v[48:49], v[78:79]
	s_nop 0
	v_addc_co_u32_e32 v91, vcc, 0, v217, vcc
	v_pk_fma_f32 v[72:73], v[72:73], v[78:79], v[76:77]
	v_add_co_u32_e32 v92, vcc, s58, v218
	global_store_dwordx4 v[88:89], v[72:75], off offset:16 nt
	s_nop 0
	v_addc_co_u32_e32 v93, vcc, 0, v219, vcc
	global_load_dwordx4 v[72:75], v[90:91], off
	global_load_dwordx4 v[76:79], v[92:93], off
	s_waitcnt vmcnt(4)
	v_lshlrev_b32_e32 v96, 16, v80
	v_and_b32_e32 v97, 0xffff0000, v80
	v_lshlrev_b32_e32 v80, 16, v81
	v_and_b32_e32 v81, 0xffff0000, v81
	v_pk_mul_f32 v[80:81], v[212:213], v[80:81] op_sel_hi:[0,1]
	v_pk_mul_f32 v[96:97], v[212:213], v[96:97] op_sel_hi:[0,1]
	v_lshlrev_b32_e32 v94, 16, v84
	v_and_b32_e32 v95, 0xffff0000, v84
	v_lshlrev_b32_e32 v84, 16, v85
	v_and_b32_e32 v85, 0xffff0000, v85
	v_pk_mul_f32 v[96:97], v[44:45], v[96:97]
	v_pk_mul_f32 v[80:81], v[46:47], v[80:81]
	v_pk_fma_f32 v[68:69], v[68:69], v[96:97], v[94:95]
	v_pk_fma_f32 v[70:71], v[70:71], v[80:81], v[84:85]
	global_store_dwordx4 v[88:89], v[68:71], off offset:512 nt
	v_lshlrev_b32_e32 v80, 16, v87
	v_and_b32_e32 v81, 0xffff0000, v87
	v_lshlrev_b32_e32 v70, 16, v82
	v_and_b32_e32 v71, 0xffff0000, v82
	v_lshlrev_b32_e32 v82, 16, v83
	v_and_b32_e32 v83, 0xffff0000, v83
	v_pk_mul_f32 v[82:83], v[212:213], v[82:83] op_sel_hi:[0,1]
	v_pk_mul_f32 v[70:71], v[212:213], v[70:71] op_sel_hi:[0,1]
	v_lshlrev_b32_e32 v68, 16, v86
	v_and_b32_e32 v69, 0xffff0000, v86
	v_pk_mul_f32 v[70:71], v[36:37], v[70:71]
	v_pk_mul_f32 v[82:83], v[38:39], v[82:83]
	v_pk_fma_f32 v[64:65], v[64:65], v[70:71], v[68:69]
	v_pk_fma_f32 v[66:67], v[66:67], v[82:83], v[80:81]
	global_store_dwordx4 v[88:89], v[64:67], off offset:528 nt
	global_load_dwordx4 v[64:67], v[90:91], off offset:256
	s_nop 0
	global_load_dwordx4 v[68:71], v[92:93], off offset:256
	v_lshlrev_b64 v[80:81], 12, v[210:211]
	v_exp_f32_e32 v15, v15
	v_exp_f32_e32 v12, v12
	v_exp_f32_e32 v13, v13
	v_pk_fma_f32 v[8:9], v[8:9], v[172:173], v[186:187] op_sel_hi:[1,0,1]
	v_pk_fma_f32 v[10:11], v[10:11], v[172:173], v[184:185] op_sel_hi:[1,0,1]
	v_exp_f32_e32 v8, v8
	v_exp_f32_e32 v9, v9
	v_exp_f32_e32 v10, v10
	v_exp_f32_e32 v11, v11
	v_pk_add_f32 v[14:15], v[14:15], 1.0 op_sel_hi:[1,0]
	v_pk_add_f32 v[12:13], v[12:13], 1.0 op_sel_hi:[1,0]
	v_rcp_f32_e32 v14, v14
	v_rcp_f32_e32 v15, v15
	v_pk_fma_f32 v[4:5], v[4:5], v[172:173], v[182:183] op_sel_hi:[1,0,1]
	v_pk_fma_f32 v[6:7], v[6:7], v[172:173], v[180:181] op_sel_hi:[1,0,1]
	v_rcp_f32_e32 v12, v12
	v_rcp_f32_e32 v13, v13
	v_pk_add_f32 v[8:9], v[8:9], 1.0 op_sel_hi:[1,0]
	v_pk_add_f32 v[10:11], v[10:11], 1.0 op_sel_hi:[1,0]
	v_exp_f32_e32 v4, v4
	v_exp_f32_e32 v5, v5
	v_exp_f32_e32 v6, v6
	v_exp_f32_e32 v7, v7
	v_rcp_f32_e32 v8, v8
	v_rcp_f32_e32 v9, v9
	v_rcp_f32_e32 v10, v10
	v_rcp_f32_e32 v11, v11
	v_pk_fma_f32 v[0:1], v[0:1], v[172:173], v[178:179] op_sel_hi:[1,0,1]
	v_pk_fma_f32 v[2:3], v[2:3], v[172:173], v[176:177] op_sel_hi:[1,0,1]
	v_pk_add_f32 v[4:5], v[4:5], 1.0 op_sel_hi:[1,0]
	v_pk_add_f32 v[6:7], v[6:7], 1.0 op_sel_hi:[1,0]
	v_exp_f32_e32 v0, v0
	v_exp_f32_e32 v1, v1
	v_exp_f32_e32 v2, v2
	v_exp_f32_e32 v3, v3
	v_rcp_f32_e32 v4, v4
	v_rcp_f32_e32 v5, v5
	v_rcp_f32_e32 v6, v6
	v_rcp_f32_e32 v7, v7
	v_pk_add_f32 v[0:1], v[0:1], 1.0 op_sel_hi:[1,0]
	v_pk_add_f32 v[2:3], v[2:3], 1.0 op_sel_hi:[1,0]
	v_rcp_f32_e32 v0, v0
	v_rcp_f32_e32 v1, v1
	v_rcp_f32_e32 v2, v2
	s_waitcnt vmcnt(5)
	v_lshlrev_b32_e32 v82, 16, v72
	s_waitcnt vmcnt(4)
	v_lshlrev_b32_e32 v84, 16, v76
	v_and_b32_e32 v85, 0xffff0000, v76
	v_lshlrev_b32_e32 v76, 16, v77
	v_and_b32_e32 v77, 0xffff0000, v77
	v_pk_mul_f32 v[76:77], v[206:207], v[76:77] op_sel_hi:[0,1]
	v_and_b32_e32 v83, 0xffff0000, v72
	v_lshlrev_b32_e32 v72, 16, v73
	v_and_b32_e32 v73, 0xffff0000, v73
	v_pk_mul_f32 v[84:85], v[206:207], v[84:85] op_sel_hi:[0,1]
	v_pk_mul_f32 v[76:77], v[58:59], v[76:77]
	v_pk_mul_f32 v[84:85], v[56:57], v[84:85]
	v_pk_fma_f32 v[62:63], v[62:63], v[76:77], v[72:73]
	v_lshl_add_u64 v[72:73], s[36:37], 0, v[80:81]
	v_lshlrev_b32_e32 v76, 16, v79
	v_and_b32_e32 v77, 0xffff0000, v79
	v_pk_fma_f32 v[60:61], v[60:61], v[84:85], v[82:83]
	v_lshl_add_u64 v[72:73], v[72:73], 0, v[188:189]
	v_pk_mul_f32 v[76:77], v[206:207], v[76:77] op_sel_hi:[0,1]
	global_store_dwordx4 v[72:73], v[60:63], off nt
	v_pk_mul_f32 v[76:77], v[50:51], v[76:77]
	v_rcp_f32_e32 v3, v3
	v_lshlrev_b32_e32 v60, 16, v74
	v_and_b32_e32 v61, 0xffff0000, v74
	v_lshlrev_b32_e32 v62, 16, v78
	v_and_b32_e32 v63, 0xffff0000, v78
	v_lshlrev_b32_e32 v74, 16, v75
	v_and_b32_e32 v75, 0xffff0000, v75
	v_pk_mul_f32 v[62:63], v[206:207], v[62:63] op_sel_hi:[0,1]
	v_pk_fma_f32 v[54:55], v[54:55], v[76:77], v[74:75]
	v_add_co_u32_e32 v74, vcc, s59, v216
	v_pk_mul_f32 v[62:63], v[48:49], v[62:63]
	s_nop 0
	v_addc_co_u32_e32 v75, vcc, 0, v217, vcc
	v_pk_fma_f32 v[52:53], v[52:53], v[62:63], v[60:61]
	v_add_co_u32_e32 v76, vcc, s59, v218
	global_store_dwordx4 v[72:73], v[52:55], off offset:16 nt
	s_nop 0
	v_addc_co_u32_e32 v77, vcc, 0, v219, vcc
	s_waitcnt vmcnt(2)
	v_lshlrev_b32_e32 v80, 16, v68
	v_and_b32_e32 v81, 0xffff0000, v68
	v_lshlrev_b32_e32 v68, 16, v69
	v_and_b32_e32 v69, 0xffff0000, v69
	global_load_dwordx4 v[52:55], v[74:75], off
	global_load_dwordx4 v[60:63], v[76:77], off
	v_pk_mul_f32 v[68:69], v[206:207], v[68:69] op_sel_hi:[0,1]
	v_pk_mul_f32 v[80:81], v[206:207], v[80:81] op_sel_hi:[0,1]
	v_lshlrev_b32_e32 v78, 16, v64
	v_and_b32_e32 v79, 0xffff0000, v64
	v_lshlrev_b32_e32 v64, 16, v65
	v_and_b32_e32 v65, 0xffff0000, v65
	v_pk_mul_f32 v[80:81], v[44:45], v[80:81]
	v_pk_mul_f32 v[68:69], v[46:47], v[68:69]
	v_pk_fma_f32 v[40:41], v[40:41], v[80:81], v[78:79]
	v_pk_fma_f32 v[42:43], v[42:43], v[68:69], v[64:65]
	global_store_dwordx4 v[72:73], v[40:43], off offset:512 nt
	v_lshlrev_b32_e32 v64, 16, v67
	v_and_b32_e32 v65, 0xffff0000, v67
	v_lshlrev_b32_e32 v40, 16, v66
	v_and_b32_e32 v41, 0xffff0000, v66
	v_lshlrev_b32_e32 v42, 16, v70
	v_and_b32_e32 v43, 0xffff0000, v70
	v_lshlrev_b32_e32 v66, 16, v71
	v_and_b32_e32 v67, 0xffff0000, v71
	v_pk_mul_f32 v[66:67], v[206:207], v[66:67] op_sel_hi:[0,1]
	v_pk_mul_f32 v[42:43], v[206:207], v[42:43] op_sel_hi:[0,1]
	v_pk_mul_f32 v[42:43], v[36:37], v[42:43]
	v_pk_mul_f32 v[66:67], v[38:39], v[66:67]
	v_pk_fma_f32 v[32:33], v[32:33], v[42:43], v[40:41]
	v_pk_fma_f32 v[34:35], v[34:35], v[66:67], v[64:65]
	global_store_dwordx4 v[72:73], v[32:35], off offset:528 nt
	global_load_dwordx4 v[32:35], v[74:75], off offset:256
	s_nop 0
	global_load_dwordx4 v[40:43], v[76:77], off offset:256
	v_lshlrev_b64 v[64:65], 12, v[204:205]
	s_waitcnt vmcnt(5)
	v_lshlrev_b32_e32 v66, 16, v52
	s_waitcnt vmcnt(4)
	v_lshlrev_b32_e32 v68, 16, v60
	v_and_b32_e32 v69, 0xffff0000, v60
	v_lshlrev_b32_e32 v60, 16, v61
	v_and_b32_e32 v61, 0xffff0000, v61
	v_pk_mul_f32 v[60:61], v[200:201], v[60:61] op_sel_hi:[0,1]
	v_and_b32_e32 v67, 0xffff0000, v52
	v_lshlrev_b32_e32 v52, 16, v53
	v_and_b32_e32 v53, 0xffff0000, v53
	v_pk_mul_f32 v[68:69], v[200:201], v[68:69] op_sel_hi:[0,1]
	v_pk_mul_f32 v[60:61], v[58:59], v[60:61]
	v_pk_mul_f32 v[68:69], v[56:57], v[68:69]
	v_pk_fma_f32 v[30:31], v[30:31], v[60:61], v[52:53]
	v_lshl_add_u64 v[52:53], s[36:37], 0, v[64:65]
	v_lshlrev_b32_e32 v60, 16, v63
	v_and_b32_e32 v61, 0xffff0000, v63
	v_pk_fma_f32 v[28:29], v[28:29], v[68:69], v[66:67]
	v_lshl_add_u64 v[52:53], v[52:53], 0, v[188:189]
	v_pk_mul_f32 v[60:61], v[200:201], v[60:61] op_sel_hi:[0,1]
	global_store_dwordx4 v[52:53], v[28:31], off nt
	v_pk_mul_f32 v[60:61], v[50:51], v[60:61]
	s_waitcnt vmcnt(2)
	v_and_b32_e32 v63, 0xffff0000, v32
	v_lshlrev_b32_e32 v28, 16, v54
	v_and_b32_e32 v29, 0xffff0000, v54
	v_lshlrev_b32_e32 v30, 16, v62
	v_and_b32_e32 v31, 0xffff0000, v62
	v_lshlrev_b32_e32 v54, 16, v55
	v_and_b32_e32 v55, 0xffff0000, v55
	v_pk_mul_f32 v[30:31], v[200:201], v[30:31] op_sel_hi:[0,1]
	v_pk_fma_f32 v[26:27], v[26:27], v[60:61], v[54:55]
	v_add_co_u32_e32 v54, vcc, s60, v216
	v_pk_mul_f32 v[30:31], v[48:49], v[30:31]
	s_nop 0
	v_addc_co_u32_e32 v55, vcc, 0, v217, vcc
	v_pk_fma_f32 v[24:25], v[24:25], v[30:31], v[28:29]
	v_add_co_u32_e32 v60, vcc, s60, v218
	s_waitcnt vmcnt(1)
	v_lshlrev_b32_e32 v64, 16, v40
	v_and_b32_e32 v65, 0xffff0000, v40
	v_lshlrev_b32_e32 v40, 16, v41
	v_and_b32_e32 v41, 0xffff0000, v41
	global_store_dwordx4 v[52:53], v[24:27], off offset:16 nt
	v_addc_co_u32_e32 v61, vcc, 0, v219, vcc
	v_pk_mul_f32 v[40:41], v[200:201], v[40:41] op_sel_hi:[0,1]
	v_pk_mul_f32 v[64:65], v[200:201], v[64:65] op_sel_hi:[0,1]
	global_load_dwordx4 v[24:27], v[54:55], off
	global_load_dwordx4 v[28:31], v[60:61], off
	v_lshlrev_b32_e32 v62, 16, v32
	v_lshlrev_b32_e32 v32, 16, v33
	v_and_b32_e32 v33, 0xffff0000, v33
	v_pk_mul_f32 v[64:65], v[44:45], v[64:65]
	v_pk_mul_f32 v[40:41], v[46:47], v[40:41]
	v_pk_fma_f32 v[20:21], v[20:21], v[64:65], v[62:63]
	v_pk_fma_f32 v[22:23], v[22:23], v[40:41], v[32:33]
	global_store_dwordx4 v[52:53], v[20:23], off offset:512 nt
	v_lshlrev_b32_e32 v32, 16, v35
	v_and_b32_e32 v33, 0xffff0000, v35
	v_lshlrev_b32_e32 v20, 16, v34
	v_and_b32_e32 v21, 0xffff0000, v34
	v_lshlrev_b32_e32 v22, 16, v42
	v_and_b32_e32 v23, 0xffff0000, v42
	v_lshlrev_b32_e32 v34, 16, v43
	v_and_b32_e32 v35, 0xffff0000, v43
	v_pk_mul_f32 v[34:35], v[200:201], v[34:35] op_sel_hi:[0,1]
	v_pk_mul_f32 v[22:23], v[200:201], v[22:23] op_sel_hi:[0,1]
	v_pk_mul_f32 v[22:23], v[36:37], v[22:23]
	v_pk_mul_f32 v[34:35], v[38:39], v[34:35]
	v_pk_fma_f32 v[16:17], v[16:17], v[22:23], v[20:21]
	v_pk_fma_f32 v[18:19], v[18:19], v[34:35], v[32:33]
	global_store_dwordx4 v[52:53], v[16:19], off offset:528 nt
	global_load_dwordx4 v[16:19], v[54:55], off offset:256
	s_nop 0
	global_load_dwordx4 v[20:23], v[60:61], off offset:256
	v_lshlrev_b64 v[40:41], 12, v[198:199]
	s_and_b64 vcc, exec, s[0:1]
	s_waitcnt vmcnt(5)
	v_lshlrev_b32_e32 v32, 16, v24
	s_waitcnt vmcnt(4)
	v_lshlrev_b32_e32 v34, 16, v28
	v_and_b32_e32 v35, 0xffff0000, v28
	v_lshlrev_b32_e32 v28, 16, v29
	v_and_b32_e32 v29, 0xffff0000, v29
	v_pk_mul_f32 v[28:29], v[194:195], v[28:29] op_sel_hi:[0,1]
	v_and_b32_e32 v33, 0xffff0000, v24
	v_lshlrev_b32_e32 v24, 16, v25
	v_and_b32_e32 v25, 0xffff0000, v25
	v_pk_mul_f32 v[34:35], v[194:195], v[34:35] op_sel_hi:[0,1]
	v_pk_mul_f32 v[28:29], v[58:59], v[28:29]
	v_pk_mul_f32 v[42:43], v[56:57], v[34:35]
	v_pk_fma_f32 v[34:35], v[14:15], v[28:29], v[24:25]
	v_lshlrev_b32_e32 v24, 16, v30
	v_and_b32_e32 v25, 0xffff0000, v30
	v_lshlrev_b32_e32 v28, 16, v31
	v_and_b32_e32 v29, 0xffff0000, v31
	v_pk_mul_f32 v[28:29], v[194:195], v[28:29] op_sel_hi:[0,1]
	v_pk_mul_f32 v[24:25], v[194:195], v[24:25] op_sel_hi:[0,1]
	v_pk_fma_f32 v[32:33], v[12:13], v[42:43], v[32:33]
	v_lshl_add_u64 v[12:13], s[36:37], 0, v[40:41]
	v_lshlrev_b32_e32 v14, 16, v26
	v_and_b32_e32 v15, 0xffff0000, v26
	v_lshlrev_b32_e32 v26, 16, v27
	v_and_b32_e32 v27, 0xffff0000, v27
	v_pk_mul_f32 v[24:25], v[48:49], v[24:25]
	v_pk_mul_f32 v[28:29], v[50:51], v[28:29]
	v_lshl_add_u64 v[12:13], v[12:13], 0, v[188:189]
	v_pk_fma_f32 v[10:11], v[10:11], v[28:29], v[26:27]
	v_pk_fma_f32 v[8:9], v[8:9], v[24:25], v[14:15]
	global_store_dwordx4 v[12:13], v[8:11], off offset:16 nt
	s_waitcnt vmcnt(2)
	v_lshlrev_b32_e32 v14, 16, v17
	v_and_b32_e32 v15, 0xffff0000, v17
	v_lshlrev_b32_e32 v8, 16, v16
	v_and_b32_e32 v9, 0xffff0000, v16
	s_waitcnt vmcnt(1)
	v_lshlrev_b32_e32 v10, 16, v20
	v_and_b32_e32 v11, 0xffff0000, v20
	v_lshlrev_b32_e32 v16, 16, v21
	v_and_b32_e32 v17, 0xffff0000, v21
	v_pk_mul_f32 v[16:17], v[194:195], v[16:17] op_sel_hi:[0,1]
	v_pk_mul_f32 v[10:11], v[194:195], v[10:11] op_sel_hi:[0,1]
	v_pk_mul_f32 v[10:11], v[44:45], v[10:11]
	v_pk_mul_f32 v[16:17], v[46:47], v[16:17]
	v_pk_fma_f32 v[4:5], v[4:5], v[10:11], v[8:9]
	v_pk_fma_f32 v[6:7], v[6:7], v[16:17], v[14:15]
	global_store_dwordx4 v[12:13], v[4:7], off offset:512 nt
	v_lshlrev_b32_e32 v10, 16, v23
	v_and_b32_e32 v11, 0xffff0000, v23
	v_lshlrev_b32_e32 v6, 16, v22
	v_and_b32_e32 v7, 0xffff0000, v22
	v_pk_mul_f32 v[10:11], v[194:195], v[10:11] op_sel_hi:[0,1]
	v_pk_mul_f32 v[6:7], v[194:195], v[6:7] op_sel_hi:[0,1]
	v_lshlrev_b32_e32 v4, 16, v18
	v_and_b32_e32 v5, 0xffff0000, v18
	v_lshlrev_b32_e32 v8, 16, v19
	v_and_b32_e32 v9, 0xffff0000, v19
	v_pk_mul_f32 v[6:7], v[36:37], v[6:7]
	v_pk_mul_f32 v[10:11], v[38:39], v[10:11]
	v_pk_fma_f32 v[0:1], v[0:1], v[6:7], v[4:5]
	v_pk_fma_f32 v[2:3], v[2:3], v[10:11], v[8:9]
	global_store_dwordx4 v[12:13], v[32:35], off nt
	global_store_dwordx4 v[12:13], v[0:3], off offset:528 nt
	s_cbranch_vccz .LBB0_2024
	s_waitcnt vmcnt(0)
	s_cmpk_gt_u32 s19, 0xff
	s_cbranch_scc1 .LBB0_2035
	s_barrier
